# EpiGU half-epilogue hand-rewritten: software-pipelined LDS reads, running output pointer, rstd up front, no denorm-rsq scaling, rcp+mul silu everywhere
# speedup vs baseline: 1.0748x; 1.0042x over previous
.LBB0_186:
	s_or_b64 exec, exec, s[42:43]
	s_movk_i32 s42, 0x410
	v_lshrrev_b32_e32 v130, 2, v142
	v_lshlrev_b32_e32 v131, 1, v142
	v_and_b32_e32 v0, 15, v142
	v_and_b32_e32 v130, 0xfffffcc, v130
	v_and_b32_e32 v131, 0x180, v131
	v_add_u32_e32 v131, 0, v131
	v_lshlrev_b32_e32 v0, 2, v0
	v_mul_lo_u32 v130, v130, s42
	v_add3_u32 v130, v131, v0, v130
	s_waitcnt vmcnt(0)
	s_barrier
	ds_write2_b32 v130, v114, v126 offset1:16
	v_add_u32_e32 v114, 0x400, v130
	ds_write2_b32 v114, v115, v127 offset0:4 offset1:20
	v_add_u32_e32 v115, 0x800, v130
	ds_write2_b32 v115, v116, v128 offset0:8 offset1:24
	v_add_u32_e32 v116, 0xc00, v130
	ds_write2_b32 v116, v117, v129 offset0:12 offset1:28
	v_add_u32_e32 v117, 0x4000, v130
	ds_write2_b32 v117, v82, v94 offset0:64 offset1:80
	v_add_u32_e32 v94, 0x4400, v130
	ds_write2_b32 v94, v83, v95 offset0:68 offset1:84
	v_add_u32_e32 v95, 0x4800, v130
	ds_write2_b32 v95, v84, v96 offset0:72 offset1:88
	v_add_u32_e32 v96, 0x4c00, v130
	v_add_u32_e32 v133, 0xc000, v130
	ds_write2_b32 v96, v85, v97 offset0:76 offset1:92
	v_add_u32_e32 v132, 0x8000, v130
	v_add_u32_e32 v97, 0x8400, v130
	v_add_u32_e32 v126, 0x8800, v130
	v_add_u32_e32 v127, 0x8c00, v130
	ds_write2_b32 v133, v66, v70 offset0:192 offset1:208
	v_add_u32_e32 v128, 0xc400, v130
	v_add_u32_e32 v129, 0xc800, v130
	v_add_u32_e32 v131, 0xcc00, v130
	v_lshlrev_b32_e32 v0, 3, v142
	v_lshlrev_b32_e32 v66, 2, v142
	ds_write2_b32 v132, v74, v78 offset0:128 offset1:144
	ds_write2_b32 v97, v75, v79 offset0:132 offset1:148
	ds_write2_b32 v126, v76, v80 offset0:136 offset1:152
	ds_write2_b32 v127, v77, v81 offset0:140 offset1:156
	ds_write2_b32 v128, v67, v71 offset0:196 offset1:212
	ds_write2_b32 v129, v68, v72 offset0:200 offset1:216
	ds_write2_b32 v131, v69, v73 offset0:204 offset1:220
	ds_write2_b32 v130, v98, v118 offset0:128 offset1:144
	ds_write2_b32 v114, v99, v119 offset0:132 offset1:148
	ds_write2_b32 v115, v100, v120 offset0:136 offset1:152
	ds_write2_b32 v116, v101, v121 offset0:140 offset1:156
	ds_write2_b32 v117, v102, v122 offset0:192 offset1:208
	ds_write2_b32 v94, v103, v123 offset0:196 offset1:212
	ds_write2_b32 v95, v104, v124 offset0:200 offset1:216
	ds_write2_b32 v96, v105, v125 offset0:204 offset1:220
	ds_write2_b32 v97, v90, v110 offset1:16
	ds_write2_b32 v126, v91, v111 offset0:4 offset1:20
	ds_write2_b32 v127, v92, v112 offset0:8 offset1:24
	v_add_u32_e32 v90, 0x9000, v130
	v_and_b32_e32 v0, 0xe0, v0
	v_and_b32_e32 v68, 12, v66
	ds_write2_b32 v90, v93, v113 offset0:12 offset1:28
	ds_write2_b32 v128, v86, v106 offset0:64 offset1:80
	ds_write2_b32 v129, v87, v107 offset0:68 offset1:84
	ds_write2_b32 v131, v88, v108 offset0:72 offset1:88
	v_lshlrev_b32_e32 v66, 2, v0
	v_lshlrev_b32_e32 v67, 2, v68
	v_or_b32_e32 v0, s38, v0
	v_ashrrev_i32_e32 v88, 5, v142
	v_add3_u32 v74, 0, v66, v67
	v_ashrrev_i32_e32 v66, 1, v0
	v_lshlrev_b32_e32 v0, 1, v68
	v_add_u32_e32 v68, s10, v88
	v_ashrrev_i32_e32 v69, 31, v68
	v_add_u32_e32 v91, 0xd000, v130
	v_lshl_add_u64 v[70:71], v[68:69], 4, s[46:47]
	ds_write2_b32 v91, v89, v109 offset0:76 offset1:92
	s_waitcnt lgkmcnt(0)
	s_barrier
	global_load_dwordx4 v[134:137], v[70:71], off
	global_load_dwordx4 v[138:141], v[70:71], off offset:256
	global_load_dwordx4 v[144:147], v[70:71], off offset:512
	global_load_dwordx4 v[148:151], v[70:71], off offset:768
	global_load_dwordx4 v[152:155], v[70:71], off offset:1024
	global_load_dwordx4 v[156:159], v[70:71], off offset:1280
	global_load_dwordx4 v[160:163], v[70:71], off offset:1536
	global_load_dwordx4 v[164:167], v[70:71], off offset:1792
	v_readlane_b32 s16, v253, 58
	v_ashrrev_i32_e32 v67, 31, v66
	v_readlane_b32 s17, v253, 59
	s_mov_b32 s33, 0x800000
	v_mad_u64_u32 v[82:83], s[36:37], v88, s42, v[74:75]
	v_lshl_add_u64 v[66:67], v[66:67], 1, s[16:17]
	v_lshl_add_u64 v[66:67], v[66:67], 0, v[0:1]
	s_movk_i32 s39, 0x1600
	v_readlane_b32 s16, v254, 61
	v_readlane_b32 s17, v254, 62
	s_waitcnt vmcnt(0)
	v_mad_i64_i32 v[68:69], s[36:37], v68, s39, v[66:67]
	ds_read_b128 v[70:73], v82
	ds_read_b128 v[74:77], v82 offset:64
	v_add_u32_e32 v0, 0x10400, v82
	s_lshl_b32 s98, s39, 4
	s_mov_b32 s99, 0
	v_add_f32_e32 v134, v134, v135
	v_add_f32_e32 v134, v134, v136
	v_add_f32_e32 v134, v134, v137
	v_fmamk_f32 v134, v134, 0x3a800000, v200
	v_rsq_f32_e32 v134, v134
	v_add_f32_e32 v138, v138, v139
	v_add_f32_e32 v138, v138, v140
	v_add_f32_e32 v138, v138, v141
	v_fmamk_f32 v138, v138, 0x3a800000, v200
	v_rsq_f32_e32 v138, v138
	v_add_f32_e32 v144, v144, v145
	v_add_f32_e32 v144, v144, v146
	v_add_f32_e32 v144, v144, v147
	v_fmamk_f32 v144, v144, 0x3a800000, v200
	v_rsq_f32_e32 v144, v144
	v_add_f32_e32 v148, v148, v149
	v_add_f32_e32 v148, v148, v150
	v_add_f32_e32 v148, v148, v151
	v_fmamk_f32 v148, v148, 0x3a800000, v200
	v_rsq_f32_e32 v148, v148
	v_add_f32_e32 v152, v152, v153
	v_add_f32_e32 v152, v152, v154
	v_add_f32_e32 v152, v152, v155
	v_fmamk_f32 v152, v152, 0x3a800000, v200
	v_rsq_f32_e32 v152, v152
	v_add_f32_e32 v156, v156, v157
	v_add_f32_e32 v156, v156, v158
	v_add_f32_e32 v156, v156, v159
	v_fmamk_f32 v156, v156, 0x3a800000, v200
	v_rsq_f32_e32 v156, v156
	v_add_f32_e32 v160, v160, v161
	v_add_f32_e32 v160, v160, v162
	v_add_f32_e32 v160, v160, v163
	v_fmamk_f32 v160, v160, 0x3a800000, v200
	v_rsq_f32_e32 v160, v160
	v_add_f32_e32 v164, v164, v165
	v_add_f32_e32 v164, v164, v166
	v_add_f32_e32 v164, v164, v167
	v_fmamk_f32 v164, v164, 0x3a800000, v200
	v_rsq_f32_e32 v164, v164
	ds_read_b128 v[78:81], v82 offset:16640
	ds_read_b128 v[84:87], v82 offset:16704
	s_waitcnt lgkmcnt(2)
	v_pk_mul_f32 v[70:71], v[70:71], v[134:135] op_sel_hi:[1,0]
	v_pk_mul_f32 v[72:73], v[72:73], v[134:135] op_sel_hi:[1,0]
	v_mul_f32_e32 v98, 0xbfb8aa3b, v70
	v_mul_f32_e32 v99, 0xbfb8aa3b, v71
	v_mul_f32_e32 v100, 0xbfb8aa3b, v72
	v_mul_f32_e32 v101, 0xbfb8aa3b, v73
	v_exp_f32_e32 v98, v98
	v_exp_f32_e32 v99, v99
	v_exp_f32_e32 v100, v100
	v_exp_f32_e32 v101, v101
	v_pk_mul_f32 v[74:75], v[74:75], v[134:135] op_sel_hi:[1,0]
	v_pk_mul_f32 v[76:77], v[76:77], v[134:135] op_sel_hi:[1,0]
	v_pk_add_f32 v[98:99], v[98:99], 1.0 op_sel_hi:[1,0]
	v_pk_add_f32 v[100:101], v[100:101], 1.0 op_sel_hi:[1,0]
	v_rcp_f32_e32 v98, v98
	v_rcp_f32_e32 v99, v99
	v_rcp_f32_e32 v100, v100
	v_rcp_f32_e32 v101, v101
	s_nop 0
	v_pk_mul_f32 v[70:71], v[70:71], v[98:99]
	v_pk_mul_f32 v[72:73], v[72:73], v[100:101]
	v_pk_mul_f32 v[70:71], v[74:75], v[70:71]
	v_pk_mul_f32 v[72:73], v[76:77], v[72:73]
	v_cvt_pk_bf16_f32 v98, v70, v71
	v_cvt_pk_bf16_f32 v99, v72, v73
	global_store_dwordx2 v[68:69], v[98:99], off
	v_lshl_add_u64 v[68:69], v[68:69], 0, s[98:99]
	ds_read_b128 v[70:73], v82 offset:33280
	ds_read_b128 v[74:77], v82 offset:33344
	s_waitcnt lgkmcnt(2)
	v_pk_mul_f32 v[78:79], v[78:79], v[138:139] op_sel_hi:[1,0]
	v_pk_mul_f32 v[80:81], v[80:81], v[138:139] op_sel_hi:[1,0]
	v_mul_f32_e32 v98, 0xbfb8aa3b, v78
	v_mul_f32_e32 v99, 0xbfb8aa3b, v79
	v_mul_f32_e32 v100, 0xbfb8aa3b, v80
	v_mul_f32_e32 v101, 0xbfb8aa3b, v81
	v_exp_f32_e32 v98, v98
	v_exp_f32_e32 v99, v99
	v_exp_f32_e32 v100, v100
	v_exp_f32_e32 v101, v101
	v_pk_mul_f32 v[84:85], v[84:85], v[138:139] op_sel_hi:[1,0]
	v_pk_mul_f32 v[86:87], v[86:87], v[138:139] op_sel_hi:[1,0]
	v_pk_add_f32 v[98:99], v[98:99], 1.0 op_sel_hi:[1,0]
	v_pk_add_f32 v[100:101], v[100:101], 1.0 op_sel_hi:[1,0]
	v_rcp_f32_e32 v98, v98
	v_rcp_f32_e32 v99, v99
	v_rcp_f32_e32 v100, v100
	v_rcp_f32_e32 v101, v101
	s_nop 0
	v_pk_mul_f32 v[78:79], v[78:79], v[98:99]
	v_pk_mul_f32 v[80:81], v[80:81], v[100:101]
	v_pk_mul_f32 v[78:79], v[84:85], v[78:79]
	v_pk_mul_f32 v[80:81], v[86:87], v[80:81]
	v_cvt_pk_bf16_f32 v98, v78, v79
	v_cvt_pk_bf16_f32 v99, v80, v81
	global_store_dwordx2 v[68:69], v[98:99], off
	v_lshl_add_u64 v[68:69], v[68:69], 0, s[98:99]
	ds_read_b128 v[78:81], v82 offset:49920
	ds_read_b128 v[84:87], v82 offset:49984
	s_waitcnt lgkmcnt(2)
	v_pk_mul_f32 v[70:71], v[70:71], v[144:145] op_sel_hi:[1,0]
	v_pk_mul_f32 v[72:73], v[72:73], v[144:145] op_sel_hi:[1,0]
	v_mul_f32_e32 v98, 0xbfb8aa3b, v70
	v_mul_f32_e32 v99, 0xbfb8aa3b, v71
	v_mul_f32_e32 v100, 0xbfb8aa3b, v72
	v_mul_f32_e32 v101, 0xbfb8aa3b, v73
	v_exp_f32_e32 v98, v98
	v_exp_f32_e32 v99, v99
	v_exp_f32_e32 v100, v100
	v_exp_f32_e32 v101, v101
	v_pk_mul_f32 v[74:75], v[74:75], v[144:145] op_sel_hi:[1,0]
	v_pk_mul_f32 v[76:77], v[76:77], v[144:145] op_sel_hi:[1,0]
	v_pk_add_f32 v[98:99], v[98:99], 1.0 op_sel_hi:[1,0]
	v_pk_add_f32 v[100:101], v[100:101], 1.0 op_sel_hi:[1,0]
	v_rcp_f32_e32 v98, v98
	v_rcp_f32_e32 v99, v99
	v_rcp_f32_e32 v100, v100
	v_rcp_f32_e32 v101, v101
	s_nop 0
	v_pk_mul_f32 v[70:71], v[70:71], v[98:99]
	v_pk_mul_f32 v[72:73], v[72:73], v[100:101]
	v_pk_mul_f32 v[70:71], v[74:75], v[70:71]
	v_pk_mul_f32 v[72:73], v[76:77], v[72:73]
	v_cvt_pk_bf16_f32 v98, v70, v71
	v_cvt_pk_bf16_f32 v99, v72, v73
	global_store_dwordx2 v[68:69], v[98:99], off
	v_lshl_add_u64 v[68:69], v[68:69], 0, s[98:99]
	ds_read_b128 v[70:73], v0
	ds_read_b128 v[74:77], v0 offset:64
	s_waitcnt lgkmcnt(2)
	v_pk_mul_f32 v[78:79], v[78:79], v[148:149] op_sel_hi:[1,0]
	v_pk_mul_f32 v[80:81], v[80:81], v[148:149] op_sel_hi:[1,0]
	v_mul_f32_e32 v98, 0xbfb8aa3b, v78
	v_mul_f32_e32 v99, 0xbfb8aa3b, v79
	v_mul_f32_e32 v100, 0xbfb8aa3b, v80
	v_mul_f32_e32 v101, 0xbfb8aa3b, v81
	v_exp_f32_e32 v98, v98
	v_exp_f32_e32 v99, v99
	v_exp_f32_e32 v100, v100
	v_exp_f32_e32 v101, v101
	v_pk_mul_f32 v[84:85], v[84:85], v[148:149] op_sel_hi:[1,0]
	v_pk_mul_f32 v[86:87], v[86:87], v[148:149] op_sel_hi:[1,0]
	v_pk_add_f32 v[98:99], v[98:99], 1.0 op_sel_hi:[1,0]
	v_pk_add_f32 v[100:101], v[100:101], 1.0 op_sel_hi:[1,0]
	v_rcp_f32_e32 v98, v98
	v_rcp_f32_e32 v99, v99
	v_rcp_f32_e32 v100, v100
	v_rcp_f32_e32 v101, v101
	s_nop 0
	v_pk_mul_f32 v[78:79], v[78:79], v[98:99]
	v_pk_mul_f32 v[80:81], v[80:81], v[100:101]
	v_pk_mul_f32 v[78:79], v[84:85], v[78:79]
	v_pk_mul_f32 v[80:81], v[86:87], v[80:81]
	v_cvt_pk_bf16_f32 v98, v78, v79
	v_cvt_pk_bf16_f32 v99, v80, v81
	global_store_dwordx2 v[68:69], v[98:99], off
	v_lshl_add_u64 v[68:69], v[68:69], 0, s[98:99]
	ds_read_b128 v[78:81], v0 offset:16640
	ds_read_b128 v[84:87], v0 offset:16704
	s_waitcnt lgkmcnt(2)
	v_pk_mul_f32 v[70:71], v[70:71], v[152:153] op_sel_hi:[1,0]
	v_pk_mul_f32 v[72:73], v[72:73], v[152:153] op_sel_hi:[1,0]
	v_mul_f32_e32 v98, 0xbfb8aa3b, v70
	v_mul_f32_e32 v99, 0xbfb8aa3b, v71
	v_mul_f32_e32 v100, 0xbfb8aa3b, v72
	v_mul_f32_e32 v101, 0xbfb8aa3b, v73
	v_exp_f32_e32 v98, v98
	v_exp_f32_e32 v99, v99
	v_exp_f32_e32 v100, v100
	v_exp_f32_e32 v101, v101
	v_pk_mul_f32 v[74:75], v[74:75], v[152:153] op_sel_hi:[1,0]
	v_pk_mul_f32 v[76:77], v[76:77], v[152:153] op_sel_hi:[1,0]
	v_pk_add_f32 v[98:99], v[98:99], 1.0 op_sel_hi:[1,0]
	v_pk_add_f32 v[100:101], v[100:101], 1.0 op_sel_hi:[1,0]
	v_rcp_f32_e32 v98, v98
	v_rcp_f32_e32 v99, v99
	v_rcp_f32_e32 v100, v100
	v_rcp_f32_e32 v101, v101
	s_nop 0
	v_pk_mul_f32 v[70:71], v[70:71], v[98:99]
	v_pk_mul_f32 v[72:73], v[72:73], v[100:101]
	v_pk_mul_f32 v[70:71], v[74:75], v[70:71]
	v_pk_mul_f32 v[72:73], v[76:77], v[72:73]
	v_cvt_pk_bf16_f32 v98, v70, v71
	v_cvt_pk_bf16_f32 v99, v72, v73
	global_store_dwordx2 v[68:69], v[98:99], off
	v_lshl_add_u64 v[68:69], v[68:69], 0, s[98:99]
	ds_read_b128 v[70:73], v0 offset:33280
	ds_read_b128 v[74:77], v0 offset:33344
	s_waitcnt lgkmcnt(2)
	v_pk_mul_f32 v[78:79], v[78:79], v[156:157] op_sel_hi:[1,0]
	v_pk_mul_f32 v[80:81], v[80:81], v[156:157] op_sel_hi:[1,0]
	v_mul_f32_e32 v98, 0xbfb8aa3b, v78
	v_mul_f32_e32 v99, 0xbfb8aa3b, v79
	v_mul_f32_e32 v100, 0xbfb8aa3b, v80
	v_mul_f32_e32 v101, 0xbfb8aa3b, v81
	v_exp_f32_e32 v98, v98
	v_exp_f32_e32 v99, v99
	v_exp_f32_e32 v100, v100
	v_exp_f32_e32 v101, v101
	v_pk_mul_f32 v[84:85], v[84:85], v[156:157] op_sel_hi:[1,0]
	v_pk_mul_f32 v[86:87], v[86:87], v[156:157] op_sel_hi:[1,0]
	v_pk_add_f32 v[98:99], v[98:99], 1.0 op_sel_hi:[1,0]
	v_pk_add_f32 v[100:101], v[100:101], 1.0 op_sel_hi:[1,0]
	v_rcp_f32_e32 v98, v98
	v_rcp_f32_e32 v99, v99
	v_rcp_f32_e32 v100, v100
	v_rcp_f32_e32 v101, v101
	s_nop 0
	v_pk_mul_f32 v[78:79], v[78:79], v[98:99]
	v_pk_mul_f32 v[80:81], v[80:81], v[100:101]
	v_pk_mul_f32 v[78:79], v[84:85], v[78:79]
	v_pk_mul_f32 v[80:81], v[86:87], v[80:81]
	v_cvt_pk_bf16_f32 v98, v78, v79
	v_cvt_pk_bf16_f32 v99, v80, v81
	global_store_dwordx2 v[68:69], v[98:99], off
	v_lshl_add_u64 v[68:69], v[68:69], 0, s[98:99]
	ds_read_b128 v[78:81], v0 offset:49920
	ds_read_b128 v[84:87], v0 offset:49984
	s_waitcnt lgkmcnt(2)
	v_pk_mul_f32 v[70:71], v[70:71], v[160:161] op_sel_hi:[1,0]
	v_pk_mul_f32 v[72:73], v[72:73], v[160:161] op_sel_hi:[1,0]
	v_mul_f32_e32 v98, 0xbfb8aa3b, v70
	v_mul_f32_e32 v99, 0xbfb8aa3b, v71
	v_mul_f32_e32 v100, 0xbfb8aa3b, v72
	v_mul_f32_e32 v101, 0xbfb8aa3b, v73
	v_exp_f32_e32 v98, v98
	v_exp_f32_e32 v99, v99
	v_exp_f32_e32 v100, v100
	v_exp_f32_e32 v101, v101
	v_pk_mul_f32 v[74:75], v[74:75], v[160:161] op_sel_hi:[1,0]
	v_pk_mul_f32 v[76:77], v[76:77], v[160:161] op_sel_hi:[1,0]
	v_pk_add_f32 v[98:99], v[98:99], 1.0 op_sel_hi:[1,0]
	v_pk_add_f32 v[100:101], v[100:101], 1.0 op_sel_hi:[1,0]
	v_rcp_f32_e32 v98, v98
	v_rcp_f32_e32 v99, v99
	v_rcp_f32_e32 v100, v100
	v_rcp_f32_e32 v101, v101
	s_nop 0
	v_pk_mul_f32 v[70:71], v[70:71], v[98:99]
	v_pk_mul_f32 v[72:73], v[72:73], v[100:101]
	v_pk_mul_f32 v[70:71], v[74:75], v[70:71]
	v_pk_mul_f32 v[72:73], v[76:77], v[72:73]
	v_cvt_pk_bf16_f32 v98, v70, v71
	v_cvt_pk_bf16_f32 v99, v72, v73
	global_store_dwordx2 v[68:69], v[98:99], off
	v_lshl_add_u64 v[68:69], v[68:69], 0, s[98:99]
	s_waitcnt lgkmcnt(0)
	v_pk_mul_f32 v[78:79], v[78:79], v[164:165] op_sel_hi:[1,0]
	v_pk_mul_f32 v[80:81], v[80:81], v[164:165] op_sel_hi:[1,0]
	v_mul_f32_e32 v98, 0xbfb8aa3b, v78
	v_mul_f32_e32 v99, 0xbfb8aa3b, v79
	v_mul_f32_e32 v100, 0xbfb8aa3b, v80
	v_mul_f32_e32 v101, 0xbfb8aa3b, v81
	v_exp_f32_e32 v98, v98
	v_exp_f32_e32 v99, v99
	v_exp_f32_e32 v100, v100
	v_exp_f32_e32 v101, v101
	v_pk_mul_f32 v[84:85], v[84:85], v[164:165] op_sel_hi:[1,0]
	v_pk_mul_f32 v[86:87], v[86:87], v[164:165] op_sel_hi:[1,0]
	v_pk_add_f32 v[98:99], v[98:99], 1.0 op_sel_hi:[1,0]
	v_pk_add_f32 v[100:101], v[100:101], 1.0 op_sel_hi:[1,0]
	v_rcp_f32_e32 v98, v98
	v_rcp_f32_e32 v99, v99
	v_rcp_f32_e32 v100, v100
	v_rcp_f32_e32 v101, v101
	s_nop 0
	v_pk_mul_f32 v[78:79], v[78:79], v[98:99]
	v_pk_mul_f32 v[80:81], v[80:81], v[100:101]
	v_pk_mul_f32 v[78:79], v[84:85], v[78:79]
	v_pk_mul_f32 v[80:81], v[86:87], v[80:81]
	v_cvt_pk_bf16_f32 v98, v78, v79
	v_cvt_pk_bf16_f32 v99, v80, v81
	global_store_dwordx2 v[68:69], v[98:99], off
	v_mov_b32_e32 v142, v201
	s_or_b32 s42, s38, 0x100
	s_ashr_i32 s43, s42, 31
	s_lshl_b64 s[70:71], s[42:43], 11
	s_barrier
	ds_write2_b32 v130, v2, v18 offset1:16
	ds_write2_b32 v114, v3, v19 offset0:4 offset1:20
	ds_write2_b32 v115, v4, v20 offset0:8 offset1:24
	ds_write2_b32 v116, v5, v21 offset0:12 offset1:28
	ds_write2_b32 v117, v6, v22 offset0:64 offset1:80
	ds_write2_b32 v94, v7, v23 offset0:68 offset1:84
	ds_write2_b32 v95, v8, v24 offset0:72 offset1:88
	ds_write2_b32 v96, v9, v25 offset0:76 offset1:92
	ds_write2_b32 v132, v10, v26 offset0:128 offset1:144
	ds_write2_b32 v97, v11, v27 offset0:132 offset1:148
	ds_write2_b32 v126, v12, v28 offset0:136 offset1:152
	ds_write2_b32 v127, v13, v29 offset0:140 offset1:156
	ds_write2_b32 v133, v14, v30 offset0:192 offset1:208
	ds_write2_b32 v128, v15, v31 offset0:196 offset1:212
	ds_write2_b32 v129, v16, v32 offset0:200 offset1:216
	ds_write2_b32 v131, v17, v33 offset0:204 offset1:220
	ds_write2_b32 v130, v34, v50 offset0:128 offset1:144
	ds_write2_b32 v114, v35, v51 offset0:132 offset1:148
	ds_write2_b32 v115, v36, v52 offset0:136 offset1:152
	ds_write2_b32 v116, v37, v53 offset0:140 offset1:156
	ds_write2_b32 v117, v38, v54 offset0:192 offset1:208
	ds_write2_b32 v94, v39, v55 offset0:196 offset1:212
	ds_write2_b32 v95, v40, v56 offset0:200 offset1:216
	ds_write2_b32 v96, v41, v57 offset0:204 offset1:220
	ds_write2_b32 v97, v42, v58 offset1:16
	ds_write2_b32 v126, v43, v59 offset0:4 offset1:20
	ds_write2_b32 v127, v44, v60 offset0:8 offset1:24
	ds_write2_b32 v90, v45, v61 offset0:12 offset1:28
	ds_write2_b32 v128, v46, v62 offset0:64 offset1:80
	ds_write2_b32 v129, v47, v63 offset0:68 offset1:84
	ds_write2_b32 v131, v48, v64 offset0:72 offset1:88
	ds_write2_b32 v91, v49, v65 offset0:76 offset1:92
	v_add_u32_e32 v2, s8, v88
	v_ashrrev_i32_e32 v3, 31, v2
	v_lshl_add_u64 v[4:5], v[2:3], 4, s[46:47]
	s_waitcnt lgkmcnt(0)
	s_barrier
	global_load_dwordx4 v[134:137], v[4:5], off
	global_load_dwordx4 v[138:141], v[4:5], off offset:256
	global_load_dwordx4 v[144:147], v[4:5], off offset:512
	global_load_dwordx4 v[148:151], v[4:5], off offset:768
	global_load_dwordx4 v[152:155], v[4:5], off offset:1024
	global_load_dwordx4 v[156:159], v[4:5], off offset:1280
	global_load_dwordx4 v[160:163], v[4:5], off offset:1536
	global_load_dwordx4 v[164:167], v[4:5], off offset:1792
	s_waitcnt vmcnt(0)
	v_mad_i64_i32 v[2:3], s[36:37], v2, s39, v[66:67]
	ds_read_b128 v[4:7], v82
	ds_read_b128 v[8:11], v82 offset:64
	v_add_u32_e32 v0, 0x10400, v82
	s_lshl_b32 s98, s39, 4
	s_mov_b32 s99, 0
	v_add_f32_e32 v134, v134, v135
	v_add_f32_e32 v134, v134, v136
	v_add_f32_e32 v134, v134, v137
	v_fmamk_f32 v134, v134, 0x3a800000, v200
	v_rsq_f32_e32 v134, v134
	v_add_f32_e32 v138, v138, v139
	v_add_f32_e32 v138, v138, v140
	v_add_f32_e32 v138, v138, v141
	v_fmamk_f32 v138, v138, 0x3a800000, v200
	v_rsq_f32_e32 v138, v138
	v_add_f32_e32 v144, v144, v145
	v_add_f32_e32 v144, v144, v146
	v_add_f32_e32 v144, v144, v147
	v_fmamk_f32 v144, v144, 0x3a800000, v200
	v_rsq_f32_e32 v144, v144
	v_add_f32_e32 v148, v148, v149
	v_add_f32_e32 v148, v148, v150
	v_add_f32_e32 v148, v148, v151
	v_fmamk_f32 v148, v148, 0x3a800000, v200
	v_rsq_f32_e32 v148, v148
	v_add_f32_e32 v152, v152, v153
	v_add_f32_e32 v152, v152, v154
	v_add_f32_e32 v152, v152, v155
	v_fmamk_f32 v152, v152, 0x3a800000, v200
	v_rsq_f32_e32 v152, v152
	v_add_f32_e32 v156, v156, v157
	v_add_f32_e32 v156, v156, v158
	v_add_f32_e32 v156, v156, v159
	v_fmamk_f32 v156, v156, 0x3a800000, v200
	v_rsq_f32_e32 v156, v156
	v_add_f32_e32 v160, v160, v161
	v_add_f32_e32 v160, v160, v162
	v_add_f32_e32 v160, v160, v163
	v_fmamk_f32 v160, v160, 0x3a800000, v200
	v_rsq_f32_e32 v160, v160
	v_add_f32_e32 v164, v164, v165
	v_add_f32_e32 v164, v164, v166
	v_add_f32_e32 v164, v164, v167
	v_fmamk_f32 v164, v164, 0x3a800000, v200
	v_rsq_f32_e32 v164, v164
	ds_read_b128 v[12:15], v82 offset:16640
	ds_read_b128 v[16:19], v82 offset:16704
	s_waitcnt lgkmcnt(2)
	v_pk_mul_f32 v[4:5], v[4:5], v[134:135] op_sel_hi:[1,0]
	v_pk_mul_f32 v[6:7], v[6:7], v[134:135] op_sel_hi:[1,0]
	v_mul_f32_e32 v20, 0xbfb8aa3b, v4
	v_mul_f32_e32 v21, 0xbfb8aa3b, v5
	v_mul_f32_e32 v22, 0xbfb8aa3b, v6
	v_mul_f32_e32 v23, 0xbfb8aa3b, v7
	v_exp_f32_e32 v20, v20
	v_exp_f32_e32 v21, v21
	v_exp_f32_e32 v22, v22
	v_exp_f32_e32 v23, v23
	v_pk_mul_f32 v[8:9], v[8:9], v[134:135] op_sel_hi:[1,0]
	v_pk_mul_f32 v[10:11], v[10:11], v[134:135] op_sel_hi:[1,0]
	v_pk_add_f32 v[20:21], v[20:21], 1.0 op_sel_hi:[1,0]
	v_pk_add_f32 v[22:23], v[22:23], 1.0 op_sel_hi:[1,0]
	v_rcp_f32_e32 v20, v20
	v_rcp_f32_e32 v21, v21
	v_rcp_f32_e32 v22, v22
	v_rcp_f32_e32 v23, v23
	s_nop 0
	v_pk_mul_f32 v[4:5], v[4:5], v[20:21]
	v_pk_mul_f32 v[6:7], v[6:7], v[22:23]
	v_pk_mul_f32 v[4:5], v[8:9], v[4:5]
	v_pk_mul_f32 v[6:7], v[10:11], v[6:7]
	v_cvt_pk_bf16_f32 v20, v4, v5
	v_cvt_pk_bf16_f32 v21, v6, v7
	global_store_dwordx2 v[2:3], v[20:21], off
	v_lshl_add_u64 v[2:3], v[2:3], 0, s[98:99]
	ds_read_b128 v[4:7], v82 offset:33280
	ds_read_b128 v[8:11], v82 offset:33344
	s_waitcnt lgkmcnt(2)
	v_pk_mul_f32 v[12:13], v[12:13], v[138:139] op_sel_hi:[1,0]
	v_pk_mul_f32 v[14:15], v[14:15], v[138:139] op_sel_hi:[1,0]
	v_mul_f32_e32 v20, 0xbfb8aa3b, v12
	v_mul_f32_e32 v21, 0xbfb8aa3b, v13
	v_mul_f32_e32 v22, 0xbfb8aa3b, v14
	v_mul_f32_e32 v23, 0xbfb8aa3b, v15
	v_exp_f32_e32 v20, v20
	v_exp_f32_e32 v21, v21
	v_exp_f32_e32 v22, v22
	v_exp_f32_e32 v23, v23
	v_pk_mul_f32 v[16:17], v[16:17], v[138:139] op_sel_hi:[1,0]
	v_pk_mul_f32 v[18:19], v[18:19], v[138:139] op_sel_hi:[1,0]
	v_pk_add_f32 v[20:21], v[20:21], 1.0 op_sel_hi:[1,0]
	v_pk_add_f32 v[22:23], v[22:23], 1.0 op_sel_hi:[1,0]
	v_rcp_f32_e32 v20, v20
	v_rcp_f32_e32 v21, v21
	v_rcp_f32_e32 v22, v22
	v_rcp_f32_e32 v23, v23
	s_nop 0
	v_pk_mul_f32 v[12:13], v[12:13], v[20:21]
	v_pk_mul_f32 v[14:15], v[14:15], v[22:23]
	v_pk_mul_f32 v[12:13], v[16:17], v[12:13]
	v_pk_mul_f32 v[14:15], v[18:19], v[14:15]
	v_cvt_pk_bf16_f32 v20, v12, v13
	v_cvt_pk_bf16_f32 v21, v14, v15
	global_store_dwordx2 v[2:3], v[20:21], off
	v_lshl_add_u64 v[2:3], v[2:3], 0, s[98:99]
	ds_read_b128 v[12:15], v82 offset:49920
	ds_read_b128 v[16:19], v82 offset:49984
	s_waitcnt lgkmcnt(2)
	v_pk_mul_f32 v[4:5], v[4:5], v[144:145] op_sel_hi:[1,0]
	v_pk_mul_f32 v[6:7], v[6:7], v[144:145] op_sel_hi:[1,0]
	v_mul_f32_e32 v20, 0xbfb8aa3b, v4
	v_mul_f32_e32 v21, 0xbfb8aa3b, v5
	v_mul_f32_e32 v22, 0xbfb8aa3b, v6
	v_mul_f32_e32 v23, 0xbfb8aa3b, v7
	v_exp_f32_e32 v20, v20
	v_exp_f32_e32 v21, v21
	v_exp_f32_e32 v22, v22
	v_exp_f32_e32 v23, v23
	v_pk_mul_f32 v[8:9], v[8:9], v[144:145] op_sel_hi:[1,0]
	v_pk_mul_f32 v[10:11], v[10:11], v[144:145] op_sel_hi:[1,0]
	v_pk_add_f32 v[20:21], v[20:21], 1.0 op_sel_hi:[1,0]
	v_pk_add_f32 v[22:23], v[22:23], 1.0 op_sel_hi:[1,0]
	v_rcp_f32_e32 v20, v20
	v_rcp_f32_e32 v21, v21
	v_rcp_f32_e32 v22, v22
	v_rcp_f32_e32 v23, v23
	s_nop 0
	v_pk_mul_f32 v[4:5], v[4:5], v[20:21]
	v_pk_mul_f32 v[6:7], v[6:7], v[22:23]
	v_pk_mul_f32 v[4:5], v[8:9], v[4:5]
	v_pk_mul_f32 v[6:7], v[10:11], v[6:7]
	v_cvt_pk_bf16_f32 v20, v4, v5
	v_cvt_pk_bf16_f32 v21, v6, v7
	global_store_dwordx2 v[2:3], v[20:21], off
	v_lshl_add_u64 v[2:3], v[2:3], 0, s[98:99]
	ds_read_b128 v[4:7], v0
	ds_read_b128 v[8:11], v0 offset:64
	s_waitcnt lgkmcnt(2)
	v_pk_mul_f32 v[12:13], v[12:13], v[148:149] op_sel_hi:[1,0]
	v_pk_mul_f32 v[14:15], v[14:15], v[148:149] op_sel_hi:[1,0]
	v_mul_f32_e32 v20, 0xbfb8aa3b, v12
	v_mul_f32_e32 v21, 0xbfb8aa3b, v13
	v_mul_f32_e32 v22, 0xbfb8aa3b, v14
	v_mul_f32_e32 v23, 0xbfb8aa3b, v15
	v_exp_f32_e32 v20, v20
	v_exp_f32_e32 v21, v21
	v_exp_f32_e32 v22, v22
	v_exp_f32_e32 v23, v23
	v_pk_mul_f32 v[16:17], v[16:17], v[148:149] op_sel_hi:[1,0]
	v_pk_mul_f32 v[18:19], v[18:19], v[148:149] op_sel_hi:[1,0]
	v_pk_add_f32 v[20:21], v[20:21], 1.0 op_sel_hi:[1,0]
	v_pk_add_f32 v[22:23], v[22:23], 1.0 op_sel_hi:[1,0]
	v_rcp_f32_e32 v20, v20
	v_rcp_f32_e32 v21, v21
	v_rcp_f32_e32 v22, v22
	v_rcp_f32_e32 v23, v23
	s_nop 0
	v_pk_mul_f32 v[12:13], v[12:13], v[20:21]
	v_pk_mul_f32 v[14:15], v[14:15], v[22:23]
	v_pk_mul_f32 v[12:13], v[16:17], v[12:13]
	v_pk_mul_f32 v[14:15], v[18:19], v[14:15]
	v_cvt_pk_bf16_f32 v20, v12, v13
	v_cvt_pk_bf16_f32 v21, v14, v15
	global_store_dwordx2 v[2:3], v[20:21], off
	v_lshl_add_u64 v[2:3], v[2:3], 0, s[98:99]
	ds_read_b128 v[12:15], v0 offset:16640
	ds_read_b128 v[16:19], v0 offset:16704
	s_waitcnt lgkmcnt(2)
	v_pk_mul_f32 v[4:5], v[4:5], v[152:153] op_sel_hi:[1,0]
	v_pk_mul_f32 v[6:7], v[6:7], v[152:153] op_sel_hi:[1,0]
	v_mul_f32_e32 v20, 0xbfb8aa3b, v4
	v_mul_f32_e32 v21, 0xbfb8aa3b, v5
	v_mul_f32_e32 v22, 0xbfb8aa3b, v6
	v_mul_f32_e32 v23, 0xbfb8aa3b, v7
	v_exp_f32_e32 v20, v20
	v_exp_f32_e32 v21, v21
	v_exp_f32_e32 v22, v22
	v_exp_f32_e32 v23, v23
	v_pk_mul_f32 v[8:9], v[8:9], v[152:153] op_sel_hi:[1,0]
	v_pk_mul_f32 v[10:11], v[10:11], v[152:153] op_sel_hi:[1,0]
	v_pk_add_f32 v[20:21], v[20:21], 1.0 op_sel_hi:[1,0]
	v_pk_add_f32 v[22:23], v[22:23], 1.0 op_sel_hi:[1,0]
	v_rcp_f32_e32 v20, v20
	v_rcp_f32_e32 v21, v21
	v_rcp_f32_e32 v22, v22
	v_rcp_f32_e32 v23, v23
	s_nop 0
	v_pk_mul_f32 v[4:5], v[4:5], v[20:21]
	v_pk_mul_f32 v[6:7], v[6:7], v[22:23]
	v_pk_mul_f32 v[4:5], v[8:9], v[4:5]
	v_pk_mul_f32 v[6:7], v[10:11], v[6:7]
	v_cvt_pk_bf16_f32 v20, v4, v5
	v_cvt_pk_bf16_f32 v21, v6, v7
	global_store_dwordx2 v[2:3], v[20:21], off
	v_lshl_add_u64 v[2:3], v[2:3], 0, s[98:99]
	ds_read_b128 v[4:7], v0 offset:33280
	ds_read_b128 v[8:11], v0 offset:33344
	s_waitcnt lgkmcnt(2)
	v_pk_mul_f32 v[12:13], v[12:13], v[156:157] op_sel_hi:[1,0]
	v_pk_mul_f32 v[14:15], v[14:15], v[156:157] op_sel_hi:[1,0]
	v_mul_f32_e32 v20, 0xbfb8aa3b, v12
	v_mul_f32_e32 v21, 0xbfb8aa3b, v13
	v_mul_f32_e32 v22, 0xbfb8aa3b, v14
	v_mul_f32_e32 v23, 0xbfb8aa3b, v15
	v_exp_f32_e32 v20, v20
	v_exp_f32_e32 v21, v21
	v_exp_f32_e32 v22, v22
	v_exp_f32_e32 v23, v23
	v_pk_mul_f32 v[16:17], v[16:17], v[156:157] op_sel_hi:[1,0]
	v_pk_mul_f32 v[18:19], v[18:19], v[156:157] op_sel_hi:[1,0]
	v_pk_add_f32 v[20:21], v[20:21], 1.0 op_sel_hi:[1,0]
	v_pk_add_f32 v[22:23], v[22:23], 1.0 op_sel_hi:[1,0]
	v_rcp_f32_e32 v20, v20
	v_rcp_f32_e32 v21, v21
	v_rcp_f32_e32 v22, v22
	v_rcp_f32_e32 v23, v23
	s_nop 0
	v_pk_mul_f32 v[12:13], v[12:13], v[20:21]
	v_pk_mul_f32 v[14:15], v[14:15], v[22:23]
	v_pk_mul_f32 v[12:13], v[16:17], v[12:13]
	v_pk_mul_f32 v[14:15], v[18:19], v[14:15]
	v_cvt_pk_bf16_f32 v20, v12, v13
	v_cvt_pk_bf16_f32 v21, v14, v15
	global_store_dwordx2 v[2:3], v[20:21], off
	v_lshl_add_u64 v[2:3], v[2:3], 0, s[98:99]
	ds_read_b128 v[12:15], v0 offset:49920
	ds_read_b128 v[16:19], v0 offset:49984
	s_waitcnt lgkmcnt(2)
	v_pk_mul_f32 v[4:5], v[4:5], v[160:161] op_sel_hi:[1,0]
	v_pk_mul_f32 v[6:7], v[6:7], v[160:161] op_sel_hi:[1,0]
	v_mul_f32_e32 v20, 0xbfb8aa3b, v4
	v_mul_f32_e32 v21, 0xbfb8aa3b, v5
	v_mul_f32_e32 v22, 0xbfb8aa3b, v6
	v_mul_f32_e32 v23, 0xbfb8aa3b, v7
	v_exp_f32_e32 v20, v20
	v_exp_f32_e32 v21, v21
	v_exp_f32_e32 v22, v22
	v_exp_f32_e32 v23, v23
	v_pk_mul_f32 v[8:9], v[8:9], v[160:161] op_sel_hi:[1,0]
	v_pk_mul_f32 v[10:11], v[10:11], v[160:161] op_sel_hi:[1,0]
	v_pk_add_f32 v[20:21], v[20:21], 1.0 op_sel_hi:[1,0]
	v_pk_add_f32 v[22:23], v[22:23], 1.0 op_sel_hi:[1,0]
	v_rcp_f32_e32 v20, v20
	v_rcp_f32_e32 v21, v21
	v_rcp_f32_e32 v22, v22
	v_rcp_f32_e32 v23, v23
	s_nop 0
	v_pk_mul_f32 v[4:5], v[4:5], v[20:21]
	v_pk_mul_f32 v[6:7], v[6:7], v[22:23]
	v_pk_mul_f32 v[4:5], v[8:9], v[4:5]
	v_pk_mul_f32 v[6:7], v[10:11], v[6:7]
	v_cvt_pk_bf16_f32 v20, v4, v5
	v_cvt_pk_bf16_f32 v21, v6, v7
	global_store_dwordx2 v[2:3], v[20:21], off
	v_lshl_add_u64 v[2:3], v[2:3], 0, s[98:99]
	s_waitcnt lgkmcnt(0)
	v_pk_mul_f32 v[12:13], v[12:13], v[164:165] op_sel_hi:[1,0]
	v_pk_mul_f32 v[14:15], v[14:15], v[164:165] op_sel_hi:[1,0]
	v_mul_f32_e32 v20, 0xbfb8aa3b, v12
	v_mul_f32_e32 v21, 0xbfb8aa3b, v13
	v_mul_f32_e32 v22, 0xbfb8aa3b, v14
	v_mul_f32_e32 v23, 0xbfb8aa3b, v15
	v_exp_f32_e32 v20, v20
	v_exp_f32_e32 v21, v21
	v_exp_f32_e32 v22, v22
	v_exp_f32_e32 v23, v23
	v_pk_mul_f32 v[16:17], v[16:17], v[164:165] op_sel_hi:[1,0]
	v_pk_mul_f32 v[18:19], v[18:19], v[164:165] op_sel_hi:[1,0]
	v_pk_add_f32 v[20:21], v[20:21], 1.0 op_sel_hi:[1,0]
	v_pk_add_f32 v[22:23], v[22:23], 1.0 op_sel_hi:[1,0]
	v_rcp_f32_e32 v20, v20
	v_rcp_f32_e32 v21, v21
	v_rcp_f32_e32 v22, v22
	v_rcp_f32_e32 v23, v23
	s_nop 0
	v_pk_mul_f32 v[12:13], v[12:13], v[20:21]
	v_pk_mul_f32 v[14:15], v[14:15], v[22:23]
	v_pk_mul_f32 v[12:13], v[16:17], v[12:13]
	v_pk_mul_f32 v[14:15], v[18:19], v[14:15]
	v_cvt_pk_bf16_f32 v20, v12, v13
	v_cvt_pk_bf16_f32 v21, v14, v15
	global_store_dwordx2 v[2:3], v[20:21], off
	s_barrier
	s_nop 0
	v_ashrrev_i32_e32 v0, 31, v142
	v_lshrrev_b32_e32 v0, 26, v0
	v_add_u32_e32 v0, v142, v0
	v_ashrrev_i32_e32 v16, 6, v0
	v_bfe_i32 v0, v142, 27, 1
	v_lshlrev_b32_e32 v2, 4, v142
	v_lshrrev_b32_e32 v0, 22, v0
	v_add_u32_e32 v0, v2, v0
	v_and_b32_e32 v0, 0xfffffc00, v0
	v_sub_u32_e32 v0, v2, v0
	v_lshrrev_b32_e32 v3, 4, v0
	v_bitop3_b32 v3, v3, v0, 32 bitop3:0x6c
	v_ashrrev_i32_e32 v0, 31, v0
	v_lshrrev_b32_e32 v0, 26, v0
	v_add_u32_e32 v0, v3, v0
	v_ashrrev_i32_e32 v18, 6, v0
	v_mul_i32_i24_e32 v5, 64, v18
	v_sub_u32_e32 v3, v3, v5
	v_lshlrev_b32_e32 v4, 3, v16
	v_lshlrev_b32_e32 v0, 5, v16
	v_ashrrev_i16_sdwa v3, v217, sext(v3) dst_sel:DWORD dst_unused:UNUSED_PAD src0_sel:DWORD src1_sel:BYTE_0
	v_and_b32_e32 v4, 0x1ffff0, v4
	v_and_b32_e32 v0, 32, v0
	v_bfe_i32 v19, v3, 0, 16
	v_add_u32_e32 v0, v0, v19
	v_add_lshl_u32 v3, v18, v4, 11
	v_add_u32_e32 v2, 0x2000, v2
	v_lshl_add_u32 v0, v0, 1, v3
	v_ashrrev_i32_e32 v3, 31, v2
	v_lshrrev_b32_e32 v3, 22, v3
	v_add_u32_e32 v3, v2, v3
	v_ashrrev_i32_e32 v21, 10, v3
	v_mul_i32_i24_e32 v3, 0x400, v21
	v_sub_u32_e32 v2, v2, v3
	v_lshrrev_b32_e32 v3, 4, v2
	v_bitop3_b32 v2, v3, v2, 32 bitop3:0x6c
	v_ashrrev_i32_e32 v4, 31, v2
	v_ashrrev_i32_e32 v20, 6, v142
	v_lshrrev_b32_e32 v4, 26, v4
	v_readfirstlane_b32 s33, v20
	v_add_u32_e32 v4, v2, v4
	s_lshl_b32 s73, s33, 10
	v_ashrrev_i32_e32 v22, 6, v4
	v_and_b32_e32 v4, 0xc0, v4
	v_sub_u32_e32 v2, v2, v4
	s_add_u32 s70, s16, s70
	v_lshlrev_b32_e32 v3, 3, v21
	v_lshlrev_b32_e32 v5, 5, v21
	v_ashrrev_i16_sdwa v2, v217, sext(v2) dst_sel:DWORD dst_unused:UNUSED_PAD src0_sel:DWORD src1_sel:BYTE_0
	s_addc_u32 s71, s17, s71
	s_add_i32 s36, s73, 0
	v_and_b32_e32 v3, 0x1ffff0, v3
	v_and_b32_e32 v5, 32, v5
	v_bfe_i32 v23, v2, 0, 16
	s_add_i32 s37, s36, 0x10000
	v_add_u32_e32 v2, v5, v23
	v_add_lshl_u32 v3, v22, v3, 11
	s_mov_b32 m0, s37
	s_add_i32 s43, s36, 0x12000
	s_or_b32 s38, s38, 0x180
	v_lshl_add_u32 v2, v2, 1, v3
	global_load_lds_dwordx4 v0, s[70:71]
	v_mov_b32_e32 v3, v1
	s_mov_b32 m0, s43
	s_ashr_i32 s39, s38, 31
	v_lshl_add_u64 v[4:5], s[70:71], 0, v[0:1]
	v_lshl_add_u64 v[8:9], s[70:71], 0, v[2:3]
	global_load_lds_dwordx4 v2, s[70:71]
	s_mov_b32 m0, s36
	s_add_i32 s70, s36, 0x2000
	s_lshl_b64 s[38:39], s[38:39], 11
	global_load_lds_dwordx4 v0, s[54:55]
	s_mov_b32 m0, s70
	s_add_u32 s38, s16, s38
	v_lshl_add_u64 v[10:11], s[54:55], 0, v[0:1]
	v_lshl_add_u64 v[6:7], s[54:55], 0, v[2:3]
	global_load_lds_dwordx4 v2, s[54:55]
	s_addc_u32 s39, s17, s39
	s_add_i32 s54, s36, 0x14000
	s_mov_b32 m0, s54
	s_add_i32 s55, s36, 0x16000
	global_load_lds_dwordx4 v0, s[38:39]
	s_mov_b32 m0, s55
	s_add_i32 s71, s36, 0x4000
	global_load_lds_dwordx4 v2, s[38:39]
	s_mov_b32 m0, s71
	s_add_i32 s72, s36, 0x6000
	global_load_lds_dwordx4 v0, s[60:61]
	s_mov_b32 m0, s72
	v_ashrrev_i32_e32 v17, 8, v142
	global_load_lds_dwordx4 v2, s[60:61]
	v_lshl_add_u64 v[12:13], s[38:39], 0, v[0:1]
	v_lshl_add_u64 v[14:15], s[38:39], 0, v[2:3]
	v_cmp_eq_u32_e32 vcc, 1, v17
	s_and_saveexec_b64 s[38:39], vcc
	v_readlane_b32 s62, v253, 50
	s_cbranch_execz .LBB0_188
	s_barrier

.LBB0_192:
	s_or_b64 exec, exec, s[12:13]
	s_movk_i32 s11, 0x410
	v_lshrrev_b32_e32 v130, 2, v142
	v_lshlrev_b32_e32 v131, 1, v142
	v_and_b32_e32 v0, 15, v142
	v_and_b32_e32 v130, 0xfffffcc, v130
	v_and_b32_e32 v131, 0x180, v131
	v_add_u32_e32 v131, 0, v131
	v_lshlrev_b32_e32 v0, 2, v0
	v_mul_lo_u32 v130, v130, s11
	v_add3_u32 v130, v131, v0, v130
	s_waitcnt vmcnt(0)
	s_barrier
	ds_write2_b32 v130, v114, v126 offset1:16
	v_add_u32_e32 v114, 0x400, v130
	ds_write2_b32 v114, v115, v127 offset0:4 offset1:20
	v_add_u32_e32 v115, 0x800, v130
	ds_write2_b32 v115, v116, v128 offset0:8 offset1:24
	v_add_u32_e32 v116, 0xc00, v130
	ds_write2_b32 v116, v117, v129 offset0:12 offset1:28
	v_add_u32_e32 v117, 0x4000, v130
	ds_write2_b32 v117, v82, v94 offset0:64 offset1:80
	v_add_u32_e32 v94, 0x4400, v130
	ds_write2_b32 v94, v83, v95 offset0:68 offset1:84
	v_add_u32_e32 v95, 0x4800, v130
	ds_write2_b32 v95, v84, v96 offset0:72 offset1:88
	v_add_u32_e32 v96, 0x4c00, v130
	ds_write2_b32 v96, v85, v97 offset0:76 offset1:92
	v_add_u32_e32 v132, 0x8000, v130
	v_add_u32_e32 v97, 0x8400, v130
	v_add_u32_e32 v126, 0x8800, v130
	v_add_u32_e32 v127, 0x8c00, v130
	v_add_u32_e32 v133, 0xc000, v130
	v_add_u32_e32 v128, 0xc400, v130
	v_add_u32_e32 v129, 0xc800, v130
	v_add_u32_e32 v131, 0xcc00, v130
	ds_write2_b32 v132, v74, v78 offset0:128 offset1:144
	ds_write2_b32 v97, v75, v79 offset0:132 offset1:148
	ds_write2_b32 v126, v76, v80 offset0:136 offset1:152
	ds_write2_b32 v127, v77, v81 offset0:140 offset1:156
	ds_write2_b32 v133, v66, v70 offset0:192 offset1:208
	ds_write2_b32 v128, v67, v71 offset0:196 offset1:212
	ds_write2_b32 v129, v68, v72 offset0:200 offset1:216
	ds_write2_b32 v131, v69, v73 offset0:204 offset1:220
	ds_write2_b32 v130, v98, v118 offset0:128 offset1:144
	ds_write2_b32 v114, v99, v119 offset0:132 offset1:148
	ds_write2_b32 v115, v100, v120 offset0:136 offset1:152
	ds_write2_b32 v116, v101, v121 offset0:140 offset1:156
	ds_write2_b32 v117, v102, v122 offset0:192 offset1:208
	ds_write2_b32 v94, v103, v123 offset0:196 offset1:212
	ds_write2_b32 v95, v104, v124 offset0:200 offset1:216
	ds_write2_b32 v96, v105, v125 offset0:204 offset1:220
	ds_write2_b32 v97, v90, v110 offset1:16
	ds_write2_b32 v126, v91, v111 offset0:4 offset1:20
	ds_write2_b32 v127, v92, v112 offset0:8 offset1:24
	v_add_u32_e32 v90, 0x9000, v130
	ds_write2_b32 v90, v93, v113 offset0:12 offset1:28
	ds_write2_b32 v128, v86, v106 offset0:64 offset1:80
	ds_write2_b32 v129, v87, v107 offset0:68 offset1:84
	ds_write2_b32 v131, v88, v108 offset0:72 offset1:88
	v_ashrrev_i32_e32 v88, 5, v142
	v_add_u32_e32 v70, s10, v88
	v_ashrrev_i32_e32 v71, 31, v70
	v_add_u32_e32 v91, 0xd000, v130
	v_lshl_add_u64 v[72:73], v[70:71], 4, s[46:47]
	ds_write2_b32 v91, v89, v109 offset0:76 offset1:92
	s_waitcnt lgkmcnt(0)
	s_barrier
	global_load_dwordx4 v[134:137], v[72:73], off
	global_load_dwordx4 v[138:141], v[72:73], off offset:256
	global_load_dwordx4 v[144:147], v[72:73], off offset:512
	global_load_dwordx4 v[148:151], v[72:73], off offset:768
	global_load_dwordx4 v[152:155], v[72:73], off offset:1024
	global_load_dwordx4 v[156:159], v[72:73], off offset:1280
	global_load_dwordx4 v[160:163], v[72:73], off offset:1536
	global_load_dwordx4 v[164:167], v[72:73], off offset:1792
	v_lshlrev_b32_e32 v0, 3, v142
	v_lshlrev_b32_e32 v66, 2, v142
	v_and_b32_e32 v0, 0xe0, v0
	v_and_b32_e32 v69, 12, v66
	v_lshlrev_b32_e32 v66, 2, v0
	v_lshlrev_b32_e32 v67, 2, v69
	v_or_b32_e32 v0, s42, v0
	v_add3_u32 v68, 0, v66, v67
	v_ashrrev_i32_e32 v66, 1, v0
	v_readlane_b32 s12, v253, 58
	v_ashrrev_i32_e32 v67, 31, v66
	v_readlane_b32 s13, v253, 59
	v_lshlrev_b32_e32 v0, 1, v69
	s_mov_b32 s9, 0x800000
	v_lshl_add_u64 v[66:67], v[66:67], 1, s[12:13]
	v_lshl_add_u64 v[66:67], v[66:67], 0, v[0:1]
	v_mad_u64_u32 v[82:83], s[12:13], v88, s11, v[68:69]
	s_movk_i32 s14, 0x1600
	s_mov_b64 s[38:39], -1
	s_waitcnt vmcnt(0)
	v_mad_i64_i32 v[70:71], s[12:13], v70, s14, v[66:67]
	ds_read_b128 v[72:75], v82
	ds_read_b128 v[76:79], v82 offset:64
	v_add_u32_e32 v0, 0x10400, v82
	s_lshl_b32 s98, s14, 4
	s_mov_b32 s99, 0
	v_add_f32_e32 v134, v134, v135
	v_add_f32_e32 v134, v134, v136
	v_add_f32_e32 v134, v134, v137
	v_fmamk_f32 v134, v134, 0x3a800000, v200
	v_rsq_f32_e32 v134, v134
	v_add_f32_e32 v138, v138, v139
	v_add_f32_e32 v138, v138, v140
	v_add_f32_e32 v138, v138, v141
	v_fmamk_f32 v138, v138, 0x3a800000, v200
	v_rsq_f32_e32 v138, v138
	v_add_f32_e32 v144, v144, v145
	v_add_f32_e32 v144, v144, v146
	v_add_f32_e32 v144, v144, v147
	v_fmamk_f32 v144, v144, 0x3a800000, v200
	v_rsq_f32_e32 v144, v144
	v_add_f32_e32 v148, v148, v149
	v_add_f32_e32 v148, v148, v150
	v_add_f32_e32 v148, v148, v151
	v_fmamk_f32 v148, v148, 0x3a800000, v200
	v_rsq_f32_e32 v148, v148
	v_add_f32_e32 v152, v152, v153
	v_add_f32_e32 v152, v152, v154
	v_add_f32_e32 v152, v152, v155
	v_fmamk_f32 v152, v152, 0x3a800000, v200
	v_rsq_f32_e32 v152, v152
	v_add_f32_e32 v156, v156, v157
	v_add_f32_e32 v156, v156, v158
	v_add_f32_e32 v156, v156, v159
	v_fmamk_f32 v156, v156, 0x3a800000, v200
	v_rsq_f32_e32 v156, v156
	v_add_f32_e32 v160, v160, v161
	v_add_f32_e32 v160, v160, v162
	v_add_f32_e32 v160, v160, v163
	v_fmamk_f32 v160, v160, 0x3a800000, v200
	v_rsq_f32_e32 v160, v160
	v_add_f32_e32 v164, v164, v165
	v_add_f32_e32 v164, v164, v166
	v_add_f32_e32 v164, v164, v167
	v_fmamk_f32 v164, v164, 0x3a800000, v200
	v_rsq_f32_e32 v164, v164
	ds_read_b128 v[84:87], v82 offset:16640
	ds_read_b128 v[98:101], v82 offset:16704
	s_waitcnt lgkmcnt(2)
	v_pk_mul_f32 v[72:73], v[72:73], v[134:135] op_sel_hi:[1,0]
	v_pk_mul_f32 v[74:75], v[74:75], v[134:135] op_sel_hi:[1,0]
	v_mul_f32_e32 v102, 0xbfb8aa3b, v72
	v_mul_f32_e32 v103, 0xbfb8aa3b, v73
	v_mul_f32_e32 v104, 0xbfb8aa3b, v74
	v_mul_f32_e32 v105, 0xbfb8aa3b, v75
	v_exp_f32_e32 v102, v102
	v_exp_f32_e32 v103, v103
	v_exp_f32_e32 v104, v104
	v_exp_f32_e32 v105, v105
	v_pk_mul_f32 v[76:77], v[76:77], v[134:135] op_sel_hi:[1,0]
	v_pk_mul_f32 v[78:79], v[78:79], v[134:135] op_sel_hi:[1,0]
	v_pk_add_f32 v[102:103], v[102:103], 1.0 op_sel_hi:[1,0]
	v_pk_add_f32 v[104:105], v[104:105], 1.0 op_sel_hi:[1,0]
	v_rcp_f32_e32 v102, v102
	v_rcp_f32_e32 v103, v103
	v_rcp_f32_e32 v104, v104
	v_rcp_f32_e32 v105, v105
	s_nop 0
	v_pk_mul_f32 v[72:73], v[72:73], v[102:103]
	v_pk_mul_f32 v[74:75], v[74:75], v[104:105]
	v_pk_mul_f32 v[72:73], v[76:77], v[72:73]
	v_pk_mul_f32 v[74:75], v[78:79], v[74:75]
	v_cvt_pk_bf16_f32 v102, v72, v73
	v_cvt_pk_bf16_f32 v103, v74, v75
	global_store_dwordx2 v[70:71], v[102:103], off
	v_lshl_add_u64 v[70:71], v[70:71], 0, s[98:99]
	ds_read_b128 v[72:75], v82 offset:33280
	ds_read_b128 v[76:79], v82 offset:33344
	s_waitcnt lgkmcnt(2)
	v_pk_mul_f32 v[84:85], v[84:85], v[138:139] op_sel_hi:[1,0]
	v_pk_mul_f32 v[86:87], v[86:87], v[138:139] op_sel_hi:[1,0]
	v_mul_f32_e32 v102, 0xbfb8aa3b, v84
	v_mul_f32_e32 v103, 0xbfb8aa3b, v85
	v_mul_f32_e32 v104, 0xbfb8aa3b, v86
	v_mul_f32_e32 v105, 0xbfb8aa3b, v87
	v_exp_f32_e32 v102, v102
	v_exp_f32_e32 v103, v103
	v_exp_f32_e32 v104, v104
	v_exp_f32_e32 v105, v105
	v_pk_mul_f32 v[98:99], v[98:99], v[138:139] op_sel_hi:[1,0]
	v_pk_mul_f32 v[100:101], v[100:101], v[138:139] op_sel_hi:[1,0]
	v_pk_add_f32 v[102:103], v[102:103], 1.0 op_sel_hi:[1,0]
	v_pk_add_f32 v[104:105], v[104:105], 1.0 op_sel_hi:[1,0]
	v_rcp_f32_e32 v102, v102
	v_rcp_f32_e32 v103, v103
	v_rcp_f32_e32 v104, v104
	v_rcp_f32_e32 v105, v105
	s_nop 0
	v_pk_mul_f32 v[84:85], v[84:85], v[102:103]
	v_pk_mul_f32 v[86:87], v[86:87], v[104:105]
	v_pk_mul_f32 v[84:85], v[98:99], v[84:85]
	v_pk_mul_f32 v[86:87], v[100:101], v[86:87]
	v_cvt_pk_bf16_f32 v102, v84, v85
	v_cvt_pk_bf16_f32 v103, v86, v87
	global_store_dwordx2 v[70:71], v[102:103], off
	v_lshl_add_u64 v[70:71], v[70:71], 0, s[98:99]
	ds_read_b128 v[84:87], v82 offset:49920
	ds_read_b128 v[98:101], v82 offset:49984
	s_waitcnt lgkmcnt(2)
	v_pk_mul_f32 v[72:73], v[72:73], v[144:145] op_sel_hi:[1,0]
	v_pk_mul_f32 v[74:75], v[74:75], v[144:145] op_sel_hi:[1,0]
	v_mul_f32_e32 v102, 0xbfb8aa3b, v72
	v_mul_f32_e32 v103, 0xbfb8aa3b, v73
	v_mul_f32_e32 v104, 0xbfb8aa3b, v74
	v_mul_f32_e32 v105, 0xbfb8aa3b, v75
	v_exp_f32_e32 v102, v102
	v_exp_f32_e32 v103, v103
	v_exp_f32_e32 v104, v104
	v_exp_f32_e32 v105, v105
	v_pk_mul_f32 v[76:77], v[76:77], v[144:145] op_sel_hi:[1,0]
	v_pk_mul_f32 v[78:79], v[78:79], v[144:145] op_sel_hi:[1,0]
	v_pk_add_f32 v[102:103], v[102:103], 1.0 op_sel_hi:[1,0]
	v_pk_add_f32 v[104:105], v[104:105], 1.0 op_sel_hi:[1,0]
	v_rcp_f32_e32 v102, v102
	v_rcp_f32_e32 v103, v103
	v_rcp_f32_e32 v104, v104
	v_rcp_f32_e32 v105, v105
	s_nop 0
	v_pk_mul_f32 v[72:73], v[72:73], v[102:103]
	v_pk_mul_f32 v[74:75], v[74:75], v[104:105]
	v_pk_mul_f32 v[72:73], v[76:77], v[72:73]
	v_pk_mul_f32 v[74:75], v[78:79], v[74:75]
	v_cvt_pk_bf16_f32 v102, v72, v73
	v_cvt_pk_bf16_f32 v103, v74, v75
	global_store_dwordx2 v[70:71], v[102:103], off
	v_lshl_add_u64 v[70:71], v[70:71], 0, s[98:99]
	ds_read_b128 v[72:75], v0
	ds_read_b128 v[76:79], v0 offset:64
	s_waitcnt lgkmcnt(2)
	v_pk_mul_f32 v[84:85], v[84:85], v[148:149] op_sel_hi:[1,0]
	v_pk_mul_f32 v[86:87], v[86:87], v[148:149] op_sel_hi:[1,0]
	v_mul_f32_e32 v102, 0xbfb8aa3b, v84
	v_mul_f32_e32 v103, 0xbfb8aa3b, v85
	v_mul_f32_e32 v104, 0xbfb8aa3b, v86
	v_mul_f32_e32 v105, 0xbfb8aa3b, v87
	v_exp_f32_e32 v102, v102
	v_exp_f32_e32 v103, v103
	v_exp_f32_e32 v104, v104
	v_exp_f32_e32 v105, v105
	v_pk_mul_f32 v[98:99], v[98:99], v[148:149] op_sel_hi:[1,0]
	v_pk_mul_f32 v[100:101], v[100:101], v[148:149] op_sel_hi:[1,0]
	v_pk_add_f32 v[102:103], v[102:103], 1.0 op_sel_hi:[1,0]
	v_pk_add_f32 v[104:105], v[104:105], 1.0 op_sel_hi:[1,0]
	v_rcp_f32_e32 v102, v102
	v_rcp_f32_e32 v103, v103
	v_rcp_f32_e32 v104, v104
	v_rcp_f32_e32 v105, v105
	s_nop 0
	v_pk_mul_f32 v[84:85], v[84:85], v[102:103]
	v_pk_mul_f32 v[86:87], v[86:87], v[104:105]
	v_pk_mul_f32 v[84:85], v[98:99], v[84:85]
	v_pk_mul_f32 v[86:87], v[100:101], v[86:87]
	v_cvt_pk_bf16_f32 v102, v84, v85
	v_cvt_pk_bf16_f32 v103, v86, v87
	global_store_dwordx2 v[70:71], v[102:103], off
	v_lshl_add_u64 v[70:71], v[70:71], 0, s[98:99]
	ds_read_b128 v[84:87], v0 offset:16640
	ds_read_b128 v[98:101], v0 offset:16704
	s_waitcnt lgkmcnt(2)
	v_pk_mul_f32 v[72:73], v[72:73], v[152:153] op_sel_hi:[1,0]
	v_pk_mul_f32 v[74:75], v[74:75], v[152:153] op_sel_hi:[1,0]
	v_mul_f32_e32 v102, 0xbfb8aa3b, v72
	v_mul_f32_e32 v103, 0xbfb8aa3b, v73
	v_mul_f32_e32 v104, 0xbfb8aa3b, v74
	v_mul_f32_e32 v105, 0xbfb8aa3b, v75
	v_exp_f32_e32 v102, v102
	v_exp_f32_e32 v103, v103
	v_exp_f32_e32 v104, v104
	v_exp_f32_e32 v105, v105
	v_pk_mul_f32 v[76:77], v[76:77], v[152:153] op_sel_hi:[1,0]
	v_pk_mul_f32 v[78:79], v[78:79], v[152:153] op_sel_hi:[1,0]
	v_pk_add_f32 v[102:103], v[102:103], 1.0 op_sel_hi:[1,0]
	v_pk_add_f32 v[104:105], v[104:105], 1.0 op_sel_hi:[1,0]
	v_rcp_f32_e32 v102, v102
	v_rcp_f32_e32 v103, v103
	v_rcp_f32_e32 v104, v104
	v_rcp_f32_e32 v105, v105
	s_nop 0
	v_pk_mul_f32 v[72:73], v[72:73], v[102:103]
	v_pk_mul_f32 v[74:75], v[74:75], v[104:105]
	v_pk_mul_f32 v[72:73], v[76:77], v[72:73]
	v_pk_mul_f32 v[74:75], v[78:79], v[74:75]
	v_cvt_pk_bf16_f32 v102, v72, v73
	v_cvt_pk_bf16_f32 v103, v74, v75
	global_store_dwordx2 v[70:71], v[102:103], off
	v_lshl_add_u64 v[70:71], v[70:71], 0, s[98:99]
	ds_read_b128 v[72:75], v0 offset:33280
	ds_read_b128 v[76:79], v0 offset:33344
	s_waitcnt lgkmcnt(2)
	v_pk_mul_f32 v[84:85], v[84:85], v[156:157] op_sel_hi:[1,0]
	v_pk_mul_f32 v[86:87], v[86:87], v[156:157] op_sel_hi:[1,0]
	v_mul_f32_e32 v102, 0xbfb8aa3b, v84
	v_mul_f32_e32 v103, 0xbfb8aa3b, v85
	v_mul_f32_e32 v104, 0xbfb8aa3b, v86
	v_mul_f32_e32 v105, 0xbfb8aa3b, v87
	v_exp_f32_e32 v102, v102
	v_exp_f32_e32 v103, v103
	v_exp_f32_e32 v104, v104
	v_exp_f32_e32 v105, v105
	v_pk_mul_f32 v[98:99], v[98:99], v[156:157] op_sel_hi:[1,0]
	v_pk_mul_f32 v[100:101], v[100:101], v[156:157] op_sel_hi:[1,0]
	v_pk_add_f32 v[102:103], v[102:103], 1.0 op_sel_hi:[1,0]
	v_pk_add_f32 v[104:105], v[104:105], 1.0 op_sel_hi:[1,0]
	v_rcp_f32_e32 v102, v102
	v_rcp_f32_e32 v103, v103
	v_rcp_f32_e32 v104, v104
	v_rcp_f32_e32 v105, v105
	s_nop 0
	v_pk_mul_f32 v[84:85], v[84:85], v[102:103]
	v_pk_mul_f32 v[86:87], v[86:87], v[104:105]
	v_pk_mul_f32 v[84:85], v[98:99], v[84:85]
	v_pk_mul_f32 v[86:87], v[100:101], v[86:87]
	v_cvt_pk_bf16_f32 v102, v84, v85
	v_cvt_pk_bf16_f32 v103, v86, v87
	global_store_dwordx2 v[70:71], v[102:103], off
	v_lshl_add_u64 v[70:71], v[70:71], 0, s[98:99]
	ds_read_b128 v[84:87], v0 offset:49920
	ds_read_b128 v[98:101], v0 offset:49984
	s_waitcnt lgkmcnt(2)
	v_pk_mul_f32 v[72:73], v[72:73], v[160:161] op_sel_hi:[1,0]
	v_pk_mul_f32 v[74:75], v[74:75], v[160:161] op_sel_hi:[1,0]
	v_mul_f32_e32 v102, 0xbfb8aa3b, v72
	v_mul_f32_e32 v103, 0xbfb8aa3b, v73
	v_mul_f32_e32 v104, 0xbfb8aa3b, v74
	v_mul_f32_e32 v105, 0xbfb8aa3b, v75
	v_exp_f32_e32 v102, v102
	v_exp_f32_e32 v103, v103
	v_exp_f32_e32 v104, v104
	v_exp_f32_e32 v105, v105
	v_pk_mul_f32 v[76:77], v[76:77], v[160:161] op_sel_hi:[1,0]
	v_pk_mul_f32 v[78:79], v[78:79], v[160:161] op_sel_hi:[1,0]
	v_pk_add_f32 v[102:103], v[102:103], 1.0 op_sel_hi:[1,0]
	v_pk_add_f32 v[104:105], v[104:105], 1.0 op_sel_hi:[1,0]
	v_rcp_f32_e32 v102, v102
	v_rcp_f32_e32 v103, v103
	v_rcp_f32_e32 v104, v104
	v_rcp_f32_e32 v105, v105
	s_nop 0
	v_pk_mul_f32 v[72:73], v[72:73], v[102:103]
	v_pk_mul_f32 v[74:75], v[74:75], v[104:105]
	v_pk_mul_f32 v[72:73], v[76:77], v[72:73]
	v_pk_mul_f32 v[74:75], v[78:79], v[74:75]
	v_cvt_pk_bf16_f32 v102, v72, v73
	v_cvt_pk_bf16_f32 v103, v74, v75
	global_store_dwordx2 v[70:71], v[102:103], off
	v_lshl_add_u64 v[70:71], v[70:71], 0, s[98:99]
	s_waitcnt lgkmcnt(0)
	v_pk_mul_f32 v[84:85], v[84:85], v[164:165] op_sel_hi:[1,0]
	v_pk_mul_f32 v[86:87], v[86:87], v[164:165] op_sel_hi:[1,0]
	v_mul_f32_e32 v102, 0xbfb8aa3b, v84
	v_mul_f32_e32 v103, 0xbfb8aa3b, v85
	v_mul_f32_e32 v104, 0xbfb8aa3b, v86
	v_mul_f32_e32 v105, 0xbfb8aa3b, v87
	v_exp_f32_e32 v102, v102
	v_exp_f32_e32 v103, v103
	v_exp_f32_e32 v104, v104
	v_exp_f32_e32 v105, v105
	v_pk_mul_f32 v[98:99], v[98:99], v[164:165] op_sel_hi:[1,0]
	v_pk_mul_f32 v[100:101], v[100:101], v[164:165] op_sel_hi:[1,0]
	v_pk_add_f32 v[102:103], v[102:103], 1.0 op_sel_hi:[1,0]
	v_pk_add_f32 v[104:105], v[104:105], 1.0 op_sel_hi:[1,0]
	v_rcp_f32_e32 v102, v102
	v_rcp_f32_e32 v103, v103
	v_rcp_f32_e32 v104, v104
	v_rcp_f32_e32 v105, v105
	s_nop 0
	v_pk_mul_f32 v[84:85], v[84:85], v[102:103]
	v_pk_mul_f32 v[86:87], v[86:87], v[104:105]
	v_pk_mul_f32 v[84:85], v[98:99], v[84:85]
	v_pk_mul_f32 v[86:87], v[100:101], v[86:87]
	v_cvt_pk_bf16_f32 v102, v84, v85
	v_cvt_pk_bf16_f32 v103, v86, v87
	global_store_dwordx2 v[70:71], v[102:103], off
	s_barrier
	ds_write2_b32 v130, v2, v18 offset1:16
	ds_write2_b32 v114, v3, v19 offset0:4 offset1:20
	ds_write2_b32 v115, v4, v20 offset0:8 offset1:24
	ds_write2_b32 v116, v5, v21 offset0:12 offset1:28
	ds_write2_b32 v117, v6, v22 offset0:64 offset1:80
	ds_write2_b32 v94, v7, v23 offset0:68 offset1:84
	ds_write2_b32 v95, v8, v24 offset0:72 offset1:88
	ds_write2_b32 v96, v9, v25 offset0:76 offset1:92
	ds_write2_b32 v132, v10, v26 offset0:128 offset1:144
	ds_write2_b32 v97, v11, v27 offset0:132 offset1:148
	ds_write2_b32 v126, v12, v28 offset0:136 offset1:152
	ds_write2_b32 v127, v13, v29 offset0:140 offset1:156
	ds_write2_b32 v133, v14, v30 offset0:192 offset1:208
	ds_write2_b32 v128, v15, v31 offset0:196 offset1:212
	ds_write2_b32 v129, v16, v32 offset0:200 offset1:216
	ds_write2_b32 v131, v17, v33 offset0:204 offset1:220
	ds_write2_b32 v130, v34, v50 offset0:128 offset1:144
	ds_write2_b32 v114, v35, v51 offset0:132 offset1:148
	ds_write2_b32 v115, v36, v52 offset0:136 offset1:152
	ds_write2_b32 v116, v37, v53 offset0:140 offset1:156
	ds_write2_b32 v117, v38, v54 offset0:192 offset1:208
	ds_write2_b32 v94, v39, v55 offset0:196 offset1:212
	ds_write2_b32 v95, v40, v56 offset0:200 offset1:216
	ds_write2_b32 v96, v41, v57 offset0:204 offset1:220
	ds_write2_b32 v97, v42, v58 offset1:16
	ds_write2_b32 v126, v43, v59 offset0:4 offset1:20
	ds_write2_b32 v127, v44, v60 offset0:8 offset1:24
	ds_write2_b32 v90, v45, v61 offset0:12 offset1:28
	ds_write2_b32 v128, v46, v62 offset0:64 offset1:80
	ds_write2_b32 v129, v47, v63 offset0:68 offset1:84
	ds_write2_b32 v131, v48, v64 offset0:72 offset1:88
	ds_write2_b32 v91, v49, v65 offset0:76 offset1:92
	v_add_u32_e32 v2, s8, v88
	v_ashrrev_i32_e32 v3, 31, v2
	v_lshl_add_u64 v[4:5], v[2:3], 4, s[46:47]
	s_waitcnt lgkmcnt(0)
	s_barrier
	global_load_dwordx4 v[134:137], v[4:5], off
	global_load_dwordx4 v[138:141], v[4:5], off offset:256
	global_load_dwordx4 v[144:147], v[4:5], off offset:512
	global_load_dwordx4 v[148:151], v[4:5], off offset:768
	global_load_dwordx4 v[152:155], v[4:5], off offset:1024
	global_load_dwordx4 v[156:159], v[4:5], off offset:1280
	global_load_dwordx4 v[160:163], v[4:5], off offset:1536
	global_load_dwordx4 v[164:167], v[4:5], off offset:1792
	s_waitcnt vmcnt(0)
	v_mad_i64_i32 v[2:3], s[10:11], v2, s14, v[66:67]
	ds_read_b128 v[4:7], v82
	ds_read_b128 v[8:11], v82 offset:64
	v_add_u32_e32 v0, 0x10400, v82
	s_lshl_b32 s98, s14, 4
	s_mov_b32 s99, 0
	v_add_f32_e32 v134, v134, v135
	v_add_f32_e32 v134, v134, v136
	v_add_f32_e32 v134, v134, v137
	v_fmamk_f32 v134, v134, 0x3a800000, v200
	v_rsq_f32_e32 v134, v134
	v_add_f32_e32 v138, v138, v139
	v_add_f32_e32 v138, v138, v140
	v_add_f32_e32 v138, v138, v141
	v_fmamk_f32 v138, v138, 0x3a800000, v200
	v_rsq_f32_e32 v138, v138
	v_add_f32_e32 v144, v144, v145
	v_add_f32_e32 v144, v144, v146
	v_add_f32_e32 v144, v144, v147
	v_fmamk_f32 v144, v144, 0x3a800000, v200
	v_rsq_f32_e32 v144, v144
	v_add_f32_e32 v148, v148, v149
	v_add_f32_e32 v148, v148, v150
	v_add_f32_e32 v148, v148, v151
	v_fmamk_f32 v148, v148, 0x3a800000, v200
	v_rsq_f32_e32 v148, v148
	v_add_f32_e32 v152, v152, v153
	v_add_f32_e32 v152, v152, v154
	v_add_f32_e32 v152, v152, v155
	v_fmamk_f32 v152, v152, 0x3a800000, v200
	v_rsq_f32_e32 v152, v152
	v_add_f32_e32 v156, v156, v157
	v_add_f32_e32 v156, v156, v158
	v_add_f32_e32 v156, v156, v159
	v_fmamk_f32 v156, v156, 0x3a800000, v200
	v_rsq_f32_e32 v156, v156
	v_add_f32_e32 v160, v160, v161
	v_add_f32_e32 v160, v160, v162
	v_add_f32_e32 v160, v160, v163
	v_fmamk_f32 v160, v160, 0x3a800000, v200
	v_rsq_f32_e32 v160, v160
	v_add_f32_e32 v164, v164, v165
	v_add_f32_e32 v164, v164, v166
	v_add_f32_e32 v164, v164, v167
	v_fmamk_f32 v164, v164, 0x3a800000, v200
	v_rsq_f32_e32 v164, v164
	ds_read_b128 v[12:15], v82 offset:16640
	ds_read_b128 v[16:19], v82 offset:16704
	s_waitcnt lgkmcnt(2)
	v_pk_mul_f32 v[4:5], v[4:5], v[134:135] op_sel_hi:[1,0]
	v_pk_mul_f32 v[6:7], v[6:7], v[134:135] op_sel_hi:[1,0]
	v_mul_f32_e32 v20, 0xbfb8aa3b, v4
	v_mul_f32_e32 v21, 0xbfb8aa3b, v5
	v_mul_f32_e32 v22, 0xbfb8aa3b, v6
	v_mul_f32_e32 v23, 0xbfb8aa3b, v7
	v_exp_f32_e32 v20, v20
	v_exp_f32_e32 v21, v21
	v_exp_f32_e32 v22, v22
	v_exp_f32_e32 v23, v23
	v_pk_mul_f32 v[8:9], v[8:9], v[134:135] op_sel_hi:[1,0]
	v_pk_mul_f32 v[10:11], v[10:11], v[134:135] op_sel_hi:[1,0]
	v_pk_add_f32 v[20:21], v[20:21], 1.0 op_sel_hi:[1,0]
	v_pk_add_f32 v[22:23], v[22:23], 1.0 op_sel_hi:[1,0]
	v_rcp_f32_e32 v20, v20
	v_rcp_f32_e32 v21, v21
	v_rcp_f32_e32 v22, v22
	v_rcp_f32_e32 v23, v23
	s_nop 0
	v_pk_mul_f32 v[4:5], v[4:5], v[20:21]
	v_pk_mul_f32 v[6:7], v[6:7], v[22:23]
	v_pk_mul_f32 v[4:5], v[8:9], v[4:5]
	v_pk_mul_f32 v[6:7], v[10:11], v[6:7]
	v_cvt_pk_bf16_f32 v20, v4, v5
	v_cvt_pk_bf16_f32 v21, v6, v7
	global_store_dwordx2 v[2:3], v[20:21], off
	v_lshl_add_u64 v[2:3], v[2:3], 0, s[98:99]
	ds_read_b128 v[4:7], v82 offset:33280
	ds_read_b128 v[8:11], v82 offset:33344
	s_waitcnt lgkmcnt(2)
	v_pk_mul_f32 v[12:13], v[12:13], v[138:139] op_sel_hi:[1,0]
	v_pk_mul_f32 v[14:15], v[14:15], v[138:139] op_sel_hi:[1,0]
	v_mul_f32_e32 v20, 0xbfb8aa3b, v12
	v_mul_f32_e32 v21, 0xbfb8aa3b, v13
	v_mul_f32_e32 v22, 0xbfb8aa3b, v14
	v_mul_f32_e32 v23, 0xbfb8aa3b, v15
	v_exp_f32_e32 v20, v20
	v_exp_f32_e32 v21, v21
	v_exp_f32_e32 v22, v22
	v_exp_f32_e32 v23, v23
	v_pk_mul_f32 v[16:17], v[16:17], v[138:139] op_sel_hi:[1,0]
	v_pk_mul_f32 v[18:19], v[18:19], v[138:139] op_sel_hi:[1,0]
	v_pk_add_f32 v[20:21], v[20:21], 1.0 op_sel_hi:[1,0]
	v_pk_add_f32 v[22:23], v[22:23], 1.0 op_sel_hi:[1,0]
	v_rcp_f32_e32 v20, v20
	v_rcp_f32_e32 v21, v21
	v_rcp_f32_e32 v22, v22
	v_rcp_f32_e32 v23, v23
	s_nop 0
	v_pk_mul_f32 v[12:13], v[12:13], v[20:21]
	v_pk_mul_f32 v[14:15], v[14:15], v[22:23]
	v_pk_mul_f32 v[12:13], v[16:17], v[12:13]
	v_pk_mul_f32 v[14:15], v[18:19], v[14:15]
	v_cvt_pk_bf16_f32 v20, v12, v13
	v_cvt_pk_bf16_f32 v21, v14, v15
	global_store_dwordx2 v[2:3], v[20:21], off
	v_lshl_add_u64 v[2:3], v[2:3], 0, s[98:99]
	ds_read_b128 v[12:15], v82 offset:49920
	ds_read_b128 v[16:19], v82 offset:49984
	s_waitcnt lgkmcnt(2)
	v_pk_mul_f32 v[4:5], v[4:5], v[144:145] op_sel_hi:[1,0]
	v_pk_mul_f32 v[6:7], v[6:7], v[144:145] op_sel_hi:[1,0]
	v_mul_f32_e32 v20, 0xbfb8aa3b, v4
	v_mul_f32_e32 v21, 0xbfb8aa3b, v5
	v_mul_f32_e32 v22, 0xbfb8aa3b, v6
	v_mul_f32_e32 v23, 0xbfb8aa3b, v7
	v_exp_f32_e32 v20, v20
	v_exp_f32_e32 v21, v21
	v_exp_f32_e32 v22, v22
	v_exp_f32_e32 v23, v23
	v_pk_mul_f32 v[8:9], v[8:9], v[144:145] op_sel_hi:[1,0]
	v_pk_mul_f32 v[10:11], v[10:11], v[144:145] op_sel_hi:[1,0]
	v_pk_add_f32 v[20:21], v[20:21], 1.0 op_sel_hi:[1,0]
	v_pk_add_f32 v[22:23], v[22:23], 1.0 op_sel_hi:[1,0]
	v_rcp_f32_e32 v20, v20
	v_rcp_f32_e32 v21, v21
	v_rcp_f32_e32 v22, v22
	v_rcp_f32_e32 v23, v23
	s_nop 0
	v_pk_mul_f32 v[4:5], v[4:5], v[20:21]
	v_pk_mul_f32 v[6:7], v[6:7], v[22:23]
	v_pk_mul_f32 v[4:5], v[8:9], v[4:5]
	v_pk_mul_f32 v[6:7], v[10:11], v[6:7]
	v_cvt_pk_bf16_f32 v20, v4, v5
	v_cvt_pk_bf16_f32 v21, v6, v7
	global_store_dwordx2 v[2:3], v[20:21], off
	v_lshl_add_u64 v[2:3], v[2:3], 0, s[98:99]
	ds_read_b128 v[4:7], v0
	ds_read_b128 v[8:11], v0 offset:64
	s_waitcnt lgkmcnt(2)
	v_pk_mul_f32 v[12:13], v[12:13], v[148:149] op_sel_hi:[1,0]
	v_pk_mul_f32 v[14:15], v[14:15], v[148:149] op_sel_hi:[1,0]
	v_mul_f32_e32 v20, 0xbfb8aa3b, v12
	v_mul_f32_e32 v21, 0xbfb8aa3b, v13
	v_mul_f32_e32 v22, 0xbfb8aa3b, v14
	v_mul_f32_e32 v23, 0xbfb8aa3b, v15
	v_exp_f32_e32 v20, v20
	v_exp_f32_e32 v21, v21
	v_exp_f32_e32 v22, v22
	v_exp_f32_e32 v23, v23
	v_pk_mul_f32 v[16:17], v[16:17], v[148:149] op_sel_hi:[1,0]
	v_pk_mul_f32 v[18:19], v[18:19], v[148:149] op_sel_hi:[1,0]
	v_pk_add_f32 v[20:21], v[20:21], 1.0 op_sel_hi:[1,0]
	v_pk_add_f32 v[22:23], v[22:23], 1.0 op_sel_hi:[1,0]
	v_rcp_f32_e32 v20, v20
	v_rcp_f32_e32 v21, v21
	v_rcp_f32_e32 v22, v22
	v_rcp_f32_e32 v23, v23
	s_nop 0
	v_pk_mul_f32 v[12:13], v[12:13], v[20:21]
	v_pk_mul_f32 v[14:15], v[14:15], v[22:23]
	v_pk_mul_f32 v[12:13], v[16:17], v[12:13]
	v_pk_mul_f32 v[14:15], v[18:19], v[14:15]
	v_cvt_pk_bf16_f32 v20, v12, v13
	v_cvt_pk_bf16_f32 v21, v14, v15
	global_store_dwordx2 v[2:3], v[20:21], off
	v_lshl_add_u64 v[2:3], v[2:3], 0, s[98:99]
	ds_read_b128 v[12:15], v0 offset:16640
	ds_read_b128 v[16:19], v0 offset:16704
	s_waitcnt lgkmcnt(2)
	v_pk_mul_f32 v[4:5], v[4:5], v[152:153] op_sel_hi:[1,0]
	v_pk_mul_f32 v[6:7], v[6:7], v[152:153] op_sel_hi:[1,0]
	v_mul_f32_e32 v20, 0xbfb8aa3b, v4
	v_mul_f32_e32 v21, 0xbfb8aa3b, v5
	v_mul_f32_e32 v22, 0xbfb8aa3b, v6
	v_mul_f32_e32 v23, 0xbfb8aa3b, v7
	v_exp_f32_e32 v20, v20
	v_exp_f32_e32 v21, v21
	v_exp_f32_e32 v22, v22
	v_exp_f32_e32 v23, v23
	v_pk_mul_f32 v[8:9], v[8:9], v[152:153] op_sel_hi:[1,0]
	v_pk_mul_f32 v[10:11], v[10:11], v[152:153] op_sel_hi:[1,0]
	v_pk_add_f32 v[20:21], v[20:21], 1.0 op_sel_hi:[1,0]
	v_pk_add_f32 v[22:23], v[22:23], 1.0 op_sel_hi:[1,0]
	v_rcp_f32_e32 v20, v20
	v_rcp_f32_e32 v21, v21
	v_rcp_f32_e32 v22, v22
	v_rcp_f32_e32 v23, v23
	s_nop 0
	v_pk_mul_f32 v[4:5], v[4:5], v[20:21]
	v_pk_mul_f32 v[6:7], v[6:7], v[22:23]
	v_pk_mul_f32 v[4:5], v[8:9], v[4:5]
	v_pk_mul_f32 v[6:7], v[10:11], v[6:7]
	v_cvt_pk_bf16_f32 v20, v4, v5
	v_cvt_pk_bf16_f32 v21, v6, v7
	global_store_dwordx2 v[2:3], v[20:21], off
	v_lshl_add_u64 v[2:3], v[2:3], 0, s[98:99]
	ds_read_b128 v[4:7], v0 offset:33280
	ds_read_b128 v[8:11], v0 offset:33344
	s_waitcnt lgkmcnt(2)
	v_pk_mul_f32 v[12:13], v[12:13], v[156:157] op_sel_hi:[1,0]
	v_pk_mul_f32 v[14:15], v[14:15], v[156:157] op_sel_hi:[1,0]
	v_mul_f32_e32 v20, 0xbfb8aa3b, v12
	v_mul_f32_e32 v21, 0xbfb8aa3b, v13
	v_mul_f32_e32 v22, 0xbfb8aa3b, v14
	v_mul_f32_e32 v23, 0xbfb8aa3b, v15
	v_exp_f32_e32 v20, v20
	v_exp_f32_e32 v21, v21
	v_exp_f32_e32 v22, v22
	v_exp_f32_e32 v23, v23
	v_pk_mul_f32 v[16:17], v[16:17], v[156:157] op_sel_hi:[1,0]
	v_pk_mul_f32 v[18:19], v[18:19], v[156:157] op_sel_hi:[1,0]
	v_pk_add_f32 v[20:21], v[20:21], 1.0 op_sel_hi:[1,0]
	v_pk_add_f32 v[22:23], v[22:23], 1.0 op_sel_hi:[1,0]
	v_rcp_f32_e32 v20, v20
	v_rcp_f32_e32 v21, v21
	v_rcp_f32_e32 v22, v22
	v_rcp_f32_e32 v23, v23
	s_nop 0
	v_pk_mul_f32 v[12:13], v[12:13], v[20:21]
	v_pk_mul_f32 v[14:15], v[14:15], v[22:23]
	v_pk_mul_f32 v[12:13], v[16:17], v[12:13]
	v_pk_mul_f32 v[14:15], v[18:19], v[14:15]
	v_cvt_pk_bf16_f32 v20, v12, v13
	v_cvt_pk_bf16_f32 v21, v14, v15
	global_store_dwordx2 v[2:3], v[20:21], off
	v_lshl_add_u64 v[2:3], v[2:3], 0, s[98:99]
	ds_read_b128 v[12:15], v0 offset:49920
	ds_read_b128 v[16:19], v0 offset:49984
	s_waitcnt lgkmcnt(2)
	v_pk_mul_f32 v[4:5], v[4:5], v[160:161] op_sel_hi:[1,0]
	v_pk_mul_f32 v[6:7], v[6:7], v[160:161] op_sel_hi:[1,0]
	v_mul_f32_e32 v20, 0xbfb8aa3b, v4
	v_mul_f32_e32 v21, 0xbfb8aa3b, v5
	v_mul_f32_e32 v22, 0xbfb8aa3b, v6
	v_mul_f32_e32 v23, 0xbfb8aa3b, v7
	v_exp_f32_e32 v20, v20
	v_exp_f32_e32 v21, v21
	v_exp_f32_e32 v22, v22
	v_exp_f32_e32 v23, v23
	v_pk_mul_f32 v[8:9], v[8:9], v[160:161] op_sel_hi:[1,0]
	v_pk_mul_f32 v[10:11], v[10:11], v[160:161] op_sel_hi:[1,0]
	v_pk_add_f32 v[20:21], v[20:21], 1.0 op_sel_hi:[1,0]
	v_pk_add_f32 v[22:23], v[22:23], 1.0 op_sel_hi:[1,0]
	v_rcp_f32_e32 v20, v20
	v_rcp_f32_e32 v21, v21
	v_rcp_f32_e32 v22, v22
	v_rcp_f32_e32 v23, v23
	s_nop 0
	v_pk_mul_f32 v[4:5], v[4:5], v[20:21]
	v_pk_mul_f32 v[6:7], v[6:7], v[22:23]
	v_pk_mul_f32 v[4:5], v[8:9], v[4:5]
	v_pk_mul_f32 v[6:7], v[10:11], v[6:7]
	v_cvt_pk_bf16_f32 v20, v4, v5
	v_cvt_pk_bf16_f32 v21, v6, v7
	global_store_dwordx2 v[2:3], v[20:21], off
	v_lshl_add_u64 v[2:3], v[2:3], 0, s[98:99]
	s_waitcnt lgkmcnt(0)
	v_pk_mul_f32 v[12:13], v[12:13], v[164:165] op_sel_hi:[1,0]
	v_pk_mul_f32 v[14:15], v[14:15], v[164:165] op_sel_hi:[1,0]
	v_mul_f32_e32 v20, 0xbfb8aa3b, v12
	v_mul_f32_e32 v21, 0xbfb8aa3b, v13
	v_mul_f32_e32 v22, 0xbfb8aa3b, v14
	v_mul_f32_e32 v23, 0xbfb8aa3b, v15
	v_exp_f32_e32 v20, v20
	v_exp_f32_e32 v21, v21
	v_exp_f32_e32 v22, v22
	v_exp_f32_e32 v23, v23
	v_pk_mul_f32 v[16:17], v[16:17], v[164:165] op_sel_hi:[1,0]
	v_pk_mul_f32 v[18:19], v[18:19], v[164:165] op_sel_hi:[1,0]
	v_pk_add_f32 v[20:21], v[20:21], 1.0 op_sel_hi:[1,0]
	v_pk_add_f32 v[22:23], v[22:23], 1.0 op_sel_hi:[1,0]
	v_rcp_f32_e32 v20, v20
	v_rcp_f32_e32 v21, v21
	v_rcp_f32_e32 v22, v22
	v_rcp_f32_e32 v23, v23
	s_nop 0
	v_pk_mul_f32 v[12:13], v[12:13], v[20:21]
	v_pk_mul_f32 v[14:15], v[14:15], v[22:23]
	v_pk_mul_f32 v[12:13], v[16:17], v[12:13]
	v_pk_mul_f32 v[14:15], v[18:19], v[14:15]
	v_cvt_pk_bf16_f32 v20, v12, v13
	v_cvt_pk_bf16_f32 v21, v14, v15
	global_store_dwordx2 v[2:3], v[20:21], off
	s_barrier

.LBB0_242:
	s_or_b64 exec, exec, s[42:43]
	s_movk_i32 s42, 0x410
	v_lshrrev_b32_e32 v130, 2, v142
	v_lshlrev_b32_e32 v131, 1, v142
	v_and_b32_e32 v0, 15, v142
	v_and_b32_e32 v130, 0xfffffcc, v130
	v_and_b32_e32 v131, 0x180, v131
	v_add_u32_e32 v131, 0, v131
	v_lshlrev_b32_e32 v0, 2, v0
	v_mul_lo_u32 v130, v130, s42
	v_add3_u32 v130, v131, v0, v130
	s_waitcnt vmcnt(0)
	s_barrier
	ds_write2_b32 v130, v114, v126 offset1:16
	v_add_u32_e32 v114, 0x400, v130
	ds_write2_b32 v114, v115, v127 offset0:4 offset1:20
	v_add_u32_e32 v115, 0x800, v130
	ds_write2_b32 v115, v116, v128 offset0:8 offset1:24
	v_add_u32_e32 v116, 0xc00, v130
	ds_write2_b32 v116, v117, v129 offset0:12 offset1:28
	v_add_u32_e32 v117, 0x4000, v130
	ds_write2_b32 v117, v82, v94 offset0:64 offset1:80
	v_add_u32_e32 v94, 0x4400, v130
	ds_write2_b32 v94, v83, v95 offset0:68 offset1:84
	v_add_u32_e32 v95, 0x4800, v130
	ds_write2_b32 v95, v84, v96 offset0:72 offset1:88
	v_add_u32_e32 v96, 0x4c00, v130
	v_add_u32_e32 v133, 0xc000, v130
	ds_write2_b32 v96, v85, v97 offset0:76 offset1:92
	v_add_u32_e32 v132, 0x8000, v130
	v_add_u32_e32 v97, 0x8400, v130
	v_add_u32_e32 v126, 0x8800, v130
	v_add_u32_e32 v127, 0x8c00, v130
	ds_write2_b32 v133, v66, v70 offset0:192 offset1:208
	v_add_u32_e32 v128, 0xc400, v130
	v_add_u32_e32 v129, 0xc800, v130
	v_add_u32_e32 v131, 0xcc00, v130
	v_lshlrev_b32_e32 v0, 3, v142
	v_lshlrev_b32_e32 v66, 2, v142
	ds_write2_b32 v132, v74, v78 offset0:128 offset1:144
	ds_write2_b32 v97, v75, v79 offset0:132 offset1:148
	ds_write2_b32 v126, v76, v80 offset0:136 offset1:152
	ds_write2_b32 v127, v77, v81 offset0:140 offset1:156
	ds_write2_b32 v128, v67, v71 offset0:196 offset1:212
	ds_write2_b32 v129, v68, v72 offset0:200 offset1:216
	ds_write2_b32 v131, v69, v73 offset0:204 offset1:220
	ds_write2_b32 v130, v98, v118 offset0:128 offset1:144
	ds_write2_b32 v114, v99, v119 offset0:132 offset1:148
	ds_write2_b32 v115, v100, v120 offset0:136 offset1:152
	ds_write2_b32 v116, v101, v121 offset0:140 offset1:156
	ds_write2_b32 v117, v102, v122 offset0:192 offset1:208
	ds_write2_b32 v94, v103, v123 offset0:196 offset1:212
	ds_write2_b32 v95, v104, v124 offset0:200 offset1:216
	ds_write2_b32 v96, v105, v125 offset0:204 offset1:220
	ds_write2_b32 v97, v90, v110 offset1:16
	ds_write2_b32 v126, v91, v111 offset0:4 offset1:20
	ds_write2_b32 v127, v92, v112 offset0:8 offset1:24
	v_add_u32_e32 v90, 0x9000, v130
	v_and_b32_e32 v0, 0xe0, v0
	v_and_b32_e32 v68, 12, v66
	ds_write2_b32 v90, v93, v113 offset0:12 offset1:28
	ds_write2_b32 v128, v86, v106 offset0:64 offset1:80
	ds_write2_b32 v129, v87, v107 offset0:68 offset1:84
	ds_write2_b32 v131, v88, v108 offset0:72 offset1:88
	v_lshlrev_b32_e32 v66, 2, v0
	v_lshlrev_b32_e32 v67, 2, v68
	v_or_b32_e32 v0, s38, v0
	v_ashrrev_i32_e32 v88, 5, v142
	v_add3_u32 v74, 0, v66, v67
	v_ashrrev_i32_e32 v66, 1, v0
	v_lshlrev_b32_e32 v0, 1, v68
	v_add_u32_e32 v68, s10, v88
	v_ashrrev_i32_e32 v69, 31, v68
	v_add_u32_e32 v91, 0xd000, v130
	v_lshl_add_u64 v[70:71], v[68:69], 4, s[46:47]
	ds_write2_b32 v91, v89, v109 offset0:76 offset1:92
	s_waitcnt lgkmcnt(0)
	s_barrier
	global_load_dwordx4 v[134:137], v[70:71], off
	global_load_dwordx4 v[138:141], v[70:71], off offset:256
	global_load_dwordx4 v[144:147], v[70:71], off offset:512
	global_load_dwordx4 v[148:151], v[70:71], off offset:768
	global_load_dwordx4 v[152:155], v[70:71], off offset:1024
	global_load_dwordx4 v[156:159], v[70:71], off offset:1280
	global_load_dwordx4 v[160:163], v[70:71], off offset:1536
	global_load_dwordx4 v[164:167], v[70:71], off offset:1792
	v_readlane_b32 s16, v253, 58
	v_ashrrev_i32_e32 v67, 31, v66
	v_readlane_b32 s17, v253, 59
	s_mov_b32 s33, 0x800000
	v_mad_u64_u32 v[82:83], s[36:37], v88, s42, v[74:75]
	v_lshl_add_u64 v[66:67], v[66:67], 1, s[16:17]
	v_lshl_add_u64 v[66:67], v[66:67], 0, v[0:1]
	s_movk_i32 s39, 0x1600
	v_readlane_b32 s16, v255, 10
	v_readlane_b32 s17, v255, 11
	s_waitcnt vmcnt(0)
	v_mad_i64_i32 v[68:69], s[36:37], v68, s39, v[66:67]
	ds_read_b128 v[70:73], v82
	ds_read_b128 v[74:77], v82 offset:64
	v_add_u32_e32 v0, 0x10400, v82
	s_lshl_b32 s98, s39, 4
	s_mov_b32 s99, 0
	v_add_f32_e32 v134, v134, v135
	v_add_f32_e32 v134, v134, v136
	v_add_f32_e32 v134, v134, v137
	v_fmamk_f32 v134, v134, 0x3a800000, v200
	v_rsq_f32_e32 v134, v134
	v_add_f32_e32 v138, v138, v139
	v_add_f32_e32 v138, v138, v140
	v_add_f32_e32 v138, v138, v141
	v_fmamk_f32 v138, v138, 0x3a800000, v200
	v_rsq_f32_e32 v138, v138
	v_add_f32_e32 v144, v144, v145
	v_add_f32_e32 v144, v144, v146
	v_add_f32_e32 v144, v144, v147
	v_fmamk_f32 v144, v144, 0x3a800000, v200
	v_rsq_f32_e32 v144, v144
	v_add_f32_e32 v148, v148, v149
	v_add_f32_e32 v148, v148, v150
	v_add_f32_e32 v148, v148, v151
	v_fmamk_f32 v148, v148, 0x3a800000, v200
	v_rsq_f32_e32 v148, v148
	v_add_f32_e32 v152, v152, v153
	v_add_f32_e32 v152, v152, v154
	v_add_f32_e32 v152, v152, v155
	v_fmamk_f32 v152, v152, 0x3a800000, v200
	v_rsq_f32_e32 v152, v152
	v_add_f32_e32 v156, v156, v157
	v_add_f32_e32 v156, v156, v158
	v_add_f32_e32 v156, v156, v159
	v_fmamk_f32 v156, v156, 0x3a800000, v200
	v_rsq_f32_e32 v156, v156
	v_add_f32_e32 v160, v160, v161
	v_add_f32_e32 v160, v160, v162
	v_add_f32_e32 v160, v160, v163
	v_fmamk_f32 v160, v160, 0x3a800000, v200
	v_rsq_f32_e32 v160, v160
	v_add_f32_e32 v164, v164, v165
	v_add_f32_e32 v164, v164, v166
	v_add_f32_e32 v164, v164, v167
	v_fmamk_f32 v164, v164, 0x3a800000, v200
	v_rsq_f32_e32 v164, v164
	ds_read_b128 v[78:81], v82 offset:16640
	ds_read_b128 v[84:87], v82 offset:16704
	s_waitcnt lgkmcnt(2)
	v_pk_mul_f32 v[70:71], v[70:71], v[134:135] op_sel_hi:[1,0]
	v_pk_mul_f32 v[72:73], v[72:73], v[134:135] op_sel_hi:[1,0]
	v_mul_f32_e32 v98, 0xbfb8aa3b, v70
	v_mul_f32_e32 v99, 0xbfb8aa3b, v71
	v_mul_f32_e32 v100, 0xbfb8aa3b, v72
	v_mul_f32_e32 v101, 0xbfb8aa3b, v73
	v_exp_f32_e32 v98, v98
	v_exp_f32_e32 v99, v99
	v_exp_f32_e32 v100, v100
	v_exp_f32_e32 v101, v101
	v_pk_mul_f32 v[74:75], v[74:75], v[134:135] op_sel_hi:[1,0]
	v_pk_mul_f32 v[76:77], v[76:77], v[134:135] op_sel_hi:[1,0]
	v_pk_add_f32 v[98:99], v[98:99], 1.0 op_sel_hi:[1,0]
	v_pk_add_f32 v[100:101], v[100:101], 1.0 op_sel_hi:[1,0]
	v_rcp_f32_e32 v98, v98
	v_rcp_f32_e32 v99, v99
	v_rcp_f32_e32 v100, v100
	v_rcp_f32_e32 v101, v101
	s_nop 0
	v_pk_mul_f32 v[70:71], v[70:71], v[98:99]
	v_pk_mul_f32 v[72:73], v[72:73], v[100:101]
	v_pk_mul_f32 v[70:71], v[74:75], v[70:71]
	v_pk_mul_f32 v[72:73], v[76:77], v[72:73]
	v_cvt_pk_bf16_f32 v98, v70, v71
	v_cvt_pk_bf16_f32 v99, v72, v73
	global_store_dwordx2 v[68:69], v[98:99], off
	v_lshl_add_u64 v[68:69], v[68:69], 0, s[98:99]
	ds_read_b128 v[70:73], v82 offset:33280
	ds_read_b128 v[74:77], v82 offset:33344
	s_waitcnt lgkmcnt(2)
	v_pk_mul_f32 v[78:79], v[78:79], v[138:139] op_sel_hi:[1,0]
	v_pk_mul_f32 v[80:81], v[80:81], v[138:139] op_sel_hi:[1,0]
	v_mul_f32_e32 v98, 0xbfb8aa3b, v78
	v_mul_f32_e32 v99, 0xbfb8aa3b, v79
	v_mul_f32_e32 v100, 0xbfb8aa3b, v80
	v_mul_f32_e32 v101, 0xbfb8aa3b, v81
	v_exp_f32_e32 v98, v98
	v_exp_f32_e32 v99, v99
	v_exp_f32_e32 v100, v100
	v_exp_f32_e32 v101, v101
	v_pk_mul_f32 v[84:85], v[84:85], v[138:139] op_sel_hi:[1,0]
	v_pk_mul_f32 v[86:87], v[86:87], v[138:139] op_sel_hi:[1,0]
	v_pk_add_f32 v[98:99], v[98:99], 1.0 op_sel_hi:[1,0]
	v_pk_add_f32 v[100:101], v[100:101], 1.0 op_sel_hi:[1,0]
	v_rcp_f32_e32 v98, v98
	v_rcp_f32_e32 v99, v99
	v_rcp_f32_e32 v100, v100
	v_rcp_f32_e32 v101, v101
	s_nop 0
	v_pk_mul_f32 v[78:79], v[78:79], v[98:99]
	v_pk_mul_f32 v[80:81], v[80:81], v[100:101]
	v_pk_mul_f32 v[78:79], v[84:85], v[78:79]
	v_pk_mul_f32 v[80:81], v[86:87], v[80:81]
	v_cvt_pk_bf16_f32 v98, v78, v79
	v_cvt_pk_bf16_f32 v99, v80, v81
	global_store_dwordx2 v[68:69], v[98:99], off
	v_lshl_add_u64 v[68:69], v[68:69], 0, s[98:99]
	ds_read_b128 v[78:81], v82 offset:49920
	ds_read_b128 v[84:87], v82 offset:49984
	s_waitcnt lgkmcnt(2)
	v_pk_mul_f32 v[70:71], v[70:71], v[144:145] op_sel_hi:[1,0]
	v_pk_mul_f32 v[72:73], v[72:73], v[144:145] op_sel_hi:[1,0]
	v_mul_f32_e32 v98, 0xbfb8aa3b, v70
	v_mul_f32_e32 v99, 0xbfb8aa3b, v71
	v_mul_f32_e32 v100, 0xbfb8aa3b, v72
	v_mul_f32_e32 v101, 0xbfb8aa3b, v73
	v_exp_f32_e32 v98, v98
	v_exp_f32_e32 v99, v99
	v_exp_f32_e32 v100, v100
	v_exp_f32_e32 v101, v101
	v_pk_mul_f32 v[74:75], v[74:75], v[144:145] op_sel_hi:[1,0]
	v_pk_mul_f32 v[76:77], v[76:77], v[144:145] op_sel_hi:[1,0]
	v_pk_add_f32 v[98:99], v[98:99], 1.0 op_sel_hi:[1,0]
	v_pk_add_f32 v[100:101], v[100:101], 1.0 op_sel_hi:[1,0]
	v_rcp_f32_e32 v98, v98
	v_rcp_f32_e32 v99, v99
	v_rcp_f32_e32 v100, v100
	v_rcp_f32_e32 v101, v101
	s_nop 0
	v_pk_mul_f32 v[70:71], v[70:71], v[98:99]
	v_pk_mul_f32 v[72:73], v[72:73], v[100:101]
	v_pk_mul_f32 v[70:71], v[74:75], v[70:71]
	v_pk_mul_f32 v[72:73], v[76:77], v[72:73]
	v_cvt_pk_bf16_f32 v98, v70, v71
	v_cvt_pk_bf16_f32 v99, v72, v73
	global_store_dwordx2 v[68:69], v[98:99], off
	v_lshl_add_u64 v[68:69], v[68:69], 0, s[98:99]
	ds_read_b128 v[70:73], v0
	ds_read_b128 v[74:77], v0 offset:64
	s_waitcnt lgkmcnt(2)
	v_pk_mul_f32 v[78:79], v[78:79], v[148:149] op_sel_hi:[1,0]
	v_pk_mul_f32 v[80:81], v[80:81], v[148:149] op_sel_hi:[1,0]
	v_mul_f32_e32 v98, 0xbfb8aa3b, v78
	v_mul_f32_e32 v99, 0xbfb8aa3b, v79
	v_mul_f32_e32 v100, 0xbfb8aa3b, v80
	v_mul_f32_e32 v101, 0xbfb8aa3b, v81
	v_exp_f32_e32 v98, v98
	v_exp_f32_e32 v99, v99
	v_exp_f32_e32 v100, v100
	v_exp_f32_e32 v101, v101
	v_pk_mul_f32 v[84:85], v[84:85], v[148:149] op_sel_hi:[1,0]
	v_pk_mul_f32 v[86:87], v[86:87], v[148:149] op_sel_hi:[1,0]
	v_pk_add_f32 v[98:99], v[98:99], 1.0 op_sel_hi:[1,0]
	v_pk_add_f32 v[100:101], v[100:101], 1.0 op_sel_hi:[1,0]
	v_rcp_f32_e32 v98, v98
	v_rcp_f32_e32 v99, v99
	v_rcp_f32_e32 v100, v100
	v_rcp_f32_e32 v101, v101
	s_nop 0
	v_pk_mul_f32 v[78:79], v[78:79], v[98:99]
	v_pk_mul_f32 v[80:81], v[80:81], v[100:101]
	v_pk_mul_f32 v[78:79], v[84:85], v[78:79]
	v_pk_mul_f32 v[80:81], v[86:87], v[80:81]
	v_cvt_pk_bf16_f32 v98, v78, v79
	v_cvt_pk_bf16_f32 v99, v80, v81
	global_store_dwordx2 v[68:69], v[98:99], off
	v_lshl_add_u64 v[68:69], v[68:69], 0, s[98:99]
	ds_read_b128 v[78:81], v0 offset:16640
	ds_read_b128 v[84:87], v0 offset:16704
	s_waitcnt lgkmcnt(2)
	v_pk_mul_f32 v[70:71], v[70:71], v[152:153] op_sel_hi:[1,0]
	v_pk_mul_f32 v[72:73], v[72:73], v[152:153] op_sel_hi:[1,0]
	v_mul_f32_e32 v98, 0xbfb8aa3b, v70
	v_mul_f32_e32 v99, 0xbfb8aa3b, v71
	v_mul_f32_e32 v100, 0xbfb8aa3b, v72
	v_mul_f32_e32 v101, 0xbfb8aa3b, v73
	v_exp_f32_e32 v98, v98
	v_exp_f32_e32 v99, v99
	v_exp_f32_e32 v100, v100
	v_exp_f32_e32 v101, v101
	v_pk_mul_f32 v[74:75], v[74:75], v[152:153] op_sel_hi:[1,0]
	v_pk_mul_f32 v[76:77], v[76:77], v[152:153] op_sel_hi:[1,0]
	v_pk_add_f32 v[98:99], v[98:99], 1.0 op_sel_hi:[1,0]
	v_pk_add_f32 v[100:101], v[100:101], 1.0 op_sel_hi:[1,0]
	v_rcp_f32_e32 v98, v98
	v_rcp_f32_e32 v99, v99
	v_rcp_f32_e32 v100, v100
	v_rcp_f32_e32 v101, v101
	s_nop 0
	v_pk_mul_f32 v[70:71], v[70:71], v[98:99]
	v_pk_mul_f32 v[72:73], v[72:73], v[100:101]
	v_pk_mul_f32 v[70:71], v[74:75], v[70:71]
	v_pk_mul_f32 v[72:73], v[76:77], v[72:73]
	v_cvt_pk_bf16_f32 v98, v70, v71
	v_cvt_pk_bf16_f32 v99, v72, v73
	global_store_dwordx2 v[68:69], v[98:99], off
	v_lshl_add_u64 v[68:69], v[68:69], 0, s[98:99]
	ds_read_b128 v[70:73], v0 offset:33280
	ds_read_b128 v[74:77], v0 offset:33344
	s_waitcnt lgkmcnt(2)
	v_pk_mul_f32 v[78:79], v[78:79], v[156:157] op_sel_hi:[1,0]
	v_pk_mul_f32 v[80:81], v[80:81], v[156:157] op_sel_hi:[1,0]
	v_mul_f32_e32 v98, 0xbfb8aa3b, v78
	v_mul_f32_e32 v99, 0xbfb8aa3b, v79
	v_mul_f32_e32 v100, 0xbfb8aa3b, v80
	v_mul_f32_e32 v101, 0xbfb8aa3b, v81
	v_exp_f32_e32 v98, v98
	v_exp_f32_e32 v99, v99
	v_exp_f32_e32 v100, v100
	v_exp_f32_e32 v101, v101
	v_pk_mul_f32 v[84:85], v[84:85], v[156:157] op_sel_hi:[1,0]
	v_pk_mul_f32 v[86:87], v[86:87], v[156:157] op_sel_hi:[1,0]
	v_pk_add_f32 v[98:99], v[98:99], 1.0 op_sel_hi:[1,0]
	v_pk_add_f32 v[100:101], v[100:101], 1.0 op_sel_hi:[1,0]
	v_rcp_f32_e32 v98, v98
	v_rcp_f32_e32 v99, v99
	v_rcp_f32_e32 v100, v100
	v_rcp_f32_e32 v101, v101
	s_nop 0
	v_pk_mul_f32 v[78:79], v[78:79], v[98:99]
	v_pk_mul_f32 v[80:81], v[80:81], v[100:101]
	v_pk_mul_f32 v[78:79], v[84:85], v[78:79]
	v_pk_mul_f32 v[80:81], v[86:87], v[80:81]
	v_cvt_pk_bf16_f32 v98, v78, v79
	v_cvt_pk_bf16_f32 v99, v80, v81
	global_store_dwordx2 v[68:69], v[98:99], off
	v_lshl_add_u64 v[68:69], v[68:69], 0, s[98:99]
	ds_read_b128 v[78:81], v0 offset:49920
	ds_read_b128 v[84:87], v0 offset:49984
	s_waitcnt lgkmcnt(2)
	v_pk_mul_f32 v[70:71], v[70:71], v[160:161] op_sel_hi:[1,0]
	v_pk_mul_f32 v[72:73], v[72:73], v[160:161] op_sel_hi:[1,0]
	v_mul_f32_e32 v98, 0xbfb8aa3b, v70
	v_mul_f32_e32 v99, 0xbfb8aa3b, v71
	v_mul_f32_e32 v100, 0xbfb8aa3b, v72
	v_mul_f32_e32 v101, 0xbfb8aa3b, v73
	v_exp_f32_e32 v98, v98
	v_exp_f32_e32 v99, v99
	v_exp_f32_e32 v100, v100
	v_exp_f32_e32 v101, v101
	v_pk_mul_f32 v[74:75], v[74:75], v[160:161] op_sel_hi:[1,0]
	v_pk_mul_f32 v[76:77], v[76:77], v[160:161] op_sel_hi:[1,0]
	v_pk_add_f32 v[98:99], v[98:99], 1.0 op_sel_hi:[1,0]
	v_pk_add_f32 v[100:101], v[100:101], 1.0 op_sel_hi:[1,0]
	v_rcp_f32_e32 v98, v98
	v_rcp_f32_e32 v99, v99
	v_rcp_f32_e32 v100, v100
	v_rcp_f32_e32 v101, v101
	s_nop 0
	v_pk_mul_f32 v[70:71], v[70:71], v[98:99]
	v_pk_mul_f32 v[72:73], v[72:73], v[100:101]
	v_pk_mul_f32 v[70:71], v[74:75], v[70:71]
	v_pk_mul_f32 v[72:73], v[76:77], v[72:73]
	v_cvt_pk_bf16_f32 v98, v70, v71
	v_cvt_pk_bf16_f32 v99, v72, v73
	global_store_dwordx2 v[68:69], v[98:99], off
	v_lshl_add_u64 v[68:69], v[68:69], 0, s[98:99]
	s_waitcnt lgkmcnt(0)
	v_pk_mul_f32 v[78:79], v[78:79], v[164:165] op_sel_hi:[1,0]
	v_pk_mul_f32 v[80:81], v[80:81], v[164:165] op_sel_hi:[1,0]
	v_mul_f32_e32 v98, 0xbfb8aa3b, v78
	v_mul_f32_e32 v99, 0xbfb8aa3b, v79
	v_mul_f32_e32 v100, 0xbfb8aa3b, v80
	v_mul_f32_e32 v101, 0xbfb8aa3b, v81
	v_exp_f32_e32 v98, v98
	v_exp_f32_e32 v99, v99
	v_exp_f32_e32 v100, v100
	v_exp_f32_e32 v101, v101
	v_pk_mul_f32 v[84:85], v[84:85], v[164:165] op_sel_hi:[1,0]
	v_pk_mul_f32 v[86:87], v[86:87], v[164:165] op_sel_hi:[1,0]
	v_pk_add_f32 v[98:99], v[98:99], 1.0 op_sel_hi:[1,0]
	v_pk_add_f32 v[100:101], v[100:101], 1.0 op_sel_hi:[1,0]
	v_rcp_f32_e32 v98, v98
	v_rcp_f32_e32 v99, v99
	v_rcp_f32_e32 v100, v100
	v_rcp_f32_e32 v101, v101
	s_nop 0
	v_pk_mul_f32 v[78:79], v[78:79], v[98:99]
	v_pk_mul_f32 v[80:81], v[80:81], v[100:101]
	v_pk_mul_f32 v[78:79], v[84:85], v[78:79]
	v_pk_mul_f32 v[80:81], v[86:87], v[80:81]
	v_cvt_pk_bf16_f32 v98, v78, v79
	v_cvt_pk_bf16_f32 v99, v80, v81
	global_store_dwordx2 v[68:69], v[98:99], off
	v_mov_b32_e32 v142, v201
	s_or_b32 s42, s38, 0x100
	s_ashr_i32 s43, s42, 31
	s_lshl_b64 s[70:71], s[42:43], 11
	s_barrier
	ds_write2_b32 v130, v2, v18 offset1:16
	ds_write2_b32 v114, v3, v19 offset0:4 offset1:20
	ds_write2_b32 v115, v4, v20 offset0:8 offset1:24
	ds_write2_b32 v116, v5, v21 offset0:12 offset1:28
	ds_write2_b32 v117, v6, v22 offset0:64 offset1:80
	ds_write2_b32 v94, v7, v23 offset0:68 offset1:84
	ds_write2_b32 v95, v8, v24 offset0:72 offset1:88
	ds_write2_b32 v96, v9, v25 offset0:76 offset1:92
	ds_write2_b32 v132, v10, v26 offset0:128 offset1:144
	ds_write2_b32 v97, v11, v27 offset0:132 offset1:148
	ds_write2_b32 v126, v12, v28 offset0:136 offset1:152
	ds_write2_b32 v127, v13, v29 offset0:140 offset1:156
	ds_write2_b32 v133, v14, v30 offset0:192 offset1:208
	ds_write2_b32 v128, v15, v31 offset0:196 offset1:212
	ds_write2_b32 v129, v16, v32 offset0:200 offset1:216
	ds_write2_b32 v131, v17, v33 offset0:204 offset1:220
	ds_write2_b32 v130, v34, v50 offset0:128 offset1:144
	ds_write2_b32 v114, v35, v51 offset0:132 offset1:148
	ds_write2_b32 v115, v36, v52 offset0:136 offset1:152
	ds_write2_b32 v116, v37, v53 offset0:140 offset1:156
	ds_write2_b32 v117, v38, v54 offset0:192 offset1:208
	ds_write2_b32 v94, v39, v55 offset0:196 offset1:212
	ds_write2_b32 v95, v40, v56 offset0:200 offset1:216
	ds_write2_b32 v96, v41, v57 offset0:204 offset1:220
	ds_write2_b32 v97, v42, v58 offset1:16
	ds_write2_b32 v126, v43, v59 offset0:4 offset1:20
	ds_write2_b32 v127, v44, v60 offset0:8 offset1:24
	ds_write2_b32 v90, v45, v61 offset0:12 offset1:28
	ds_write2_b32 v128, v46, v62 offset0:64 offset1:80
	ds_write2_b32 v129, v47, v63 offset0:68 offset1:84
	ds_write2_b32 v131, v48, v64 offset0:72 offset1:88
	ds_write2_b32 v91, v49, v65 offset0:76 offset1:92
	v_add_u32_e32 v2, s8, v88
	v_ashrrev_i32_e32 v3, 31, v2
	v_lshl_add_u64 v[4:5], v[2:3], 4, s[46:47]
	s_waitcnt lgkmcnt(0)
	s_barrier
	global_load_dwordx4 v[134:137], v[4:5], off
	global_load_dwordx4 v[138:141], v[4:5], off offset:256
	global_load_dwordx4 v[144:147], v[4:5], off offset:512
	global_load_dwordx4 v[148:151], v[4:5], off offset:768
	global_load_dwordx4 v[152:155], v[4:5], off offset:1024
	global_load_dwordx4 v[156:159], v[4:5], off offset:1280
	global_load_dwordx4 v[160:163], v[4:5], off offset:1536
	global_load_dwordx4 v[164:167], v[4:5], off offset:1792
	s_waitcnt vmcnt(0)
	v_mad_i64_i32 v[2:3], s[36:37], v2, s39, v[66:67]
	ds_read_b128 v[4:7], v82
	ds_read_b128 v[8:11], v82 offset:64
	v_add_u32_e32 v0, 0x10400, v82
	s_lshl_b32 s98, s39, 4
	s_mov_b32 s99, 0
	v_add_f32_e32 v134, v134, v135
	v_add_f32_e32 v134, v134, v136
	v_add_f32_e32 v134, v134, v137
	v_fmamk_f32 v134, v134, 0x3a800000, v200
	v_rsq_f32_e32 v134, v134
	v_add_f32_e32 v138, v138, v139
	v_add_f32_e32 v138, v138, v140
	v_add_f32_e32 v138, v138, v141
	v_fmamk_f32 v138, v138, 0x3a800000, v200
	v_rsq_f32_e32 v138, v138
	v_add_f32_e32 v144, v144, v145
	v_add_f32_e32 v144, v144, v146
	v_add_f32_e32 v144, v144, v147
	v_fmamk_f32 v144, v144, 0x3a800000, v200
	v_rsq_f32_e32 v144, v144
	v_add_f32_e32 v148, v148, v149
	v_add_f32_e32 v148, v148, v150
	v_add_f32_e32 v148, v148, v151
	v_fmamk_f32 v148, v148, 0x3a800000, v200
	v_rsq_f32_e32 v148, v148
	v_add_f32_e32 v152, v152, v153
	v_add_f32_e32 v152, v152, v154
	v_add_f32_e32 v152, v152, v155
	v_fmamk_f32 v152, v152, 0x3a800000, v200
	v_rsq_f32_e32 v152, v152
	v_add_f32_e32 v156, v156, v157
	v_add_f32_e32 v156, v156, v158
	v_add_f32_e32 v156, v156, v159
	v_fmamk_f32 v156, v156, 0x3a800000, v200
	v_rsq_f32_e32 v156, v156
	v_add_f32_e32 v160, v160, v161
	v_add_f32_e32 v160, v160, v162
	v_add_f32_e32 v160, v160, v163
	v_fmamk_f32 v160, v160, 0x3a800000, v200
	v_rsq_f32_e32 v160, v160
	v_add_f32_e32 v164, v164, v165
	v_add_f32_e32 v164, v164, v166
	v_add_f32_e32 v164, v164, v167
	v_fmamk_f32 v164, v164, 0x3a800000, v200
	v_rsq_f32_e32 v164, v164
	ds_read_b128 v[12:15], v82 offset:16640
	ds_read_b128 v[16:19], v82 offset:16704
	s_waitcnt lgkmcnt(2)
	v_pk_mul_f32 v[4:5], v[4:5], v[134:135] op_sel_hi:[1,0]
	v_pk_mul_f32 v[6:7], v[6:7], v[134:135] op_sel_hi:[1,0]
	v_mul_f32_e32 v20, 0xbfb8aa3b, v4
	v_mul_f32_e32 v21, 0xbfb8aa3b, v5
	v_mul_f32_e32 v22, 0xbfb8aa3b, v6
	v_mul_f32_e32 v23, 0xbfb8aa3b, v7
	v_exp_f32_e32 v20, v20
	v_exp_f32_e32 v21, v21
	v_exp_f32_e32 v22, v22
	v_exp_f32_e32 v23, v23
	v_pk_mul_f32 v[8:9], v[8:9], v[134:135] op_sel_hi:[1,0]
	v_pk_mul_f32 v[10:11], v[10:11], v[134:135] op_sel_hi:[1,0]
	v_pk_add_f32 v[20:21], v[20:21], 1.0 op_sel_hi:[1,0]
	v_pk_add_f32 v[22:23], v[22:23], 1.0 op_sel_hi:[1,0]
	v_rcp_f32_e32 v20, v20
	v_rcp_f32_e32 v21, v21
	v_rcp_f32_e32 v22, v22
	v_rcp_f32_e32 v23, v23
	s_nop 0
	v_pk_mul_f32 v[4:5], v[4:5], v[20:21]
	v_pk_mul_f32 v[6:7], v[6:7], v[22:23]
	v_pk_mul_f32 v[4:5], v[8:9], v[4:5]
	v_pk_mul_f32 v[6:7], v[10:11], v[6:7]
	v_cvt_pk_bf16_f32 v20, v4, v5
	v_cvt_pk_bf16_f32 v21, v6, v7
	global_store_dwordx2 v[2:3], v[20:21], off
	v_lshl_add_u64 v[2:3], v[2:3], 0, s[98:99]
	ds_read_b128 v[4:7], v82 offset:33280
	ds_read_b128 v[8:11], v82 offset:33344
	s_waitcnt lgkmcnt(2)
	v_pk_mul_f32 v[12:13], v[12:13], v[138:139] op_sel_hi:[1,0]
	v_pk_mul_f32 v[14:15], v[14:15], v[138:139] op_sel_hi:[1,0]
	v_mul_f32_e32 v20, 0xbfb8aa3b, v12
	v_mul_f32_e32 v21, 0xbfb8aa3b, v13
	v_mul_f32_e32 v22, 0xbfb8aa3b, v14
	v_mul_f32_e32 v23, 0xbfb8aa3b, v15
	v_exp_f32_e32 v20, v20
	v_exp_f32_e32 v21, v21
	v_exp_f32_e32 v22, v22
	v_exp_f32_e32 v23, v23
	v_pk_mul_f32 v[16:17], v[16:17], v[138:139] op_sel_hi:[1,0]
	v_pk_mul_f32 v[18:19], v[18:19], v[138:139] op_sel_hi:[1,0]
	v_pk_add_f32 v[20:21], v[20:21], 1.0 op_sel_hi:[1,0]
	v_pk_add_f32 v[22:23], v[22:23], 1.0 op_sel_hi:[1,0]
	v_rcp_f32_e32 v20, v20
	v_rcp_f32_e32 v21, v21
	v_rcp_f32_e32 v22, v22
	v_rcp_f32_e32 v23, v23
	s_nop 0
	v_pk_mul_f32 v[12:13], v[12:13], v[20:21]
	v_pk_mul_f32 v[14:15], v[14:15], v[22:23]
	v_pk_mul_f32 v[12:13], v[16:17], v[12:13]
	v_pk_mul_f32 v[14:15], v[18:19], v[14:15]
	v_cvt_pk_bf16_f32 v20, v12, v13
	v_cvt_pk_bf16_f32 v21, v14, v15
	global_store_dwordx2 v[2:3], v[20:21], off
	v_lshl_add_u64 v[2:3], v[2:3], 0, s[98:99]
	ds_read_b128 v[12:15], v82 offset:49920
	ds_read_b128 v[16:19], v82 offset:49984
	s_waitcnt lgkmcnt(2)
	v_pk_mul_f32 v[4:5], v[4:5], v[144:145] op_sel_hi:[1,0]
	v_pk_mul_f32 v[6:7], v[6:7], v[144:145] op_sel_hi:[1,0]
	v_mul_f32_e32 v20, 0xbfb8aa3b, v4
	v_mul_f32_e32 v21, 0xbfb8aa3b, v5
	v_mul_f32_e32 v22, 0xbfb8aa3b, v6
	v_mul_f32_e32 v23, 0xbfb8aa3b, v7
	v_exp_f32_e32 v20, v20
	v_exp_f32_e32 v21, v21
	v_exp_f32_e32 v22, v22
	v_exp_f32_e32 v23, v23
	v_pk_mul_f32 v[8:9], v[8:9], v[144:145] op_sel_hi:[1,0]
	v_pk_mul_f32 v[10:11], v[10:11], v[144:145] op_sel_hi:[1,0]
	v_pk_add_f32 v[20:21], v[20:21], 1.0 op_sel_hi:[1,0]
	v_pk_add_f32 v[22:23], v[22:23], 1.0 op_sel_hi:[1,0]
	v_rcp_f32_e32 v20, v20
	v_rcp_f32_e32 v21, v21
	v_rcp_f32_e32 v22, v22
	v_rcp_f32_e32 v23, v23
	s_nop 0
	v_pk_mul_f32 v[4:5], v[4:5], v[20:21]
	v_pk_mul_f32 v[6:7], v[6:7], v[22:23]
	v_pk_mul_f32 v[4:5], v[8:9], v[4:5]
	v_pk_mul_f32 v[6:7], v[10:11], v[6:7]
	v_cvt_pk_bf16_f32 v20, v4, v5
	v_cvt_pk_bf16_f32 v21, v6, v7
	global_store_dwordx2 v[2:3], v[20:21], off
	v_lshl_add_u64 v[2:3], v[2:3], 0, s[98:99]
	ds_read_b128 v[4:7], v0
	ds_read_b128 v[8:11], v0 offset:64
	s_waitcnt lgkmcnt(2)
	v_pk_mul_f32 v[12:13], v[12:13], v[148:149] op_sel_hi:[1,0]
	v_pk_mul_f32 v[14:15], v[14:15], v[148:149] op_sel_hi:[1,0]
	v_mul_f32_e32 v20, 0xbfb8aa3b, v12
	v_mul_f32_e32 v21, 0xbfb8aa3b, v13
	v_mul_f32_e32 v22, 0xbfb8aa3b, v14
	v_mul_f32_e32 v23, 0xbfb8aa3b, v15
	v_exp_f32_e32 v20, v20
	v_exp_f32_e32 v21, v21
	v_exp_f32_e32 v22, v22
	v_exp_f32_e32 v23, v23
	v_pk_mul_f32 v[16:17], v[16:17], v[148:149] op_sel_hi:[1,0]
	v_pk_mul_f32 v[18:19], v[18:19], v[148:149] op_sel_hi:[1,0]
	v_pk_add_f32 v[20:21], v[20:21], 1.0 op_sel_hi:[1,0]
	v_pk_add_f32 v[22:23], v[22:23], 1.0 op_sel_hi:[1,0]
	v_rcp_f32_e32 v20, v20
	v_rcp_f32_e32 v21, v21
	v_rcp_f32_e32 v22, v22
	v_rcp_f32_e32 v23, v23
	s_nop 0
	v_pk_mul_f32 v[12:13], v[12:13], v[20:21]
	v_pk_mul_f32 v[14:15], v[14:15], v[22:23]
	v_pk_mul_f32 v[12:13], v[16:17], v[12:13]
	v_pk_mul_f32 v[14:15], v[18:19], v[14:15]
	v_cvt_pk_bf16_f32 v20, v12, v13
	v_cvt_pk_bf16_f32 v21, v14, v15
	global_store_dwordx2 v[2:3], v[20:21], off
	v_lshl_add_u64 v[2:3], v[2:3], 0, s[98:99]
	ds_read_b128 v[12:15], v0 offset:16640
	ds_read_b128 v[16:19], v0 offset:16704
	s_waitcnt lgkmcnt(2)
	v_pk_mul_f32 v[4:5], v[4:5], v[152:153] op_sel_hi:[1,0]
	v_pk_mul_f32 v[6:7], v[6:7], v[152:153] op_sel_hi:[1,0]
	v_mul_f32_e32 v20, 0xbfb8aa3b, v4
	v_mul_f32_e32 v21, 0xbfb8aa3b, v5
	v_mul_f32_e32 v22, 0xbfb8aa3b, v6
	v_mul_f32_e32 v23, 0xbfb8aa3b, v7
	v_exp_f32_e32 v20, v20
	v_exp_f32_e32 v21, v21
	v_exp_f32_e32 v22, v22
	v_exp_f32_e32 v23, v23
	v_pk_mul_f32 v[8:9], v[8:9], v[152:153] op_sel_hi:[1,0]
	v_pk_mul_f32 v[10:11], v[10:11], v[152:153] op_sel_hi:[1,0]
	v_pk_add_f32 v[20:21], v[20:21], 1.0 op_sel_hi:[1,0]
	v_pk_add_f32 v[22:23], v[22:23], 1.0 op_sel_hi:[1,0]
	v_rcp_f32_e32 v20, v20
	v_rcp_f32_e32 v21, v21
	v_rcp_f32_e32 v22, v22
	v_rcp_f32_e32 v23, v23
	s_nop 0
	v_pk_mul_f32 v[4:5], v[4:5], v[20:21]
	v_pk_mul_f32 v[6:7], v[6:7], v[22:23]
	v_pk_mul_f32 v[4:5], v[8:9], v[4:5]
	v_pk_mul_f32 v[6:7], v[10:11], v[6:7]
	v_cvt_pk_bf16_f32 v20, v4, v5
	v_cvt_pk_bf16_f32 v21, v6, v7
	global_store_dwordx2 v[2:3], v[20:21], off
	v_lshl_add_u64 v[2:3], v[2:3], 0, s[98:99]
	ds_read_b128 v[4:7], v0 offset:33280
	ds_read_b128 v[8:11], v0 offset:33344
	s_waitcnt lgkmcnt(2)
	v_pk_mul_f32 v[12:13], v[12:13], v[156:157] op_sel_hi:[1,0]
	v_pk_mul_f32 v[14:15], v[14:15], v[156:157] op_sel_hi:[1,0]
	v_mul_f32_e32 v20, 0xbfb8aa3b, v12
	v_mul_f32_e32 v21, 0xbfb8aa3b, v13
	v_mul_f32_e32 v22, 0xbfb8aa3b, v14
	v_mul_f32_e32 v23, 0xbfb8aa3b, v15
	v_exp_f32_e32 v20, v20
	v_exp_f32_e32 v21, v21
	v_exp_f32_e32 v22, v22
	v_exp_f32_e32 v23, v23
	v_pk_mul_f32 v[16:17], v[16:17], v[156:157] op_sel_hi:[1,0]
	v_pk_mul_f32 v[18:19], v[18:19], v[156:157] op_sel_hi:[1,0]
	v_pk_add_f32 v[20:21], v[20:21], 1.0 op_sel_hi:[1,0]
	v_pk_add_f32 v[22:23], v[22:23], 1.0 op_sel_hi:[1,0]
	v_rcp_f32_e32 v20, v20
	v_rcp_f32_e32 v21, v21
	v_rcp_f32_e32 v22, v22
	v_rcp_f32_e32 v23, v23
	s_nop 0
	v_pk_mul_f32 v[12:13], v[12:13], v[20:21]
	v_pk_mul_f32 v[14:15], v[14:15], v[22:23]
	v_pk_mul_f32 v[12:13], v[16:17], v[12:13]
	v_pk_mul_f32 v[14:15], v[18:19], v[14:15]
	v_cvt_pk_bf16_f32 v20, v12, v13
	v_cvt_pk_bf16_f32 v21, v14, v15
	global_store_dwordx2 v[2:3], v[20:21], off
	v_lshl_add_u64 v[2:3], v[2:3], 0, s[98:99]
	ds_read_b128 v[12:15], v0 offset:49920
	ds_read_b128 v[16:19], v0 offset:49984
	s_waitcnt lgkmcnt(2)
	v_pk_mul_f32 v[4:5], v[4:5], v[160:161] op_sel_hi:[1,0]
	v_pk_mul_f32 v[6:7], v[6:7], v[160:161] op_sel_hi:[1,0]
	v_mul_f32_e32 v20, 0xbfb8aa3b, v4
	v_mul_f32_e32 v21, 0xbfb8aa3b, v5
	v_mul_f32_e32 v22, 0xbfb8aa3b, v6
	v_mul_f32_e32 v23, 0xbfb8aa3b, v7
	v_exp_f32_e32 v20, v20
	v_exp_f32_e32 v21, v21
	v_exp_f32_e32 v22, v22
	v_exp_f32_e32 v23, v23
	v_pk_mul_f32 v[8:9], v[8:9], v[160:161] op_sel_hi:[1,0]
	v_pk_mul_f32 v[10:11], v[10:11], v[160:161] op_sel_hi:[1,0]
	v_pk_add_f32 v[20:21], v[20:21], 1.0 op_sel_hi:[1,0]
	v_pk_add_f32 v[22:23], v[22:23], 1.0 op_sel_hi:[1,0]
	v_rcp_f32_e32 v20, v20
	v_rcp_f32_e32 v21, v21
	v_rcp_f32_e32 v22, v22
	v_rcp_f32_e32 v23, v23
	s_nop 0
	v_pk_mul_f32 v[4:5], v[4:5], v[20:21]
	v_pk_mul_f32 v[6:7], v[6:7], v[22:23]
	v_pk_mul_f32 v[4:5], v[8:9], v[4:5]
	v_pk_mul_f32 v[6:7], v[10:11], v[6:7]
	v_cvt_pk_bf16_f32 v20, v4, v5
	v_cvt_pk_bf16_f32 v21, v6, v7
	global_store_dwordx2 v[2:3], v[20:21], off
	v_lshl_add_u64 v[2:3], v[2:3], 0, s[98:99]
	s_waitcnt lgkmcnt(0)
	v_pk_mul_f32 v[12:13], v[12:13], v[164:165] op_sel_hi:[1,0]
	v_pk_mul_f32 v[14:15], v[14:15], v[164:165] op_sel_hi:[1,0]
	v_mul_f32_e32 v20, 0xbfb8aa3b, v12
	v_mul_f32_e32 v21, 0xbfb8aa3b, v13
	v_mul_f32_e32 v22, 0xbfb8aa3b, v14
	v_mul_f32_e32 v23, 0xbfb8aa3b, v15
	v_exp_f32_e32 v20, v20
	v_exp_f32_e32 v21, v21
	v_exp_f32_e32 v22, v22
	v_exp_f32_e32 v23, v23
	v_pk_mul_f32 v[16:17], v[16:17], v[164:165] op_sel_hi:[1,0]
	v_pk_mul_f32 v[18:19], v[18:19], v[164:165] op_sel_hi:[1,0]
	v_pk_add_f32 v[20:21], v[20:21], 1.0 op_sel_hi:[1,0]
	v_pk_add_f32 v[22:23], v[22:23], 1.0 op_sel_hi:[1,0]
	v_rcp_f32_e32 v20, v20
	v_rcp_f32_e32 v21, v21
	v_rcp_f32_e32 v22, v22
	v_rcp_f32_e32 v23, v23
	s_nop 0
	v_pk_mul_f32 v[12:13], v[12:13], v[20:21]
	v_pk_mul_f32 v[14:15], v[14:15], v[22:23]
	v_pk_mul_f32 v[12:13], v[16:17], v[12:13]
	v_pk_mul_f32 v[14:15], v[18:19], v[14:15]
	v_cvt_pk_bf16_f32 v20, v12, v13
	v_cvt_pk_bf16_f32 v21, v14, v15
	global_store_dwordx2 v[2:3], v[20:21], off
	s_barrier
	s_nop 0
	v_ashrrev_i32_e32 v0, 31, v142
	v_lshrrev_b32_e32 v0, 26, v0
	v_add_u32_e32 v0, v142, v0
	v_ashrrev_i32_e32 v16, 6, v0
	v_bfe_i32 v0, v142, 27, 1
	v_lshlrev_b32_e32 v2, 4, v142
	v_lshrrev_b32_e32 v0, 22, v0
	v_add_u32_e32 v0, v2, v0
	v_and_b32_e32 v0, 0xfffffc00, v0
	v_sub_u32_e32 v0, v2, v0
	v_lshrrev_b32_e32 v3, 4, v0
	v_bitop3_b32 v3, v3, v0, 32 bitop3:0x6c
	v_ashrrev_i32_e32 v0, 31, v0
	v_lshrrev_b32_e32 v0, 26, v0
	v_add_u32_e32 v0, v3, v0
	v_ashrrev_i32_e32 v18, 6, v0
	v_mul_i32_i24_e32 v5, 64, v18
	v_sub_u32_e32 v3, v3, v5
	v_lshlrev_b32_e32 v4, 3, v16
	v_lshlrev_b32_e32 v0, 5, v16
	v_ashrrev_i16_sdwa v3, v217, sext(v3) dst_sel:DWORD dst_unused:UNUSED_PAD src0_sel:DWORD src1_sel:BYTE_0
	v_and_b32_e32 v4, 0x1ffff0, v4
	v_and_b32_e32 v0, 32, v0
	v_bfe_i32 v19, v3, 0, 16
	v_add_u32_e32 v0, v0, v19
	v_add_lshl_u32 v3, v18, v4, 11
	v_add_u32_e32 v2, 0x2000, v2
	v_lshl_add_u32 v0, v0, 1, v3
	v_ashrrev_i32_e32 v3, 31, v2
	v_lshrrev_b32_e32 v3, 22, v3
	v_add_u32_e32 v3, v2, v3
	v_ashrrev_i32_e32 v21, 10, v3
	v_mul_i32_i24_e32 v3, 0x400, v21
	v_sub_u32_e32 v2, v2, v3
	v_lshrrev_b32_e32 v3, 4, v2
	v_bitop3_b32 v2, v3, v2, 32 bitop3:0x6c
	v_ashrrev_i32_e32 v4, 31, v2
	v_ashrrev_i32_e32 v20, 6, v142
	v_lshrrev_b32_e32 v4, 26, v4
	v_readfirstlane_b32 s33, v20
	v_add_u32_e32 v4, v2, v4
	s_lshl_b32 s73, s33, 10
	v_ashrrev_i32_e32 v22, 6, v4
	v_and_b32_e32 v4, 0xc0, v4
	v_sub_u32_e32 v2, v2, v4
	s_add_u32 s70, s16, s70
	v_lshlrev_b32_e32 v3, 3, v21
	v_lshlrev_b32_e32 v5, 5, v21
	v_ashrrev_i16_sdwa v2, v217, sext(v2) dst_sel:DWORD dst_unused:UNUSED_PAD src0_sel:DWORD src1_sel:BYTE_0
	s_addc_u32 s71, s17, s71
	s_add_i32 s36, s73, 0
	v_and_b32_e32 v3, 0x1ffff0, v3
	v_and_b32_e32 v5, 32, v5
	v_bfe_i32 v23, v2, 0, 16
	s_add_i32 s37, s36, 0x10000
	v_add_u32_e32 v2, v5, v23
	v_add_lshl_u32 v3, v22, v3, 11
	s_mov_b32 m0, s37
	s_add_i32 s43, s36, 0x12000
	s_or_b32 s38, s38, 0x180
	v_lshl_add_u32 v2, v2, 1, v3
	global_load_lds_dwordx4 v0, s[70:71]
	v_mov_b32_e32 v3, v1
	s_mov_b32 m0, s43
	s_ashr_i32 s39, s38, 31
	v_lshl_add_u64 v[4:5], s[70:71], 0, v[0:1]
	v_lshl_add_u64 v[8:9], s[70:71], 0, v[2:3]
	global_load_lds_dwordx4 v2, s[70:71]
	s_mov_b32 m0, s36
	s_add_i32 s70, s36, 0x2000
	s_lshl_b64 s[38:39], s[38:39], 11
	global_load_lds_dwordx4 v0, s[54:55]
	s_mov_b32 m0, s70
	s_add_u32 s38, s16, s38
	v_lshl_add_u64 v[10:11], s[54:55], 0, v[0:1]
	v_lshl_add_u64 v[6:7], s[54:55], 0, v[2:3]
	global_load_lds_dwordx4 v2, s[54:55]
	s_addc_u32 s39, s17, s39
	s_add_i32 s54, s36, 0x14000
	s_mov_b32 m0, s54
	s_add_i32 s55, s36, 0x16000
	global_load_lds_dwordx4 v0, s[38:39]
	s_mov_b32 m0, s55
	s_add_i32 s71, s36, 0x4000
	global_load_lds_dwordx4 v2, s[38:39]
	s_mov_b32 m0, s71
	s_add_i32 s72, s36, 0x6000
	global_load_lds_dwordx4 v0, s[60:61]
	s_mov_b32 m0, s72
	v_ashrrev_i32_e32 v17, 8, v142
	global_load_lds_dwordx4 v2, s[60:61]
	v_lshl_add_u64 v[12:13], s[38:39], 0, v[0:1]
	v_lshl_add_u64 v[14:15], s[38:39], 0, v[2:3]
	v_cmp_eq_u32_e32 vcc, 1, v17
	s_and_saveexec_b64 s[38:39], vcc
	v_readlane_b32 s62, v253, 50
	s_cbranch_execz .LBB0_244
	s_barrier

.LBB0_248:
	s_or_b64 exec, exec, s[12:13]
	s_movk_i32 s11, 0x410
	v_lshrrev_b32_e32 v130, 2, v142
	v_lshlrev_b32_e32 v131, 1, v142
	v_and_b32_e32 v0, 15, v142
	v_and_b32_e32 v130, 0xfffffcc, v130
	v_and_b32_e32 v131, 0x180, v131
	v_add_u32_e32 v131, 0, v131
	v_lshlrev_b32_e32 v0, 2, v0
	v_mul_lo_u32 v130, v130, s11
	v_add3_u32 v130, v131, v0, v130
	s_waitcnt vmcnt(0)
	s_barrier
	ds_write2_b32 v130, v114, v126 offset1:16
	v_add_u32_e32 v114, 0x400, v130
	ds_write2_b32 v114, v115, v127 offset0:4 offset1:20
	v_add_u32_e32 v115, 0x800, v130
	ds_write2_b32 v115, v116, v128 offset0:8 offset1:24
	v_add_u32_e32 v116, 0xc00, v130
	ds_write2_b32 v116, v117, v129 offset0:12 offset1:28
	v_add_u32_e32 v117, 0x4000, v130
	ds_write2_b32 v117, v82, v94 offset0:64 offset1:80
	v_add_u32_e32 v94, 0x4400, v130
	ds_write2_b32 v94, v83, v95 offset0:68 offset1:84
	v_add_u32_e32 v95, 0x4800, v130
	ds_write2_b32 v95, v84, v96 offset0:72 offset1:88
	v_add_u32_e32 v96, 0x4c00, v130
	ds_write2_b32 v96, v85, v97 offset0:76 offset1:92
	v_add_u32_e32 v132, 0x8000, v130
	v_add_u32_e32 v97, 0x8400, v130
	v_add_u32_e32 v126, 0x8800, v130
	v_add_u32_e32 v127, 0x8c00, v130
	v_add_u32_e32 v133, 0xc000, v130
	v_add_u32_e32 v128, 0xc400, v130
	v_add_u32_e32 v129, 0xc800, v130
	v_add_u32_e32 v131, 0xcc00, v130
	ds_write2_b32 v132, v74, v78 offset0:128 offset1:144
	ds_write2_b32 v97, v75, v79 offset0:132 offset1:148
	ds_write2_b32 v126, v76, v80 offset0:136 offset1:152
	ds_write2_b32 v127, v77, v81 offset0:140 offset1:156
	ds_write2_b32 v133, v66, v70 offset0:192 offset1:208
	ds_write2_b32 v128, v67, v71 offset0:196 offset1:212
	ds_write2_b32 v129, v68, v72 offset0:200 offset1:216
	ds_write2_b32 v131, v69, v73 offset0:204 offset1:220
	ds_write2_b32 v130, v98, v118 offset0:128 offset1:144
	ds_write2_b32 v114, v99, v119 offset0:132 offset1:148
	ds_write2_b32 v115, v100, v120 offset0:136 offset1:152
	ds_write2_b32 v116, v101, v121 offset0:140 offset1:156
	ds_write2_b32 v117, v102, v122 offset0:192 offset1:208
	ds_write2_b32 v94, v103, v123 offset0:196 offset1:212
	ds_write2_b32 v95, v104, v124 offset0:200 offset1:216
	ds_write2_b32 v96, v105, v125 offset0:204 offset1:220
	ds_write2_b32 v97, v90, v110 offset1:16
	ds_write2_b32 v126, v91, v111 offset0:4 offset1:20
	ds_write2_b32 v127, v92, v112 offset0:8 offset1:24
	v_add_u32_e32 v90, 0x9000, v130
	ds_write2_b32 v90, v93, v113 offset0:12 offset1:28
	ds_write2_b32 v128, v86, v106 offset0:64 offset1:80
	ds_write2_b32 v129, v87, v107 offset0:68 offset1:84
	ds_write2_b32 v131, v88, v108 offset0:72 offset1:88
	v_ashrrev_i32_e32 v88, 5, v142
	v_add_u32_e32 v70, s10, v88
	v_ashrrev_i32_e32 v71, 31, v70
	v_add_u32_e32 v91, 0xd000, v130
	v_lshl_add_u64 v[72:73], v[70:71], 4, s[46:47]
	ds_write2_b32 v91, v89, v109 offset0:76 offset1:92
	s_waitcnt lgkmcnt(0)
	s_barrier
	global_load_dwordx4 v[134:137], v[72:73], off
	global_load_dwordx4 v[138:141], v[72:73], off offset:256
	global_load_dwordx4 v[144:147], v[72:73], off offset:512
	global_load_dwordx4 v[148:151], v[72:73], off offset:768
	global_load_dwordx4 v[152:155], v[72:73], off offset:1024
	global_load_dwordx4 v[156:159], v[72:73], off offset:1280
	global_load_dwordx4 v[160:163], v[72:73], off offset:1536
	global_load_dwordx4 v[164:167], v[72:73], off offset:1792
	v_lshlrev_b32_e32 v0, 3, v142
	v_lshlrev_b32_e32 v66, 2, v142
	v_and_b32_e32 v0, 0xe0, v0
	v_and_b32_e32 v69, 12, v66
	v_lshlrev_b32_e32 v66, 2, v0
	v_lshlrev_b32_e32 v67, 2, v69
	v_or_b32_e32 v0, s42, v0
	v_add3_u32 v68, 0, v66, v67
	v_ashrrev_i32_e32 v66, 1, v0
	v_readlane_b32 s12, v253, 58
	v_ashrrev_i32_e32 v67, 31, v66
	v_readlane_b32 s13, v253, 59
	v_lshlrev_b32_e32 v0, 1, v69
	s_mov_b32 s9, 0x800000
	v_lshl_add_u64 v[66:67], v[66:67], 1, s[12:13]
	v_lshl_add_u64 v[66:67], v[66:67], 0, v[0:1]
	v_mad_u64_u32 v[82:83], s[12:13], v88, s11, v[68:69]
	s_movk_i32 s14, 0x1600
	s_waitcnt vmcnt(0)
	v_mad_i64_i32 v[70:71], s[12:13], v70, s14, v[66:67]
	ds_read_b128 v[72:75], v82
	ds_read_b128 v[76:79], v82 offset:64
	v_add_u32_e32 v0, 0x10400, v82
	s_lshl_b32 s98, s14, 4
	s_mov_b32 s99, 0
	v_add_f32_e32 v134, v134, v135
	v_add_f32_e32 v134, v134, v136
	v_add_f32_e32 v134, v134, v137
	v_fmamk_f32 v134, v134, 0x3a800000, v200
	v_rsq_f32_e32 v134, v134
	v_add_f32_e32 v138, v138, v139
	v_add_f32_e32 v138, v138, v140
	v_add_f32_e32 v138, v138, v141
	v_fmamk_f32 v138, v138, 0x3a800000, v200
	v_rsq_f32_e32 v138, v138
	v_add_f32_e32 v144, v144, v145
	v_add_f32_e32 v144, v144, v146
	v_add_f32_e32 v144, v144, v147
	v_fmamk_f32 v144, v144, 0x3a800000, v200
	v_rsq_f32_e32 v144, v144
	v_add_f32_e32 v148, v148, v149
	v_add_f32_e32 v148, v148, v150
	v_add_f32_e32 v148, v148, v151
	v_fmamk_f32 v148, v148, 0x3a800000, v200
	v_rsq_f32_e32 v148, v148
	v_add_f32_e32 v152, v152, v153
	v_add_f32_e32 v152, v152, v154
	v_add_f32_e32 v152, v152, v155
	v_fmamk_f32 v152, v152, 0x3a800000, v200
	v_rsq_f32_e32 v152, v152
	v_add_f32_e32 v156, v156, v157
	v_add_f32_e32 v156, v156, v158
	v_add_f32_e32 v156, v156, v159
	v_fmamk_f32 v156, v156, 0x3a800000, v200
	v_rsq_f32_e32 v156, v156
	v_add_f32_e32 v160, v160, v161
	v_add_f32_e32 v160, v160, v162
	v_add_f32_e32 v160, v160, v163
	v_fmamk_f32 v160, v160, 0x3a800000, v200
	v_rsq_f32_e32 v160, v160
	v_add_f32_e32 v164, v164, v165
	v_add_f32_e32 v164, v164, v166
	v_add_f32_e32 v164, v164, v167
	v_fmamk_f32 v164, v164, 0x3a800000, v200
	v_rsq_f32_e32 v164, v164
	ds_read_b128 v[84:87], v82 offset:16640
	ds_read_b128 v[98:101], v82 offset:16704
	s_waitcnt lgkmcnt(2)
	v_pk_mul_f32 v[72:73], v[72:73], v[134:135] op_sel_hi:[1,0]
	v_pk_mul_f32 v[74:75], v[74:75], v[134:135] op_sel_hi:[1,0]
	v_mul_f32_e32 v102, 0xbfb8aa3b, v72
	v_mul_f32_e32 v103, 0xbfb8aa3b, v73
	v_mul_f32_e32 v104, 0xbfb8aa3b, v74
	v_mul_f32_e32 v105, 0xbfb8aa3b, v75
	v_exp_f32_e32 v102, v102
	v_exp_f32_e32 v103, v103
	v_exp_f32_e32 v104, v104
	v_exp_f32_e32 v105, v105
	v_pk_mul_f32 v[76:77], v[76:77], v[134:135] op_sel_hi:[1,0]
	v_pk_mul_f32 v[78:79], v[78:79], v[134:135] op_sel_hi:[1,0]
	v_pk_add_f32 v[102:103], v[102:103], 1.0 op_sel_hi:[1,0]
	v_pk_add_f32 v[104:105], v[104:105], 1.0 op_sel_hi:[1,0]
	v_rcp_f32_e32 v102, v102
	v_rcp_f32_e32 v103, v103
	v_rcp_f32_e32 v104, v104
	v_rcp_f32_e32 v105, v105
	s_nop 0
	v_pk_mul_f32 v[72:73], v[72:73], v[102:103]
	v_pk_mul_f32 v[74:75], v[74:75], v[104:105]
	v_pk_mul_f32 v[72:73], v[76:77], v[72:73]
	v_pk_mul_f32 v[74:75], v[78:79], v[74:75]
	v_cvt_pk_bf16_f32 v102, v72, v73
	v_cvt_pk_bf16_f32 v103, v74, v75
	global_store_dwordx2 v[70:71], v[102:103], off
	v_lshl_add_u64 v[70:71], v[70:71], 0, s[98:99]
	ds_read_b128 v[72:75], v82 offset:33280
	ds_read_b128 v[76:79], v82 offset:33344
	s_waitcnt lgkmcnt(2)
	v_pk_mul_f32 v[84:85], v[84:85], v[138:139] op_sel_hi:[1,0]
	v_pk_mul_f32 v[86:87], v[86:87], v[138:139] op_sel_hi:[1,0]
	v_mul_f32_e32 v102, 0xbfb8aa3b, v84
	v_mul_f32_e32 v103, 0xbfb8aa3b, v85
	v_mul_f32_e32 v104, 0xbfb8aa3b, v86
	v_mul_f32_e32 v105, 0xbfb8aa3b, v87
	v_exp_f32_e32 v102, v102
	v_exp_f32_e32 v103, v103
	v_exp_f32_e32 v104, v104
	v_exp_f32_e32 v105, v105
	v_pk_mul_f32 v[98:99], v[98:99], v[138:139] op_sel_hi:[1,0]
	v_pk_mul_f32 v[100:101], v[100:101], v[138:139] op_sel_hi:[1,0]
	v_pk_add_f32 v[102:103], v[102:103], 1.0 op_sel_hi:[1,0]
	v_pk_add_f32 v[104:105], v[104:105], 1.0 op_sel_hi:[1,0]
	v_rcp_f32_e32 v102, v102
	v_rcp_f32_e32 v103, v103
	v_rcp_f32_e32 v104, v104
	v_rcp_f32_e32 v105, v105
	s_nop 0
	v_pk_mul_f32 v[84:85], v[84:85], v[102:103]
	v_pk_mul_f32 v[86:87], v[86:87], v[104:105]
	v_pk_mul_f32 v[84:85], v[98:99], v[84:85]
	v_pk_mul_f32 v[86:87], v[100:101], v[86:87]
	v_cvt_pk_bf16_f32 v102, v84, v85
	v_cvt_pk_bf16_f32 v103, v86, v87
	global_store_dwordx2 v[70:71], v[102:103], off
	v_lshl_add_u64 v[70:71], v[70:71], 0, s[98:99]
	ds_read_b128 v[84:87], v82 offset:49920
	ds_read_b128 v[98:101], v82 offset:49984
	s_waitcnt lgkmcnt(2)
	v_pk_mul_f32 v[72:73], v[72:73], v[144:145] op_sel_hi:[1,0]
	v_pk_mul_f32 v[74:75], v[74:75], v[144:145] op_sel_hi:[1,0]
	v_mul_f32_e32 v102, 0xbfb8aa3b, v72
	v_mul_f32_e32 v103, 0xbfb8aa3b, v73
	v_mul_f32_e32 v104, 0xbfb8aa3b, v74
	v_mul_f32_e32 v105, 0xbfb8aa3b, v75
	v_exp_f32_e32 v102, v102
	v_exp_f32_e32 v103, v103
	v_exp_f32_e32 v104, v104
	v_exp_f32_e32 v105, v105
	v_pk_mul_f32 v[76:77], v[76:77], v[144:145] op_sel_hi:[1,0]
	v_pk_mul_f32 v[78:79], v[78:79], v[144:145] op_sel_hi:[1,0]
	v_pk_add_f32 v[102:103], v[102:103], 1.0 op_sel_hi:[1,0]
	v_pk_add_f32 v[104:105], v[104:105], 1.0 op_sel_hi:[1,0]
	v_rcp_f32_e32 v102, v102
	v_rcp_f32_e32 v103, v103
	v_rcp_f32_e32 v104, v104
	v_rcp_f32_e32 v105, v105
	s_nop 0
	v_pk_mul_f32 v[72:73], v[72:73], v[102:103]
	v_pk_mul_f32 v[74:75], v[74:75], v[104:105]
	v_pk_mul_f32 v[72:73], v[76:77], v[72:73]
	v_pk_mul_f32 v[74:75], v[78:79], v[74:75]
	v_cvt_pk_bf16_f32 v102, v72, v73
	v_cvt_pk_bf16_f32 v103, v74, v75
	global_store_dwordx2 v[70:71], v[102:103], off
	v_lshl_add_u64 v[70:71], v[70:71], 0, s[98:99]
	ds_read_b128 v[72:75], v0
	ds_read_b128 v[76:79], v0 offset:64
	s_waitcnt lgkmcnt(2)
	v_pk_mul_f32 v[84:85], v[84:85], v[148:149] op_sel_hi:[1,0]
	v_pk_mul_f32 v[86:87], v[86:87], v[148:149] op_sel_hi:[1,0]
	v_mul_f32_e32 v102, 0xbfb8aa3b, v84
	v_mul_f32_e32 v103, 0xbfb8aa3b, v85
	v_mul_f32_e32 v104, 0xbfb8aa3b, v86
	v_mul_f32_e32 v105, 0xbfb8aa3b, v87
	v_exp_f32_e32 v102, v102
	v_exp_f32_e32 v103, v103
	v_exp_f32_e32 v104, v104
	v_exp_f32_e32 v105, v105
	v_pk_mul_f32 v[98:99], v[98:99], v[148:149] op_sel_hi:[1,0]
	v_pk_mul_f32 v[100:101], v[100:101], v[148:149] op_sel_hi:[1,0]
	v_pk_add_f32 v[102:103], v[102:103], 1.0 op_sel_hi:[1,0]
	v_pk_add_f32 v[104:105], v[104:105], 1.0 op_sel_hi:[1,0]
	v_rcp_f32_e32 v102, v102
	v_rcp_f32_e32 v103, v103
	v_rcp_f32_e32 v104, v104
	v_rcp_f32_e32 v105, v105
	s_nop 0
	v_pk_mul_f32 v[84:85], v[84:85], v[102:103]
	v_pk_mul_f32 v[86:87], v[86:87], v[104:105]
	v_pk_mul_f32 v[84:85], v[98:99], v[84:85]
	v_pk_mul_f32 v[86:87], v[100:101], v[86:87]
	v_cvt_pk_bf16_f32 v102, v84, v85
	v_cvt_pk_bf16_f32 v103, v86, v87
	global_store_dwordx2 v[70:71], v[102:103], off
	v_lshl_add_u64 v[70:71], v[70:71], 0, s[98:99]
	ds_read_b128 v[84:87], v0 offset:16640
	ds_read_b128 v[98:101], v0 offset:16704
	s_waitcnt lgkmcnt(2)
	v_pk_mul_f32 v[72:73], v[72:73], v[152:153] op_sel_hi:[1,0]
	v_pk_mul_f32 v[74:75], v[74:75], v[152:153] op_sel_hi:[1,0]
	v_mul_f32_e32 v102, 0xbfb8aa3b, v72
	v_mul_f32_e32 v103, 0xbfb8aa3b, v73
	v_mul_f32_e32 v104, 0xbfb8aa3b, v74
	v_mul_f32_e32 v105, 0xbfb8aa3b, v75
	v_exp_f32_e32 v102, v102
	v_exp_f32_e32 v103, v103
	v_exp_f32_e32 v104, v104
	v_exp_f32_e32 v105, v105
	v_pk_mul_f32 v[76:77], v[76:77], v[152:153] op_sel_hi:[1,0]
	v_pk_mul_f32 v[78:79], v[78:79], v[152:153] op_sel_hi:[1,0]
	v_pk_add_f32 v[102:103], v[102:103], 1.0 op_sel_hi:[1,0]
	v_pk_add_f32 v[104:105], v[104:105], 1.0 op_sel_hi:[1,0]
	v_rcp_f32_e32 v102, v102
	v_rcp_f32_e32 v103, v103
	v_rcp_f32_e32 v104, v104
	v_rcp_f32_e32 v105, v105
	s_nop 0
	v_pk_mul_f32 v[72:73], v[72:73], v[102:103]
	v_pk_mul_f32 v[74:75], v[74:75], v[104:105]
	v_pk_mul_f32 v[72:73], v[76:77], v[72:73]
	v_pk_mul_f32 v[74:75], v[78:79], v[74:75]
	v_cvt_pk_bf16_f32 v102, v72, v73
	v_cvt_pk_bf16_f32 v103, v74, v75
	global_store_dwordx2 v[70:71], v[102:103], off
	v_lshl_add_u64 v[70:71], v[70:71], 0, s[98:99]
	ds_read_b128 v[72:75], v0 offset:33280
	ds_read_b128 v[76:79], v0 offset:33344
	s_waitcnt lgkmcnt(2)
	v_pk_mul_f32 v[84:85], v[84:85], v[156:157] op_sel_hi:[1,0]
	v_pk_mul_f32 v[86:87], v[86:87], v[156:157] op_sel_hi:[1,0]
	v_mul_f32_e32 v102, 0xbfb8aa3b, v84
	v_mul_f32_e32 v103, 0xbfb8aa3b, v85
	v_mul_f32_e32 v104, 0xbfb8aa3b, v86
	v_mul_f32_e32 v105, 0xbfb8aa3b, v87
	v_exp_f32_e32 v102, v102
	v_exp_f32_e32 v103, v103
	v_exp_f32_e32 v104, v104
	v_exp_f32_e32 v105, v105
	v_pk_mul_f32 v[98:99], v[98:99], v[156:157] op_sel_hi:[1,0]
	v_pk_mul_f32 v[100:101], v[100:101], v[156:157] op_sel_hi:[1,0]
	v_pk_add_f32 v[102:103], v[102:103], 1.0 op_sel_hi:[1,0]
	v_pk_add_f32 v[104:105], v[104:105], 1.0 op_sel_hi:[1,0]
	v_rcp_f32_e32 v102, v102
	v_rcp_f32_e32 v103, v103
	v_rcp_f32_e32 v104, v104
	v_rcp_f32_e32 v105, v105
	s_nop 0
	v_pk_mul_f32 v[84:85], v[84:85], v[102:103]
	v_pk_mul_f32 v[86:87], v[86:87], v[104:105]
	v_pk_mul_f32 v[84:85], v[98:99], v[84:85]
	v_pk_mul_f32 v[86:87], v[100:101], v[86:87]
	v_cvt_pk_bf16_f32 v102, v84, v85
	v_cvt_pk_bf16_f32 v103, v86, v87
	global_store_dwordx2 v[70:71], v[102:103], off
	v_lshl_add_u64 v[70:71], v[70:71], 0, s[98:99]
	ds_read_b128 v[84:87], v0 offset:49920
	ds_read_b128 v[98:101], v0 offset:49984
	s_waitcnt lgkmcnt(2)
	v_pk_mul_f32 v[72:73], v[72:73], v[160:161] op_sel_hi:[1,0]
	v_pk_mul_f32 v[74:75], v[74:75], v[160:161] op_sel_hi:[1,0]
	v_mul_f32_e32 v102, 0xbfb8aa3b, v72
	v_mul_f32_e32 v103, 0xbfb8aa3b, v73
	v_mul_f32_e32 v104, 0xbfb8aa3b, v74
	v_mul_f32_e32 v105, 0xbfb8aa3b, v75
	v_exp_f32_e32 v102, v102
	v_exp_f32_e32 v103, v103
	v_exp_f32_e32 v104, v104
	v_exp_f32_e32 v105, v105
	v_pk_mul_f32 v[76:77], v[76:77], v[160:161] op_sel_hi:[1,0]
	v_pk_mul_f32 v[78:79], v[78:79], v[160:161] op_sel_hi:[1,0]
	v_pk_add_f32 v[102:103], v[102:103], 1.0 op_sel_hi:[1,0]
	v_pk_add_f32 v[104:105], v[104:105], 1.0 op_sel_hi:[1,0]
	v_rcp_f32_e32 v102, v102
	v_rcp_f32_e32 v103, v103
	v_rcp_f32_e32 v104, v104
	v_rcp_f32_e32 v105, v105
	s_nop 0
	v_pk_mul_f32 v[72:73], v[72:73], v[102:103]
	v_pk_mul_f32 v[74:75], v[74:75], v[104:105]
	v_pk_mul_f32 v[72:73], v[76:77], v[72:73]
	v_pk_mul_f32 v[74:75], v[78:79], v[74:75]
	v_cvt_pk_bf16_f32 v102, v72, v73
	v_cvt_pk_bf16_f32 v103, v74, v75
	global_store_dwordx2 v[70:71], v[102:103], off
	v_lshl_add_u64 v[70:71], v[70:71], 0, s[98:99]
	s_waitcnt lgkmcnt(0)
	v_pk_mul_f32 v[84:85], v[84:85], v[164:165] op_sel_hi:[1,0]
	v_pk_mul_f32 v[86:87], v[86:87], v[164:165] op_sel_hi:[1,0]
	v_mul_f32_e32 v102, 0xbfb8aa3b, v84
	v_mul_f32_e32 v103, 0xbfb8aa3b, v85
	v_mul_f32_e32 v104, 0xbfb8aa3b, v86
	v_mul_f32_e32 v105, 0xbfb8aa3b, v87
	v_exp_f32_e32 v102, v102
	v_exp_f32_e32 v103, v103
	v_exp_f32_e32 v104, v104
	v_exp_f32_e32 v105, v105
	v_pk_mul_f32 v[98:99], v[98:99], v[164:165] op_sel_hi:[1,0]
	v_pk_mul_f32 v[100:101], v[100:101], v[164:165] op_sel_hi:[1,0]
	v_pk_add_f32 v[102:103], v[102:103], 1.0 op_sel_hi:[1,0]
	v_pk_add_f32 v[104:105], v[104:105], 1.0 op_sel_hi:[1,0]
	v_rcp_f32_e32 v102, v102
	v_rcp_f32_e32 v103, v103
	v_rcp_f32_e32 v104, v104
	v_rcp_f32_e32 v105, v105
	s_nop 0
	v_pk_mul_f32 v[84:85], v[84:85], v[102:103]
	v_pk_mul_f32 v[86:87], v[86:87], v[104:105]
	v_pk_mul_f32 v[84:85], v[98:99], v[84:85]
	v_pk_mul_f32 v[86:87], v[100:101], v[86:87]
	v_cvt_pk_bf16_f32 v102, v84, v85
	v_cvt_pk_bf16_f32 v103, v86, v87
	global_store_dwordx2 v[70:71], v[102:103], off
	s_barrier
	ds_write2_b32 v130, v2, v18 offset1:16
	ds_write2_b32 v114, v3, v19 offset0:4 offset1:20
	ds_write2_b32 v115, v4, v20 offset0:8 offset1:24
	ds_write2_b32 v116, v5, v21 offset0:12 offset1:28
	ds_write2_b32 v117, v6, v22 offset0:64 offset1:80
	ds_write2_b32 v94, v7, v23 offset0:68 offset1:84
	ds_write2_b32 v95, v8, v24 offset0:72 offset1:88
	ds_write2_b32 v96, v9, v25 offset0:76 offset1:92
	ds_write2_b32 v132, v10, v26 offset0:128 offset1:144
	ds_write2_b32 v97, v11, v27 offset0:132 offset1:148
	ds_write2_b32 v126, v12, v28 offset0:136 offset1:152
	ds_write2_b32 v127, v13, v29 offset0:140 offset1:156
	ds_write2_b32 v133, v14, v30 offset0:192 offset1:208
	ds_write2_b32 v128, v15, v31 offset0:196 offset1:212
	ds_write2_b32 v129, v16, v32 offset0:200 offset1:216
	ds_write2_b32 v131, v17, v33 offset0:204 offset1:220
	ds_write2_b32 v130, v34, v50 offset0:128 offset1:144
	ds_write2_b32 v114, v35, v51 offset0:132 offset1:148
	ds_write2_b32 v115, v36, v52 offset0:136 offset1:152
	ds_write2_b32 v116, v37, v53 offset0:140 offset1:156
	ds_write2_b32 v117, v38, v54 offset0:192 offset1:208
	ds_write2_b32 v94, v39, v55 offset0:196 offset1:212
	ds_write2_b32 v95, v40, v56 offset0:200 offset1:216
	ds_write2_b32 v96, v41, v57 offset0:204 offset1:220
	ds_write2_b32 v97, v42, v58 offset1:16
	ds_write2_b32 v126, v43, v59 offset0:4 offset1:20
	ds_write2_b32 v127, v44, v60 offset0:8 offset1:24
	ds_write2_b32 v90, v45, v61 offset0:12 offset1:28
	ds_write2_b32 v128, v46, v62 offset0:64 offset1:80
	ds_write2_b32 v129, v47, v63 offset0:68 offset1:84
	ds_write2_b32 v131, v48, v64 offset0:72 offset1:88
	ds_write2_b32 v91, v49, v65 offset0:76 offset1:92
	v_add_u32_e32 v2, s8, v88
	v_ashrrev_i32_e32 v3, 31, v2
	v_lshl_add_u64 v[4:5], v[2:3], 4, s[46:47]
	s_waitcnt lgkmcnt(0)
	s_barrier
	global_load_dwordx4 v[134:137], v[4:5], off
	global_load_dwordx4 v[138:141], v[4:5], off offset:256
	global_load_dwordx4 v[144:147], v[4:5], off offset:512
	global_load_dwordx4 v[148:151], v[4:5], off offset:768
	global_load_dwordx4 v[152:155], v[4:5], off offset:1024
	global_load_dwordx4 v[156:159], v[4:5], off offset:1280
	global_load_dwordx4 v[160:163], v[4:5], off offset:1536
	global_load_dwordx4 v[164:167], v[4:5], off offset:1792
	s_waitcnt vmcnt(0)
	v_mad_i64_i32 v[2:3], s[10:11], v2, s14, v[66:67]
	ds_read_b128 v[4:7], v82
	ds_read_b128 v[8:11], v82 offset:64
	v_add_u32_e32 v0, 0x10400, v82
	s_lshl_b32 s98, s14, 4
	s_mov_b32 s99, 0
	v_add_f32_e32 v134, v134, v135
	v_add_f32_e32 v134, v134, v136
	v_add_f32_e32 v134, v134, v137
	v_fmamk_f32 v134, v134, 0x3a800000, v200
	v_rsq_f32_e32 v134, v134
	v_add_f32_e32 v138, v138, v139
	v_add_f32_e32 v138, v138, v140
	v_add_f32_e32 v138, v138, v141
	v_fmamk_f32 v138, v138, 0x3a800000, v200
	v_rsq_f32_e32 v138, v138
	v_add_f32_e32 v144, v144, v145
	v_add_f32_e32 v144, v144, v146
	v_add_f32_e32 v144, v144, v147
	v_fmamk_f32 v144, v144, 0x3a800000, v200
	v_rsq_f32_e32 v144, v144
	v_add_f32_e32 v148, v148, v149
	v_add_f32_e32 v148, v148, v150
	v_add_f32_e32 v148, v148, v151
	v_fmamk_f32 v148, v148, 0x3a800000, v200
	v_rsq_f32_e32 v148, v148
	v_add_f32_e32 v152, v152, v153
	v_add_f32_e32 v152, v152, v154
	v_add_f32_e32 v152, v152, v155
	v_fmamk_f32 v152, v152, 0x3a800000, v200
	v_rsq_f32_e32 v152, v152
	v_add_f32_e32 v156, v156, v157
	v_add_f32_e32 v156, v156, v158
	v_add_f32_e32 v156, v156, v159
	v_fmamk_f32 v156, v156, 0x3a800000, v200
	v_rsq_f32_e32 v156, v156
	v_add_f32_e32 v160, v160, v161
	v_add_f32_e32 v160, v160, v162
	v_add_f32_e32 v160, v160, v163
	v_fmamk_f32 v160, v160, 0x3a800000, v200
	v_rsq_f32_e32 v160, v160
	v_add_f32_e32 v164, v164, v165
	v_add_f32_e32 v164, v164, v166
	v_add_f32_e32 v164, v164, v167
	v_fmamk_f32 v164, v164, 0x3a800000, v200
	v_rsq_f32_e32 v164, v164
	ds_read_b128 v[12:15], v82 offset:16640
	ds_read_b128 v[16:19], v82 offset:16704
	s_waitcnt lgkmcnt(2)
	v_pk_mul_f32 v[4:5], v[4:5], v[134:135] op_sel_hi:[1,0]
	v_pk_mul_f32 v[6:7], v[6:7], v[134:135] op_sel_hi:[1,0]
	v_mul_f32_e32 v20, 0xbfb8aa3b, v4
	v_mul_f32_e32 v21, 0xbfb8aa3b, v5
	v_mul_f32_e32 v22, 0xbfb8aa3b, v6
	v_mul_f32_e32 v23, 0xbfb8aa3b, v7
	v_exp_f32_e32 v20, v20
	v_exp_f32_e32 v21, v21
	v_exp_f32_e32 v22, v22
	v_exp_f32_e32 v23, v23
	v_pk_mul_f32 v[8:9], v[8:9], v[134:135] op_sel_hi:[1,0]
	v_pk_mul_f32 v[10:11], v[10:11], v[134:135] op_sel_hi:[1,0]
	v_pk_add_f32 v[20:21], v[20:21], 1.0 op_sel_hi:[1,0]
	v_pk_add_f32 v[22:23], v[22:23], 1.0 op_sel_hi:[1,0]
	v_rcp_f32_e32 v20, v20
	v_rcp_f32_e32 v21, v21
	v_rcp_f32_e32 v22, v22
	v_rcp_f32_e32 v23, v23
	s_nop 0
	v_pk_mul_f32 v[4:5], v[4:5], v[20:21]
	v_pk_mul_f32 v[6:7], v[6:7], v[22:23]
	v_pk_mul_f32 v[4:5], v[8:9], v[4:5]
	v_pk_mul_f32 v[6:7], v[10:11], v[6:7]
	v_cvt_pk_bf16_f32 v20, v4, v5
	v_cvt_pk_bf16_f32 v21, v6, v7
	global_store_dwordx2 v[2:3], v[20:21], off
	v_lshl_add_u64 v[2:3], v[2:3], 0, s[98:99]
	ds_read_b128 v[4:7], v82 offset:33280
	ds_read_b128 v[8:11], v82 offset:33344
	s_waitcnt lgkmcnt(2)
	v_pk_mul_f32 v[12:13], v[12:13], v[138:139] op_sel_hi:[1,0]
	v_pk_mul_f32 v[14:15], v[14:15], v[138:139] op_sel_hi:[1,0]
	v_mul_f32_e32 v20, 0xbfb8aa3b, v12
	v_mul_f32_e32 v21, 0xbfb8aa3b, v13
	v_mul_f32_e32 v22, 0xbfb8aa3b, v14
	v_mul_f32_e32 v23, 0xbfb8aa3b, v15
	v_exp_f32_e32 v20, v20
	v_exp_f32_e32 v21, v21
	v_exp_f32_e32 v22, v22
	v_exp_f32_e32 v23, v23
	v_pk_mul_f32 v[16:17], v[16:17], v[138:139] op_sel_hi:[1,0]
	v_pk_mul_f32 v[18:19], v[18:19], v[138:139] op_sel_hi:[1,0]
	v_pk_add_f32 v[20:21], v[20:21], 1.0 op_sel_hi:[1,0]
	v_pk_add_f32 v[22:23], v[22:23], 1.0 op_sel_hi:[1,0]
	v_rcp_f32_e32 v20, v20
	v_rcp_f32_e32 v21, v21
	v_rcp_f32_e32 v22, v22
	v_rcp_f32_e32 v23, v23
	s_nop 0
	v_pk_mul_f32 v[12:13], v[12:13], v[20:21]
	v_pk_mul_f32 v[14:15], v[14:15], v[22:23]
	v_pk_mul_f32 v[12:13], v[16:17], v[12:13]
	v_pk_mul_f32 v[14:15], v[18:19], v[14:15]
	v_cvt_pk_bf16_f32 v20, v12, v13
	v_cvt_pk_bf16_f32 v21, v14, v15
	global_store_dwordx2 v[2:3], v[20:21], off
	v_lshl_add_u64 v[2:3], v[2:3], 0, s[98:99]
	ds_read_b128 v[12:15], v82 offset:49920
	ds_read_b128 v[16:19], v82 offset:49984
	s_waitcnt lgkmcnt(2)
	v_pk_mul_f32 v[4:5], v[4:5], v[144:145] op_sel_hi:[1,0]
	v_pk_mul_f32 v[6:7], v[6:7], v[144:145] op_sel_hi:[1,0]
	v_mul_f32_e32 v20, 0xbfb8aa3b, v4
	v_mul_f32_e32 v21, 0xbfb8aa3b, v5
	v_mul_f32_e32 v22, 0xbfb8aa3b, v6
	v_mul_f32_e32 v23, 0xbfb8aa3b, v7
	v_exp_f32_e32 v20, v20
	v_exp_f32_e32 v21, v21
	v_exp_f32_e32 v22, v22
	v_exp_f32_e32 v23, v23
	v_pk_mul_f32 v[8:9], v[8:9], v[144:145] op_sel_hi:[1,0]
	v_pk_mul_f32 v[10:11], v[10:11], v[144:145] op_sel_hi:[1,0]
	v_pk_add_f32 v[20:21], v[20:21], 1.0 op_sel_hi:[1,0]
	v_pk_add_f32 v[22:23], v[22:23], 1.0 op_sel_hi:[1,0]
	v_rcp_f32_e32 v20, v20
	v_rcp_f32_e32 v21, v21
	v_rcp_f32_e32 v22, v22
	v_rcp_f32_e32 v23, v23
	s_nop 0
	v_pk_mul_f32 v[4:5], v[4:5], v[20:21]
	v_pk_mul_f32 v[6:7], v[6:7], v[22:23]
	v_pk_mul_f32 v[4:5], v[8:9], v[4:5]
	v_pk_mul_f32 v[6:7], v[10:11], v[6:7]
	v_cvt_pk_bf16_f32 v20, v4, v5
	v_cvt_pk_bf16_f32 v21, v6, v7
	global_store_dwordx2 v[2:3], v[20:21], off
	v_lshl_add_u64 v[2:3], v[2:3], 0, s[98:99]
	ds_read_b128 v[4:7], v0
	ds_read_b128 v[8:11], v0 offset:64
	s_waitcnt lgkmcnt(2)
	v_pk_mul_f32 v[12:13], v[12:13], v[148:149] op_sel_hi:[1,0]
	v_pk_mul_f32 v[14:15], v[14:15], v[148:149] op_sel_hi:[1,0]
	v_mul_f32_e32 v20, 0xbfb8aa3b, v12
	v_mul_f32_e32 v21, 0xbfb8aa3b, v13
	v_mul_f32_e32 v22, 0xbfb8aa3b, v14
	v_mul_f32_e32 v23, 0xbfb8aa3b, v15
	v_exp_f32_e32 v20, v20
	v_exp_f32_e32 v21, v21
	v_exp_f32_e32 v22, v22
	v_exp_f32_e32 v23, v23
	v_pk_mul_f32 v[16:17], v[16:17], v[148:149] op_sel_hi:[1,0]
	v_pk_mul_f32 v[18:19], v[18:19], v[148:149] op_sel_hi:[1,0]
	v_pk_add_f32 v[20:21], v[20:21], 1.0 op_sel_hi:[1,0]
	v_pk_add_f32 v[22:23], v[22:23], 1.0 op_sel_hi:[1,0]
	v_rcp_f32_e32 v20, v20
	v_rcp_f32_e32 v21, v21
	v_rcp_f32_e32 v22, v22
	v_rcp_f32_e32 v23, v23
	s_nop 0
	v_pk_mul_f32 v[12:13], v[12:13], v[20:21]
	v_pk_mul_f32 v[14:15], v[14:15], v[22:23]
	v_pk_mul_f32 v[12:13], v[16:17], v[12:13]
	v_pk_mul_f32 v[14:15], v[18:19], v[14:15]
	v_cvt_pk_bf16_f32 v20, v12, v13
	v_cvt_pk_bf16_f32 v21, v14, v15
	global_store_dwordx2 v[2:3], v[20:21], off
	v_lshl_add_u64 v[2:3], v[2:3], 0, s[98:99]
	ds_read_b128 v[12:15], v0 offset:16640
	ds_read_b128 v[16:19], v0 offset:16704
	s_waitcnt lgkmcnt(2)
	v_pk_mul_f32 v[4:5], v[4:5], v[152:153] op_sel_hi:[1,0]
	v_pk_mul_f32 v[6:7], v[6:7], v[152:153] op_sel_hi:[1,0]
	v_mul_f32_e32 v20, 0xbfb8aa3b, v4
	v_mul_f32_e32 v21, 0xbfb8aa3b, v5
	v_mul_f32_e32 v22, 0xbfb8aa3b, v6
	v_mul_f32_e32 v23, 0xbfb8aa3b, v7
	v_exp_f32_e32 v20, v20
	v_exp_f32_e32 v21, v21
	v_exp_f32_e32 v22, v22
	v_exp_f32_e32 v23, v23
	v_pk_mul_f32 v[8:9], v[8:9], v[152:153] op_sel_hi:[1,0]
	v_pk_mul_f32 v[10:11], v[10:11], v[152:153] op_sel_hi:[1,0]
	v_pk_add_f32 v[20:21], v[20:21], 1.0 op_sel_hi:[1,0]
	v_pk_add_f32 v[22:23], v[22:23], 1.0 op_sel_hi:[1,0]
	v_rcp_f32_e32 v20, v20
	v_rcp_f32_e32 v21, v21
	v_rcp_f32_e32 v22, v22
	v_rcp_f32_e32 v23, v23
	s_nop 0
	v_pk_mul_f32 v[4:5], v[4:5], v[20:21]
	v_pk_mul_f32 v[6:7], v[6:7], v[22:23]
	v_pk_mul_f32 v[4:5], v[8:9], v[4:5]
	v_pk_mul_f32 v[6:7], v[10:11], v[6:7]
	v_cvt_pk_bf16_f32 v20, v4, v5
	v_cvt_pk_bf16_f32 v21, v6, v7
	global_store_dwordx2 v[2:3], v[20:21], off
	v_lshl_add_u64 v[2:3], v[2:3], 0, s[98:99]
	ds_read_b128 v[4:7], v0 offset:33280
	ds_read_b128 v[8:11], v0 offset:33344
	s_waitcnt lgkmcnt(2)
	v_pk_mul_f32 v[12:13], v[12:13], v[156:157] op_sel_hi:[1,0]
	v_pk_mul_f32 v[14:15], v[14:15], v[156:157] op_sel_hi:[1,0]
	v_mul_f32_e32 v20, 0xbfb8aa3b, v12
	v_mul_f32_e32 v21, 0xbfb8aa3b, v13
	v_mul_f32_e32 v22, 0xbfb8aa3b, v14
	v_mul_f32_e32 v23, 0xbfb8aa3b, v15
	v_exp_f32_e32 v20, v20
	v_exp_f32_e32 v21, v21
	v_exp_f32_e32 v22, v22
	v_exp_f32_e32 v23, v23
	v_pk_mul_f32 v[16:17], v[16:17], v[156:157] op_sel_hi:[1,0]
	v_pk_mul_f32 v[18:19], v[18:19], v[156:157] op_sel_hi:[1,0]
	v_pk_add_f32 v[20:21], v[20:21], 1.0 op_sel_hi:[1,0]
	v_pk_add_f32 v[22:23], v[22:23], 1.0 op_sel_hi:[1,0]
	v_rcp_f32_e32 v20, v20
	v_rcp_f32_e32 v21, v21
	v_rcp_f32_e32 v22, v22
	v_rcp_f32_e32 v23, v23
	s_nop 0
	v_pk_mul_f32 v[12:13], v[12:13], v[20:21]
	v_pk_mul_f32 v[14:15], v[14:15], v[22:23]
	v_pk_mul_f32 v[12:13], v[16:17], v[12:13]
	v_pk_mul_f32 v[14:15], v[18:19], v[14:15]
	v_cvt_pk_bf16_f32 v20, v12, v13
	v_cvt_pk_bf16_f32 v21, v14, v15
	global_store_dwordx2 v[2:3], v[20:21], off
	v_lshl_add_u64 v[2:3], v[2:3], 0, s[98:99]
	ds_read_b128 v[12:15], v0 offset:49920
	ds_read_b128 v[16:19], v0 offset:49984
	s_waitcnt lgkmcnt(2)
	v_pk_mul_f32 v[4:5], v[4:5], v[160:161] op_sel_hi:[1,0]
	v_pk_mul_f32 v[6:7], v[6:7], v[160:161] op_sel_hi:[1,0]
	v_mul_f32_e32 v20, 0xbfb8aa3b, v4
	v_mul_f32_e32 v21, 0xbfb8aa3b, v5
	v_mul_f32_e32 v22, 0xbfb8aa3b, v6
	v_mul_f32_e32 v23, 0xbfb8aa3b, v7
	v_exp_f32_e32 v20, v20
	v_exp_f32_e32 v21, v21
	v_exp_f32_e32 v22, v22
	v_exp_f32_e32 v23, v23
	v_pk_mul_f32 v[8:9], v[8:9], v[160:161] op_sel_hi:[1,0]
	v_pk_mul_f32 v[10:11], v[10:11], v[160:161] op_sel_hi:[1,0]
	v_pk_add_f32 v[20:21], v[20:21], 1.0 op_sel_hi:[1,0]
	v_pk_add_f32 v[22:23], v[22:23], 1.0 op_sel_hi:[1,0]
	v_rcp_f32_e32 v20, v20
	v_rcp_f32_e32 v21, v21
	v_rcp_f32_e32 v22, v22
	v_rcp_f32_e32 v23, v23
	s_nop 0
	v_pk_mul_f32 v[4:5], v[4:5], v[20:21]
	v_pk_mul_f32 v[6:7], v[6:7], v[22:23]
	v_pk_mul_f32 v[4:5], v[8:9], v[4:5]
	v_pk_mul_f32 v[6:7], v[10:11], v[6:7]
	v_cvt_pk_bf16_f32 v20, v4, v5
	v_cvt_pk_bf16_f32 v21, v6, v7
	global_store_dwordx2 v[2:3], v[20:21], off
	v_lshl_add_u64 v[2:3], v[2:3], 0, s[98:99]
	s_waitcnt lgkmcnt(0)
	v_pk_mul_f32 v[12:13], v[12:13], v[164:165] op_sel_hi:[1,0]
	v_pk_mul_f32 v[14:15], v[14:15], v[164:165] op_sel_hi:[1,0]
	v_mul_f32_e32 v20, 0xbfb8aa3b, v12
	v_mul_f32_e32 v21, 0xbfb8aa3b, v13
	v_mul_f32_e32 v22, 0xbfb8aa3b, v14
	v_mul_f32_e32 v23, 0xbfb8aa3b, v15
	v_exp_f32_e32 v20, v20
	v_exp_f32_e32 v21, v21
	v_exp_f32_e32 v22, v22
	v_exp_f32_e32 v23, v23
	v_pk_mul_f32 v[16:17], v[16:17], v[164:165] op_sel_hi:[1,0]
	v_pk_mul_f32 v[18:19], v[18:19], v[164:165] op_sel_hi:[1,0]
	v_pk_add_f32 v[20:21], v[20:21], 1.0 op_sel_hi:[1,0]
	v_pk_add_f32 v[22:23], v[22:23], 1.0 op_sel_hi:[1,0]
	v_rcp_f32_e32 v20, v20
	v_rcp_f32_e32 v21, v21
	v_rcp_f32_e32 v22, v22
	v_rcp_f32_e32 v23, v23
	s_nop 0
	v_pk_mul_f32 v[12:13], v[12:13], v[20:21]
	v_pk_mul_f32 v[14:15], v[14:15], v[22:23]
	v_pk_mul_f32 v[12:13], v[16:17], v[12:13]
	v_pk_mul_f32 v[14:15], v[18:19], v[14:15]
	v_cvt_pk_bf16_f32 v20, v12, v13
	v_cvt_pk_bf16_f32 v21, v14, v15
	global_store_dwordx2 v[2:3], v[20:21], off
	s_barrier

.LBB0_1078:
	s_or_b64 exec, exec, s[42:43]
	s_movk_i32 s33, 0x410
	v_lshrrev_b32_e32 v130, 2, v142
	v_lshlrev_b32_e32 v131, 1, v142
	v_and_b32_e32 v0, 15, v142
	v_and_b32_e32 v130, 0xfffffcc, v130
	v_and_b32_e32 v131, 0x180, v131
	v_add_u32_e32 v131, 0, v131
	v_lshlrev_b32_e32 v0, 2, v0
	v_mul_lo_u32 v130, v130, s33
	v_add3_u32 v130, v131, v0, v130
	s_waitcnt vmcnt(0)
	s_barrier
	ds_write2_b32 v130, v114, v126 offset1:16
	v_add_u32_e32 v114, 0x400, v130
	ds_write2_b32 v114, v115, v127 offset0:4 offset1:20
	v_add_u32_e32 v115, 0x800, v130
	ds_write2_b32 v115, v116, v128 offset0:8 offset1:24
	v_add_u32_e32 v116, 0xc00, v130
	ds_write2_b32 v116, v117, v129 offset0:12 offset1:28
	v_add_u32_e32 v117, 0x4000, v130
	ds_write2_b32 v117, v82, v94 offset0:64 offset1:80
	v_add_u32_e32 v94, 0x4400, v130
	ds_write2_b32 v94, v83, v95 offset0:68 offset1:84
	v_add_u32_e32 v95, 0x4800, v130
	ds_write2_b32 v95, v84, v96 offset0:72 offset1:88
	v_add_u32_e32 v96, 0x4c00, v130
	v_add_u32_e32 v133, 0xc000, v130
	ds_write2_b32 v96, v85, v97 offset0:76 offset1:92
	v_add_u32_e32 v132, 0x8000, v130
	v_add_u32_e32 v97, 0x8400, v130
	v_add_u32_e32 v126, 0x8800, v130
	v_add_u32_e32 v127, 0x8c00, v130
	ds_write2_b32 v133, v66, v70 offset0:192 offset1:208
	v_add_u32_e32 v128, 0xc400, v130
	v_add_u32_e32 v129, 0xc800, v130
	v_add_u32_e32 v131, 0xcc00, v130
	v_lshlrev_b32_e32 v0, 3, v142
	v_lshlrev_b32_e32 v66, 2, v142
	ds_write2_b32 v132, v74, v78 offset0:128 offset1:144
	ds_write2_b32 v97, v75, v79 offset0:132 offset1:148
	ds_write2_b32 v126, v76, v80 offset0:136 offset1:152
	ds_write2_b32 v127, v77, v81 offset0:140 offset1:156
	ds_write2_b32 v128, v67, v71 offset0:196 offset1:212
	ds_write2_b32 v129, v68, v72 offset0:200 offset1:216
	ds_write2_b32 v131, v69, v73 offset0:204 offset1:220
	ds_write2_b32 v130, v98, v118 offset0:128 offset1:144
	ds_write2_b32 v114, v99, v119 offset0:132 offset1:148
	ds_write2_b32 v115, v100, v120 offset0:136 offset1:152
	ds_write2_b32 v116, v101, v121 offset0:140 offset1:156
	ds_write2_b32 v117, v102, v122 offset0:192 offset1:208
	ds_write2_b32 v94, v103, v123 offset0:196 offset1:212
	ds_write2_b32 v95, v104, v124 offset0:200 offset1:216
	ds_write2_b32 v96, v105, v125 offset0:204 offset1:220
	ds_write2_b32 v97, v90, v110 offset1:16
	ds_write2_b32 v126, v91, v111 offset0:4 offset1:20
	ds_write2_b32 v127, v92, v112 offset0:8 offset1:24
	v_add_u32_e32 v90, 0x9000, v130
	v_and_b32_e32 v0, 0xe0, v0
	v_and_b32_e32 v68, 12, v66
	ds_write2_b32 v90, v93, v113 offset0:12 offset1:28
	ds_write2_b32 v128, v86, v106 offset0:64 offset1:80
	ds_write2_b32 v129, v87, v107 offset0:68 offset1:84
	ds_write2_b32 v131, v88, v108 offset0:72 offset1:88
	v_lshlrev_b32_e32 v66, 2, v0
	v_lshlrev_b32_e32 v67, 2, v68
	v_or_b32_e32 v0, s60, v0
	v_ashrrev_i32_e32 v88, 5, v142
	v_add3_u32 v74, 0, v66, v67
	v_ashrrev_i32_e32 v66, 1, v0
	v_lshlrev_b32_e32 v0, 1, v68
	v_add_u32_e32 v68, s12, v88
	v_ashrrev_i32_e32 v69, 31, v68
	v_add_u32_e32 v91, 0xd000, v130
	v_lshl_add_u64 v[70:71], v[68:69], 4, s[40:41]
	ds_write2_b32 v91, v89, v109 offset0:76 offset1:92
	s_waitcnt lgkmcnt(0)
	s_barrier
	global_load_dwordx4 v[134:137], v[70:71], off
	global_load_dwordx4 v[138:141], v[70:71], off offset:256
	global_load_dwordx4 v[144:147], v[70:71], off offset:512
	global_load_dwordx4 v[148:151], v[70:71], off offset:768
	global_load_dwordx4 v[152:155], v[70:71], off offset:1024
	global_load_dwordx4 v[156:159], v[70:71], off offset:1280
	global_load_dwordx4 v[160:163], v[70:71], off offset:1536
	global_load_dwordx4 v[164:167], v[70:71], off offset:1792
	v_readlane_b32 s20, v255, 27
	v_ashrrev_i32_e32 v67, 31, v66
	v_readlane_b32 s21, v255, 28
	v_mad_u64_u32 v[82:83], s[36:37], v88, s33, v[74:75]
	s_nop 0
	v_lshl_add_u64 v[66:67], v[66:67], 1, s[20:21]
	v_lshl_add_u64 v[66:67], v[66:67], 0, v[0:1]
	s_mov_b32 s20, 0x800000
	s_movk_i32 s21, 0x1600
	s_or_b32 s42, s60, 0x100
	s_ashr_i32 s43, s42, 31
	s_lshl_b64 s[44:45], s[42:43], 11
	s_waitcnt vmcnt(0)
	v_mad_i64_i32 v[68:69], s[36:37], v68, s21, v[66:67]
	ds_read_b128 v[70:73], v82
	ds_read_b128 v[74:77], v82 offset:64
	v_add_u32_e32 v0, 0x10400, v82
	s_lshl_b32 s98, s21, 4
	s_mov_b32 s99, 0
	v_add_f32_e32 v134, v134, v135
	v_add_f32_e32 v134, v134, v136
	v_add_f32_e32 v134, v134, v137
	v_fmamk_f32 v134, v134, 0x3a800000, v200
	v_rsq_f32_e32 v134, v134
	v_add_f32_e32 v138, v138, v139
	v_add_f32_e32 v138, v138, v140
	v_add_f32_e32 v138, v138, v141
	v_fmamk_f32 v138, v138, 0x3a800000, v200
	v_rsq_f32_e32 v138, v138
	v_add_f32_e32 v144, v144, v145
	v_add_f32_e32 v144, v144, v146
	v_add_f32_e32 v144, v144, v147
	v_fmamk_f32 v144, v144, 0x3a800000, v200
	v_rsq_f32_e32 v144, v144
	v_add_f32_e32 v148, v148, v149
	v_add_f32_e32 v148, v148, v150
	v_add_f32_e32 v148, v148, v151
	v_fmamk_f32 v148, v148, 0x3a800000, v200
	v_rsq_f32_e32 v148, v148
	v_add_f32_e32 v152, v152, v153
	v_add_f32_e32 v152, v152, v154
	v_add_f32_e32 v152, v152, v155
	v_fmamk_f32 v152, v152, 0x3a800000, v200
	v_rsq_f32_e32 v152, v152
	v_add_f32_e32 v156, v156, v157
	v_add_f32_e32 v156, v156, v158
	v_add_f32_e32 v156, v156, v159
	v_fmamk_f32 v156, v156, 0x3a800000, v200
	v_rsq_f32_e32 v156, v156
	v_add_f32_e32 v160, v160, v161
	v_add_f32_e32 v160, v160, v162
	v_add_f32_e32 v160, v160, v163
	v_fmamk_f32 v160, v160, 0x3a800000, v200
	v_rsq_f32_e32 v160, v160
	v_add_f32_e32 v164, v164, v165
	v_add_f32_e32 v164, v164, v166
	v_add_f32_e32 v164, v164, v167
	v_fmamk_f32 v164, v164, 0x3a800000, v200
	v_rsq_f32_e32 v164, v164
	ds_read_b128 v[78:81], v82 offset:16640
	ds_read_b128 v[84:87], v82 offset:16704
	s_waitcnt lgkmcnt(2)
	v_pk_mul_f32 v[70:71], v[70:71], v[134:135] op_sel_hi:[1,0]
	v_pk_mul_f32 v[72:73], v[72:73], v[134:135] op_sel_hi:[1,0]
	v_mul_f32_e32 v98, 0xbfb8aa3b, v70
	v_mul_f32_e32 v99, 0xbfb8aa3b, v71
	v_mul_f32_e32 v100, 0xbfb8aa3b, v72
	v_mul_f32_e32 v101, 0xbfb8aa3b, v73
	v_exp_f32_e32 v98, v98
	v_exp_f32_e32 v99, v99
	v_exp_f32_e32 v100, v100
	v_exp_f32_e32 v101, v101
	v_pk_mul_f32 v[74:75], v[74:75], v[134:135] op_sel_hi:[1,0]
	v_pk_mul_f32 v[76:77], v[76:77], v[134:135] op_sel_hi:[1,0]
	v_pk_add_f32 v[98:99], v[98:99], 1.0 op_sel_hi:[1,0]
	v_pk_add_f32 v[100:101], v[100:101], 1.0 op_sel_hi:[1,0]
	v_rcp_f32_e32 v98, v98
	v_rcp_f32_e32 v99, v99
	v_rcp_f32_e32 v100, v100
	v_rcp_f32_e32 v101, v101
	s_nop 0
	v_pk_mul_f32 v[70:71], v[70:71], v[98:99]
	v_pk_mul_f32 v[72:73], v[72:73], v[100:101]
	v_pk_mul_f32 v[70:71], v[74:75], v[70:71]
	v_pk_mul_f32 v[72:73], v[76:77], v[72:73]
	v_cvt_pk_bf16_f32 v98, v70, v71
	v_cvt_pk_bf16_f32 v99, v72, v73
	global_store_dwordx2 v[68:69], v[98:99], off
	v_lshl_add_u64 v[68:69], v[68:69], 0, s[98:99]
	ds_read_b128 v[70:73], v82 offset:33280
	ds_read_b128 v[74:77], v82 offset:33344
	s_waitcnt lgkmcnt(2)
	v_pk_mul_f32 v[78:79], v[78:79], v[138:139] op_sel_hi:[1,0]
	v_pk_mul_f32 v[80:81], v[80:81], v[138:139] op_sel_hi:[1,0]
	v_mul_f32_e32 v98, 0xbfb8aa3b, v78
	v_mul_f32_e32 v99, 0xbfb8aa3b, v79
	v_mul_f32_e32 v100, 0xbfb8aa3b, v80
	v_mul_f32_e32 v101, 0xbfb8aa3b, v81
	v_exp_f32_e32 v98, v98
	v_exp_f32_e32 v99, v99
	v_exp_f32_e32 v100, v100
	v_exp_f32_e32 v101, v101
	v_pk_mul_f32 v[84:85], v[84:85], v[138:139] op_sel_hi:[1,0]
	v_pk_mul_f32 v[86:87], v[86:87], v[138:139] op_sel_hi:[1,0]
	v_pk_add_f32 v[98:99], v[98:99], 1.0 op_sel_hi:[1,0]
	v_pk_add_f32 v[100:101], v[100:101], 1.0 op_sel_hi:[1,0]
	v_rcp_f32_e32 v98, v98
	v_rcp_f32_e32 v99, v99
	v_rcp_f32_e32 v100, v100
	v_rcp_f32_e32 v101, v101
	s_nop 0
	v_pk_mul_f32 v[78:79], v[78:79], v[98:99]
	v_pk_mul_f32 v[80:81], v[80:81], v[100:101]
	v_pk_mul_f32 v[78:79], v[84:85], v[78:79]
	v_pk_mul_f32 v[80:81], v[86:87], v[80:81]
	v_cvt_pk_bf16_f32 v98, v78, v79
	v_cvt_pk_bf16_f32 v99, v80, v81
	global_store_dwordx2 v[68:69], v[98:99], off
	v_lshl_add_u64 v[68:69], v[68:69], 0, s[98:99]
	ds_read_b128 v[78:81], v82 offset:49920
	ds_read_b128 v[84:87], v82 offset:49984
	s_waitcnt lgkmcnt(2)
	v_pk_mul_f32 v[70:71], v[70:71], v[144:145] op_sel_hi:[1,0]
	v_pk_mul_f32 v[72:73], v[72:73], v[144:145] op_sel_hi:[1,0]
	v_mul_f32_e32 v98, 0xbfb8aa3b, v70
	v_mul_f32_e32 v99, 0xbfb8aa3b, v71
	v_mul_f32_e32 v100, 0xbfb8aa3b, v72
	v_mul_f32_e32 v101, 0xbfb8aa3b, v73
	v_exp_f32_e32 v98, v98
	v_exp_f32_e32 v99, v99
	v_exp_f32_e32 v100, v100
	v_exp_f32_e32 v101, v101
	v_pk_mul_f32 v[74:75], v[74:75], v[144:145] op_sel_hi:[1,0]
	v_pk_mul_f32 v[76:77], v[76:77], v[144:145] op_sel_hi:[1,0]
	v_pk_add_f32 v[98:99], v[98:99], 1.0 op_sel_hi:[1,0]
	v_pk_add_f32 v[100:101], v[100:101], 1.0 op_sel_hi:[1,0]
	v_rcp_f32_e32 v98, v98
	v_rcp_f32_e32 v99, v99
	v_rcp_f32_e32 v100, v100
	v_rcp_f32_e32 v101, v101
	s_nop 0
	v_pk_mul_f32 v[70:71], v[70:71], v[98:99]
	v_pk_mul_f32 v[72:73], v[72:73], v[100:101]
	v_pk_mul_f32 v[70:71], v[74:75], v[70:71]
	v_pk_mul_f32 v[72:73], v[76:77], v[72:73]
	v_cvt_pk_bf16_f32 v98, v70, v71
	v_cvt_pk_bf16_f32 v99, v72, v73
	global_store_dwordx2 v[68:69], v[98:99], off
	v_lshl_add_u64 v[68:69], v[68:69], 0, s[98:99]
	ds_read_b128 v[70:73], v0
	ds_read_b128 v[74:77], v0 offset:64
	s_waitcnt lgkmcnt(2)
	v_pk_mul_f32 v[78:79], v[78:79], v[148:149] op_sel_hi:[1,0]
	v_pk_mul_f32 v[80:81], v[80:81], v[148:149] op_sel_hi:[1,0]
	v_mul_f32_e32 v98, 0xbfb8aa3b, v78
	v_mul_f32_e32 v99, 0xbfb8aa3b, v79
	v_mul_f32_e32 v100, 0xbfb8aa3b, v80
	v_mul_f32_e32 v101, 0xbfb8aa3b, v81
	v_exp_f32_e32 v98, v98
	v_exp_f32_e32 v99, v99
	v_exp_f32_e32 v100, v100
	v_exp_f32_e32 v101, v101
	v_pk_mul_f32 v[84:85], v[84:85], v[148:149] op_sel_hi:[1,0]
	v_pk_mul_f32 v[86:87], v[86:87], v[148:149] op_sel_hi:[1,0]
	v_pk_add_f32 v[98:99], v[98:99], 1.0 op_sel_hi:[1,0]
	v_pk_add_f32 v[100:101], v[100:101], 1.0 op_sel_hi:[1,0]
	v_rcp_f32_e32 v98, v98
	v_rcp_f32_e32 v99, v99
	v_rcp_f32_e32 v100, v100
	v_rcp_f32_e32 v101, v101
	s_nop 0
	v_pk_mul_f32 v[78:79], v[78:79], v[98:99]
	v_pk_mul_f32 v[80:81], v[80:81], v[100:101]
	v_pk_mul_f32 v[78:79], v[84:85], v[78:79]
	v_pk_mul_f32 v[80:81], v[86:87], v[80:81]
	v_cvt_pk_bf16_f32 v98, v78, v79
	v_cvt_pk_bf16_f32 v99, v80, v81
	global_store_dwordx2 v[68:69], v[98:99], off
	v_lshl_add_u64 v[68:69], v[68:69], 0, s[98:99]
	ds_read_b128 v[78:81], v0 offset:16640
	ds_read_b128 v[84:87], v0 offset:16704
	s_waitcnt lgkmcnt(2)
	v_pk_mul_f32 v[70:71], v[70:71], v[152:153] op_sel_hi:[1,0]
	v_pk_mul_f32 v[72:73], v[72:73], v[152:153] op_sel_hi:[1,0]
	v_mul_f32_e32 v98, 0xbfb8aa3b, v70
	v_mul_f32_e32 v99, 0xbfb8aa3b, v71
	v_mul_f32_e32 v100, 0xbfb8aa3b, v72
	v_mul_f32_e32 v101, 0xbfb8aa3b, v73
	v_exp_f32_e32 v98, v98
	v_exp_f32_e32 v99, v99
	v_exp_f32_e32 v100, v100
	v_exp_f32_e32 v101, v101
	v_pk_mul_f32 v[74:75], v[74:75], v[152:153] op_sel_hi:[1,0]
	v_pk_mul_f32 v[76:77], v[76:77], v[152:153] op_sel_hi:[1,0]
	v_pk_add_f32 v[98:99], v[98:99], 1.0 op_sel_hi:[1,0]
	v_pk_add_f32 v[100:101], v[100:101], 1.0 op_sel_hi:[1,0]
	v_rcp_f32_e32 v98, v98
	v_rcp_f32_e32 v99, v99
	v_rcp_f32_e32 v100, v100
	v_rcp_f32_e32 v101, v101
	s_nop 0
	v_pk_mul_f32 v[70:71], v[70:71], v[98:99]
	v_pk_mul_f32 v[72:73], v[72:73], v[100:101]
	v_pk_mul_f32 v[70:71], v[74:75], v[70:71]
	v_pk_mul_f32 v[72:73], v[76:77], v[72:73]
	v_cvt_pk_bf16_f32 v98, v70, v71
	v_cvt_pk_bf16_f32 v99, v72, v73
	global_store_dwordx2 v[68:69], v[98:99], off
	v_lshl_add_u64 v[68:69], v[68:69], 0, s[98:99]
	ds_read_b128 v[70:73], v0 offset:33280
	ds_read_b128 v[74:77], v0 offset:33344
	s_waitcnt lgkmcnt(2)
	v_pk_mul_f32 v[78:79], v[78:79], v[156:157] op_sel_hi:[1,0]
	v_pk_mul_f32 v[80:81], v[80:81], v[156:157] op_sel_hi:[1,0]
	v_mul_f32_e32 v98, 0xbfb8aa3b, v78
	v_mul_f32_e32 v99, 0xbfb8aa3b, v79
	v_mul_f32_e32 v100, 0xbfb8aa3b, v80
	v_mul_f32_e32 v101, 0xbfb8aa3b, v81
	v_exp_f32_e32 v98, v98
	v_exp_f32_e32 v99, v99
	v_exp_f32_e32 v100, v100
	v_exp_f32_e32 v101, v101
	v_pk_mul_f32 v[84:85], v[84:85], v[156:157] op_sel_hi:[1,0]
	v_pk_mul_f32 v[86:87], v[86:87], v[156:157] op_sel_hi:[1,0]
	v_pk_add_f32 v[98:99], v[98:99], 1.0 op_sel_hi:[1,0]
	v_pk_add_f32 v[100:101], v[100:101], 1.0 op_sel_hi:[1,0]
	v_rcp_f32_e32 v98, v98
	v_rcp_f32_e32 v99, v99
	v_rcp_f32_e32 v100, v100
	v_rcp_f32_e32 v101, v101
	s_nop 0
	v_pk_mul_f32 v[78:79], v[78:79], v[98:99]
	v_pk_mul_f32 v[80:81], v[80:81], v[100:101]
	v_pk_mul_f32 v[78:79], v[84:85], v[78:79]
	v_pk_mul_f32 v[80:81], v[86:87], v[80:81]
	v_cvt_pk_bf16_f32 v98, v78, v79
	v_cvt_pk_bf16_f32 v99, v80, v81
	global_store_dwordx2 v[68:69], v[98:99], off
	v_lshl_add_u64 v[68:69], v[68:69], 0, s[98:99]
	ds_read_b128 v[78:81], v0 offset:49920
	ds_read_b128 v[84:87], v0 offset:49984
	s_waitcnt lgkmcnt(2)
	v_pk_mul_f32 v[70:71], v[70:71], v[160:161] op_sel_hi:[1,0]
	v_pk_mul_f32 v[72:73], v[72:73], v[160:161] op_sel_hi:[1,0]
	v_mul_f32_e32 v98, 0xbfb8aa3b, v70
	v_mul_f32_e32 v99, 0xbfb8aa3b, v71
	v_mul_f32_e32 v100, 0xbfb8aa3b, v72
	v_mul_f32_e32 v101, 0xbfb8aa3b, v73
	v_exp_f32_e32 v98, v98
	v_exp_f32_e32 v99, v99
	v_exp_f32_e32 v100, v100
	v_exp_f32_e32 v101, v101
	v_pk_mul_f32 v[74:75], v[74:75], v[160:161] op_sel_hi:[1,0]
	v_pk_mul_f32 v[76:77], v[76:77], v[160:161] op_sel_hi:[1,0]
	v_pk_add_f32 v[98:99], v[98:99], 1.0 op_sel_hi:[1,0]
	v_pk_add_f32 v[100:101], v[100:101], 1.0 op_sel_hi:[1,0]
	v_rcp_f32_e32 v98, v98
	v_rcp_f32_e32 v99, v99
	v_rcp_f32_e32 v100, v100
	v_rcp_f32_e32 v101, v101
	s_nop 0
	v_pk_mul_f32 v[70:71], v[70:71], v[98:99]
	v_pk_mul_f32 v[72:73], v[72:73], v[100:101]
	v_pk_mul_f32 v[70:71], v[74:75], v[70:71]
	v_pk_mul_f32 v[72:73], v[76:77], v[72:73]
	v_cvt_pk_bf16_f32 v98, v70, v71
	v_cvt_pk_bf16_f32 v99, v72, v73
	global_store_dwordx2 v[68:69], v[98:99], off
	v_lshl_add_u64 v[68:69], v[68:69], 0, s[98:99]
	s_waitcnt lgkmcnt(0)
	v_pk_mul_f32 v[78:79], v[78:79], v[164:165] op_sel_hi:[1,0]
	v_pk_mul_f32 v[80:81], v[80:81], v[164:165] op_sel_hi:[1,0]
	v_mul_f32_e32 v98, 0xbfb8aa3b, v78
	v_mul_f32_e32 v99, 0xbfb8aa3b, v79
	v_mul_f32_e32 v100, 0xbfb8aa3b, v80
	v_mul_f32_e32 v101, 0xbfb8aa3b, v81
	v_exp_f32_e32 v98, v98
	v_exp_f32_e32 v99, v99
	v_exp_f32_e32 v100, v100
	v_exp_f32_e32 v101, v101
	v_pk_mul_f32 v[84:85], v[84:85], v[164:165] op_sel_hi:[1,0]
	v_pk_mul_f32 v[86:87], v[86:87], v[164:165] op_sel_hi:[1,0]
	v_pk_add_f32 v[98:99], v[98:99], 1.0 op_sel_hi:[1,0]
	v_pk_add_f32 v[100:101], v[100:101], 1.0 op_sel_hi:[1,0]
	v_rcp_f32_e32 v98, v98
	v_rcp_f32_e32 v99, v99
	v_rcp_f32_e32 v100, v100
	v_rcp_f32_e32 v101, v101
	s_nop 0
	v_pk_mul_f32 v[78:79], v[78:79], v[98:99]
	v_pk_mul_f32 v[80:81], v[80:81], v[100:101]
	v_pk_mul_f32 v[78:79], v[84:85], v[78:79]
	v_pk_mul_f32 v[80:81], v[86:87], v[80:81]
	v_cvt_pk_bf16_f32 v98, v78, v79
	v_cvt_pk_bf16_f32 v99, v80, v81
	global_store_dwordx2 v[68:69], v[98:99], off
	v_mov_b32_e32 v142, v201
	s_barrier
	ds_write2_b32 v130, v2, v18 offset1:16
	ds_write2_b32 v114, v3, v19 offset0:4 offset1:20
	ds_write2_b32 v115, v4, v20 offset0:8 offset1:24
	ds_write2_b32 v116, v5, v21 offset0:12 offset1:28
	ds_write2_b32 v117, v6, v22 offset0:64 offset1:80
	ds_write2_b32 v94, v7, v23 offset0:68 offset1:84
	ds_write2_b32 v95, v8, v24 offset0:72 offset1:88
	ds_write2_b32 v96, v9, v25 offset0:76 offset1:92
	ds_write2_b32 v132, v10, v26 offset0:128 offset1:144
	ds_write2_b32 v97, v11, v27 offset0:132 offset1:148
	ds_write2_b32 v126, v12, v28 offset0:136 offset1:152
	ds_write2_b32 v127, v13, v29 offset0:140 offset1:156
	ds_write2_b32 v133, v14, v30 offset0:192 offset1:208
	ds_write2_b32 v128, v15, v31 offset0:196 offset1:212
	ds_write2_b32 v129, v16, v32 offset0:200 offset1:216
	ds_write2_b32 v131, v17, v33 offset0:204 offset1:220
	ds_write2_b32 v130, v34, v50 offset0:128 offset1:144
	ds_write2_b32 v114, v35, v51 offset0:132 offset1:148
	ds_write2_b32 v115, v36, v52 offset0:136 offset1:152
	ds_write2_b32 v116, v37, v53 offset0:140 offset1:156
	ds_write2_b32 v117, v38, v54 offset0:192 offset1:208
	ds_write2_b32 v94, v39, v55 offset0:196 offset1:212
	ds_write2_b32 v95, v40, v56 offset0:200 offset1:216
	ds_write2_b32 v96, v41, v57 offset0:204 offset1:220
	ds_write2_b32 v97, v42, v58 offset1:16
	ds_write2_b32 v126, v43, v59 offset0:4 offset1:20
	ds_write2_b32 v127, v44, v60 offset0:8 offset1:24
	ds_write2_b32 v90, v45, v61 offset0:12 offset1:28
	ds_write2_b32 v128, v46, v62 offset0:64 offset1:80
	ds_write2_b32 v129, v47, v63 offset0:68 offset1:84
	ds_write2_b32 v131, v48, v64 offset0:72 offset1:88
	ds_write2_b32 v91, v49, v65 offset0:76 offset1:92
	v_add_u32_e32 v2, s10, v88
	v_ashrrev_i32_e32 v3, 31, v2
	v_lshl_add_u64 v[4:5], v[2:3], 4, s[40:41]
	s_waitcnt lgkmcnt(0)
	s_barrier
	global_load_dwordx4 v[134:137], v[4:5], off
	global_load_dwordx4 v[138:141], v[4:5], off offset:256
	global_load_dwordx4 v[144:147], v[4:5], off offset:512
	global_load_dwordx4 v[148:151], v[4:5], off offset:768
	global_load_dwordx4 v[152:155], v[4:5], off offset:1024
	global_load_dwordx4 v[156:159], v[4:5], off offset:1280
	global_load_dwordx4 v[160:163], v[4:5], off offset:1536
	global_load_dwordx4 v[164:167], v[4:5], off offset:1792
	s_waitcnt vmcnt(0)
	v_mad_i64_i32 v[2:3], s[36:37], v2, s21, v[66:67]
	ds_read_b128 v[4:7], v82
	ds_read_b128 v[8:11], v82 offset:64
	v_add_u32_e32 v0, 0x10400, v82
	s_lshl_b32 s98, s21, 4
	s_mov_b32 s99, 0
	v_add_f32_e32 v134, v134, v135
	v_add_f32_e32 v134, v134, v136
	v_add_f32_e32 v134, v134, v137
	v_fmamk_f32 v134, v134, 0x3a800000, v200
	v_rsq_f32_e32 v134, v134
	v_add_f32_e32 v138, v138, v139
	v_add_f32_e32 v138, v138, v140
	v_add_f32_e32 v138, v138, v141
	v_fmamk_f32 v138, v138, 0x3a800000, v200
	v_rsq_f32_e32 v138, v138
	v_add_f32_e32 v144, v144, v145
	v_add_f32_e32 v144, v144, v146
	v_add_f32_e32 v144, v144, v147
	v_fmamk_f32 v144, v144, 0x3a800000, v200
	v_rsq_f32_e32 v144, v144
	v_add_f32_e32 v148, v148, v149
	v_add_f32_e32 v148, v148, v150
	v_add_f32_e32 v148, v148, v151
	v_fmamk_f32 v148, v148, 0x3a800000, v200
	v_rsq_f32_e32 v148, v148
	v_add_f32_e32 v152, v152, v153
	v_add_f32_e32 v152, v152, v154
	v_add_f32_e32 v152, v152, v155
	v_fmamk_f32 v152, v152, 0x3a800000, v200
	v_rsq_f32_e32 v152, v152
	v_add_f32_e32 v156, v156, v157
	v_add_f32_e32 v156, v156, v158
	v_add_f32_e32 v156, v156, v159
	v_fmamk_f32 v156, v156, 0x3a800000, v200
	v_rsq_f32_e32 v156, v156
	v_add_f32_e32 v160, v160, v161
	v_add_f32_e32 v160, v160, v162
	v_add_f32_e32 v160, v160, v163
	v_fmamk_f32 v160, v160, 0x3a800000, v200
	v_rsq_f32_e32 v160, v160
	v_add_f32_e32 v164, v164, v165
	v_add_f32_e32 v164, v164, v166
	v_add_f32_e32 v164, v164, v167
	v_fmamk_f32 v164, v164, 0x3a800000, v200
	v_rsq_f32_e32 v164, v164
	ds_read_b128 v[12:15], v82 offset:16640
	ds_read_b128 v[16:19], v82 offset:16704
	s_waitcnt lgkmcnt(2)
	v_pk_mul_f32 v[4:5], v[4:5], v[134:135] op_sel_hi:[1,0]
	v_pk_mul_f32 v[6:7], v[6:7], v[134:135] op_sel_hi:[1,0]
	v_mul_f32_e32 v20, 0xbfb8aa3b, v4
	v_mul_f32_e32 v21, 0xbfb8aa3b, v5
	v_mul_f32_e32 v22, 0xbfb8aa3b, v6
	v_mul_f32_e32 v23, 0xbfb8aa3b, v7
	v_exp_f32_e32 v20, v20
	v_exp_f32_e32 v21, v21
	v_exp_f32_e32 v22, v22
	v_exp_f32_e32 v23, v23
	v_pk_mul_f32 v[8:9], v[8:9], v[134:135] op_sel_hi:[1,0]
	v_pk_mul_f32 v[10:11], v[10:11], v[134:135] op_sel_hi:[1,0]
	v_pk_add_f32 v[20:21], v[20:21], 1.0 op_sel_hi:[1,0]
	v_pk_add_f32 v[22:23], v[22:23], 1.0 op_sel_hi:[1,0]
	v_rcp_f32_e32 v20, v20
	v_rcp_f32_e32 v21, v21
	v_rcp_f32_e32 v22, v22
	v_rcp_f32_e32 v23, v23
	s_nop 0
	v_pk_mul_f32 v[4:5], v[4:5], v[20:21]
	v_pk_mul_f32 v[6:7], v[6:7], v[22:23]
	v_pk_mul_f32 v[4:5], v[8:9], v[4:5]
	v_pk_mul_f32 v[6:7], v[10:11], v[6:7]
	v_cvt_pk_bf16_f32 v20, v4, v5
	v_cvt_pk_bf16_f32 v21, v6, v7
	global_store_dwordx2 v[2:3], v[20:21], off
	v_lshl_add_u64 v[2:3], v[2:3], 0, s[98:99]
	ds_read_b128 v[4:7], v82 offset:33280
	ds_read_b128 v[8:11], v82 offset:33344
	s_waitcnt lgkmcnt(2)
	v_pk_mul_f32 v[12:13], v[12:13], v[138:139] op_sel_hi:[1,0]
	v_pk_mul_f32 v[14:15], v[14:15], v[138:139] op_sel_hi:[1,0]
	v_mul_f32_e32 v20, 0xbfb8aa3b, v12
	v_mul_f32_e32 v21, 0xbfb8aa3b, v13
	v_mul_f32_e32 v22, 0xbfb8aa3b, v14
	v_mul_f32_e32 v23, 0xbfb8aa3b, v15
	v_exp_f32_e32 v20, v20
	v_exp_f32_e32 v21, v21
	v_exp_f32_e32 v22, v22
	v_exp_f32_e32 v23, v23
	v_pk_mul_f32 v[16:17], v[16:17], v[138:139] op_sel_hi:[1,0]
	v_pk_mul_f32 v[18:19], v[18:19], v[138:139] op_sel_hi:[1,0]
	v_pk_add_f32 v[20:21], v[20:21], 1.0 op_sel_hi:[1,0]
	v_pk_add_f32 v[22:23], v[22:23], 1.0 op_sel_hi:[1,0]
	v_rcp_f32_e32 v20, v20
	v_rcp_f32_e32 v21, v21
	v_rcp_f32_e32 v22, v22
	v_rcp_f32_e32 v23, v23
	s_nop 0
	v_pk_mul_f32 v[12:13], v[12:13], v[20:21]
	v_pk_mul_f32 v[14:15], v[14:15], v[22:23]
	v_pk_mul_f32 v[12:13], v[16:17], v[12:13]
	v_pk_mul_f32 v[14:15], v[18:19], v[14:15]
	v_cvt_pk_bf16_f32 v20, v12, v13
	v_cvt_pk_bf16_f32 v21, v14, v15
	global_store_dwordx2 v[2:3], v[20:21], off
	v_lshl_add_u64 v[2:3], v[2:3], 0, s[98:99]
	ds_read_b128 v[12:15], v82 offset:49920
	ds_read_b128 v[16:19], v82 offset:49984
	s_waitcnt lgkmcnt(2)
	v_pk_mul_f32 v[4:5], v[4:5], v[144:145] op_sel_hi:[1,0]
	v_pk_mul_f32 v[6:7], v[6:7], v[144:145] op_sel_hi:[1,0]
	v_mul_f32_e32 v20, 0xbfb8aa3b, v4
	v_mul_f32_e32 v21, 0xbfb8aa3b, v5
	v_mul_f32_e32 v22, 0xbfb8aa3b, v6
	v_mul_f32_e32 v23, 0xbfb8aa3b, v7
	v_exp_f32_e32 v20, v20
	v_exp_f32_e32 v21, v21
	v_exp_f32_e32 v22, v22
	v_exp_f32_e32 v23, v23
	v_pk_mul_f32 v[8:9], v[8:9], v[144:145] op_sel_hi:[1,0]
	v_pk_mul_f32 v[10:11], v[10:11], v[144:145] op_sel_hi:[1,0]
	v_pk_add_f32 v[20:21], v[20:21], 1.0 op_sel_hi:[1,0]
	v_pk_add_f32 v[22:23], v[22:23], 1.0 op_sel_hi:[1,0]
	v_rcp_f32_e32 v20, v20
	v_rcp_f32_e32 v21, v21
	v_rcp_f32_e32 v22, v22
	v_rcp_f32_e32 v23, v23
	s_nop 0
	v_pk_mul_f32 v[4:5], v[4:5], v[20:21]
	v_pk_mul_f32 v[6:7], v[6:7], v[22:23]
	v_pk_mul_f32 v[4:5], v[8:9], v[4:5]
	v_pk_mul_f32 v[6:7], v[10:11], v[6:7]
	v_cvt_pk_bf16_f32 v20, v4, v5
	v_cvt_pk_bf16_f32 v21, v6, v7
	global_store_dwordx2 v[2:3], v[20:21], off
	v_lshl_add_u64 v[2:3], v[2:3], 0, s[98:99]
	ds_read_b128 v[4:7], v0
	ds_read_b128 v[8:11], v0 offset:64
	s_waitcnt lgkmcnt(2)
	v_pk_mul_f32 v[12:13], v[12:13], v[148:149] op_sel_hi:[1,0]
	v_pk_mul_f32 v[14:15], v[14:15], v[148:149] op_sel_hi:[1,0]
	v_mul_f32_e32 v20, 0xbfb8aa3b, v12
	v_mul_f32_e32 v21, 0xbfb8aa3b, v13
	v_mul_f32_e32 v22, 0xbfb8aa3b, v14
	v_mul_f32_e32 v23, 0xbfb8aa3b, v15
	v_exp_f32_e32 v20, v20
	v_exp_f32_e32 v21, v21
	v_exp_f32_e32 v22, v22
	v_exp_f32_e32 v23, v23
	v_pk_mul_f32 v[16:17], v[16:17], v[148:149] op_sel_hi:[1,0]
	v_pk_mul_f32 v[18:19], v[18:19], v[148:149] op_sel_hi:[1,0]
	v_pk_add_f32 v[20:21], v[20:21], 1.0 op_sel_hi:[1,0]
	v_pk_add_f32 v[22:23], v[22:23], 1.0 op_sel_hi:[1,0]
	v_rcp_f32_e32 v20, v20
	v_rcp_f32_e32 v21, v21
	v_rcp_f32_e32 v22, v22
	v_rcp_f32_e32 v23, v23
	s_nop 0
	v_pk_mul_f32 v[12:13], v[12:13], v[20:21]
	v_pk_mul_f32 v[14:15], v[14:15], v[22:23]
	v_pk_mul_f32 v[12:13], v[16:17], v[12:13]
	v_pk_mul_f32 v[14:15], v[18:19], v[14:15]
	v_cvt_pk_bf16_f32 v20, v12, v13
	v_cvt_pk_bf16_f32 v21, v14, v15
	global_store_dwordx2 v[2:3], v[20:21], off
	v_lshl_add_u64 v[2:3], v[2:3], 0, s[98:99]
	ds_read_b128 v[12:15], v0 offset:16640
	ds_read_b128 v[16:19], v0 offset:16704
	s_waitcnt lgkmcnt(2)
	v_pk_mul_f32 v[4:5], v[4:5], v[152:153] op_sel_hi:[1,0]
	v_pk_mul_f32 v[6:7], v[6:7], v[152:153] op_sel_hi:[1,0]
	v_mul_f32_e32 v20, 0xbfb8aa3b, v4
	v_mul_f32_e32 v21, 0xbfb8aa3b, v5
	v_mul_f32_e32 v22, 0xbfb8aa3b, v6
	v_mul_f32_e32 v23, 0xbfb8aa3b, v7
	v_exp_f32_e32 v20, v20
	v_exp_f32_e32 v21, v21
	v_exp_f32_e32 v22, v22
	v_exp_f32_e32 v23, v23
	v_pk_mul_f32 v[8:9], v[8:9], v[152:153] op_sel_hi:[1,0]
	v_pk_mul_f32 v[10:11], v[10:11], v[152:153] op_sel_hi:[1,0]
	v_pk_add_f32 v[20:21], v[20:21], 1.0 op_sel_hi:[1,0]
	v_pk_add_f32 v[22:23], v[22:23], 1.0 op_sel_hi:[1,0]
	v_rcp_f32_e32 v20, v20
	v_rcp_f32_e32 v21, v21
	v_rcp_f32_e32 v22, v22
	v_rcp_f32_e32 v23, v23
	s_nop 0
	v_pk_mul_f32 v[4:5], v[4:5], v[20:21]
	v_pk_mul_f32 v[6:7], v[6:7], v[22:23]
	v_pk_mul_f32 v[4:5], v[8:9], v[4:5]
	v_pk_mul_f32 v[6:7], v[10:11], v[6:7]
	v_cvt_pk_bf16_f32 v20, v4, v5
	v_cvt_pk_bf16_f32 v21, v6, v7
	global_store_dwordx2 v[2:3], v[20:21], off
	v_lshl_add_u64 v[2:3], v[2:3], 0, s[98:99]
	ds_read_b128 v[4:7], v0 offset:33280
	ds_read_b128 v[8:11], v0 offset:33344
	s_waitcnt lgkmcnt(2)
	v_pk_mul_f32 v[12:13], v[12:13], v[156:157] op_sel_hi:[1,0]
	v_pk_mul_f32 v[14:15], v[14:15], v[156:157] op_sel_hi:[1,0]
	v_mul_f32_e32 v20, 0xbfb8aa3b, v12
	v_mul_f32_e32 v21, 0xbfb8aa3b, v13
	v_mul_f32_e32 v22, 0xbfb8aa3b, v14
	v_mul_f32_e32 v23, 0xbfb8aa3b, v15
	v_exp_f32_e32 v20, v20
	v_exp_f32_e32 v21, v21
	v_exp_f32_e32 v22, v22
	v_exp_f32_e32 v23, v23
	v_pk_mul_f32 v[16:17], v[16:17], v[156:157] op_sel_hi:[1,0]
	v_pk_mul_f32 v[18:19], v[18:19], v[156:157] op_sel_hi:[1,0]
	v_pk_add_f32 v[20:21], v[20:21], 1.0 op_sel_hi:[1,0]
	v_pk_add_f32 v[22:23], v[22:23], 1.0 op_sel_hi:[1,0]
	v_rcp_f32_e32 v20, v20
	v_rcp_f32_e32 v21, v21
	v_rcp_f32_e32 v22, v22
	v_rcp_f32_e32 v23, v23
	s_nop 0
	v_pk_mul_f32 v[12:13], v[12:13], v[20:21]
	v_pk_mul_f32 v[14:15], v[14:15], v[22:23]
	v_pk_mul_f32 v[12:13], v[16:17], v[12:13]
	v_pk_mul_f32 v[14:15], v[18:19], v[14:15]
	v_cvt_pk_bf16_f32 v20, v12, v13
	v_cvt_pk_bf16_f32 v21, v14, v15
	global_store_dwordx2 v[2:3], v[20:21], off
	v_lshl_add_u64 v[2:3], v[2:3], 0, s[98:99]
	ds_read_b128 v[12:15], v0 offset:49920
	ds_read_b128 v[16:19], v0 offset:49984
	s_waitcnt lgkmcnt(2)
	v_pk_mul_f32 v[4:5], v[4:5], v[160:161] op_sel_hi:[1,0]
	v_pk_mul_f32 v[6:7], v[6:7], v[160:161] op_sel_hi:[1,0]
	v_mul_f32_e32 v20, 0xbfb8aa3b, v4
	v_mul_f32_e32 v21, 0xbfb8aa3b, v5
	v_mul_f32_e32 v22, 0xbfb8aa3b, v6
	v_mul_f32_e32 v23, 0xbfb8aa3b, v7
	v_exp_f32_e32 v20, v20
	v_exp_f32_e32 v21, v21
	v_exp_f32_e32 v22, v22
	v_exp_f32_e32 v23, v23
	v_pk_mul_f32 v[8:9], v[8:9], v[160:161] op_sel_hi:[1,0]
	v_pk_mul_f32 v[10:11], v[10:11], v[160:161] op_sel_hi:[1,0]
	v_pk_add_f32 v[20:21], v[20:21], 1.0 op_sel_hi:[1,0]
	v_pk_add_f32 v[22:23], v[22:23], 1.0 op_sel_hi:[1,0]
	v_rcp_f32_e32 v20, v20
	v_rcp_f32_e32 v21, v21
	v_rcp_f32_e32 v22, v22
	v_rcp_f32_e32 v23, v23
	s_nop 0
	v_pk_mul_f32 v[4:5], v[4:5], v[20:21]
	v_pk_mul_f32 v[6:7], v[6:7], v[22:23]
	v_pk_mul_f32 v[4:5], v[8:9], v[4:5]
	v_pk_mul_f32 v[6:7], v[10:11], v[6:7]
	v_cvt_pk_bf16_f32 v20, v4, v5
	v_cvt_pk_bf16_f32 v21, v6, v7
	global_store_dwordx2 v[2:3], v[20:21], off
	v_lshl_add_u64 v[2:3], v[2:3], 0, s[98:99]
	s_waitcnt lgkmcnt(0)
	v_pk_mul_f32 v[12:13], v[12:13], v[164:165] op_sel_hi:[1,0]
	v_pk_mul_f32 v[14:15], v[14:15], v[164:165] op_sel_hi:[1,0]
	v_mul_f32_e32 v20, 0xbfb8aa3b, v12
	v_mul_f32_e32 v21, 0xbfb8aa3b, v13
	v_mul_f32_e32 v22, 0xbfb8aa3b, v14
	v_mul_f32_e32 v23, 0xbfb8aa3b, v15
	v_exp_f32_e32 v20, v20
	v_exp_f32_e32 v21, v21
	v_exp_f32_e32 v22, v22
	v_exp_f32_e32 v23, v23
	v_pk_mul_f32 v[16:17], v[16:17], v[164:165] op_sel_hi:[1,0]
	v_pk_mul_f32 v[18:19], v[18:19], v[164:165] op_sel_hi:[1,0]
	v_pk_add_f32 v[20:21], v[20:21], 1.0 op_sel_hi:[1,0]
	v_pk_add_f32 v[22:23], v[22:23], 1.0 op_sel_hi:[1,0]
	v_rcp_f32_e32 v20, v20
	v_rcp_f32_e32 v21, v21
	v_rcp_f32_e32 v22, v22
	v_rcp_f32_e32 v23, v23
	s_nop 0
	v_pk_mul_f32 v[12:13], v[12:13], v[20:21]
	v_pk_mul_f32 v[14:15], v[14:15], v[22:23]
	v_pk_mul_f32 v[12:13], v[16:17], v[12:13]
	v_pk_mul_f32 v[14:15], v[18:19], v[14:15]
	v_cvt_pk_bf16_f32 v20, v12, v13
	v_cvt_pk_bf16_f32 v21, v14, v15
	global_store_dwordx2 v[2:3], v[20:21], off
	v_readlane_b32 s20, v255, 9
	s_barrier
	v_readlane_b32 s21, v255, 15
	v_ashrrev_i32_e32 v0, 31, v142
	v_lshrrev_b32_e32 v0, 26, v0
	v_add_u32_e32 v0, v142, v0
	v_ashrrev_i32_e32 v16, 6, v0
	v_bfe_i32 v0, v142, 27, 1
	v_lshlrev_b32_e32 v2, 4, v142
	v_lshrrev_b32_e32 v0, 22, v0
	v_add_u32_e32 v0, v2, v0
	v_and_b32_e32 v0, 0xfffffc00, v0
	v_sub_u32_e32 v0, v2, v0
	v_lshrrev_b32_e32 v3, 4, v0
	v_bitop3_b32 v3, v3, v0, 32 bitop3:0x6c
	v_ashrrev_i32_e32 v0, 31, v0
	v_lshrrev_b32_e32 v0, 26, v0
	v_add_u32_e32 v0, v3, v0
	v_ashrrev_i32_e32 v18, 6, v0
	v_mul_i32_i24_e32 v5, 64, v18
	v_sub_u32_e32 v3, v3, v5
	v_lshlrev_b32_e32 v4, 3, v16
	v_lshlrev_b32_e32 v0, 5, v16
	v_ashrrev_i16_sdwa v3, v217, sext(v3) dst_sel:DWORD dst_unused:UNUSED_PAD src0_sel:DWORD src1_sel:BYTE_0
	v_and_b32_e32 v4, 0x1ffff0, v4
	v_and_b32_e32 v0, 32, v0
	v_bfe_i32 v19, v3, 0, 16
	v_add_u32_e32 v0, v0, v19
	v_add_lshl_u32 v3, v18, v4, 11
	v_add_u32_e32 v2, 0x2000, v2
	v_lshl_add_u32 v0, v0, 1, v3
	v_ashrrev_i32_e32 v3, 31, v2
	v_lshrrev_b32_e32 v3, 22, v3
	v_add_u32_e32 v3, v2, v3
	v_ashrrev_i32_e32 v21, 10, v3
	v_mul_i32_i24_e32 v3, 0x400, v21
	v_sub_u32_e32 v2, v2, v3
	v_lshrrev_b32_e32 v3, 4, v2
	v_bitop3_b32 v2, v3, v2, 32 bitop3:0x6c
	v_ashrrev_i32_e32 v4, 31, v2
	v_ashrrev_i32_e32 v20, 6, v142
	v_lshrrev_b32_e32 v4, 26, v4
	v_readfirstlane_b32 s33, v20
	v_add_u32_e32 v4, v2, v4
	s_lshl_b32 s70, s33, 10
	v_ashrrev_i32_e32 v22, 6, v4
	v_and_b32_e32 v4, 0xc0, v4
	v_sub_u32_e32 v2, v2, v4
	s_add_u32 s44, s20, s44
	v_lshlrev_b32_e32 v3, 3, v21
	v_lshlrev_b32_e32 v5, 5, v21
	v_ashrrev_i16_sdwa v2, v217, sext(v2) dst_sel:DWORD dst_unused:UNUSED_PAD src0_sel:DWORD src1_sel:BYTE_0
	s_addc_u32 s45, s21, s45
	s_add_i32 s36, s70, 0
	v_and_b32_e32 v3, 0x1ffff0, v3
	v_and_b32_e32 v5, 32, v5
	v_bfe_i32 v23, v2, 0, 16
	s_add_i32 s37, s36, 0x10000
	v_add_u32_e32 v2, v5, v23
	v_add_lshl_u32 v3, v22, v3, 11
	s_mov_b32 m0, s37
	s_add_i32 s43, s36, 0x12000
	v_lshl_add_u32 v2, v2, 1, v3
	global_load_lds_dwordx4 v0, s[44:45]
	v_mov_b32_e32 v3, v1
	s_mov_b32 m0, s43
	v_lshl_add_u64 v[4:5], s[44:45], 0, v[0:1]
	v_lshl_add_u64 v[8:9], s[44:45], 0, v[2:3]
	global_load_lds_dwordx4 v2, s[44:45]
	s_mov_b32 m0, s36
	s_add_i32 s44, s36, 0x2000
	global_load_lds_dwordx4 v0, s[22:23]
	s_mov_b32 m0, s44
	v_lshl_add_u64 v[10:11], s[22:23], 0, v[0:1]
	v_lshl_add_u64 v[6:7], s[22:23], 0, v[2:3]
	global_load_lds_dwordx4 v2, s[22:23]
	s_or_b32 s22, s60, 0x180
	s_ashr_i32 s23, s22, 31
	s_lshl_b64 s[22:23], s[22:23], 11
	s_add_u32 s22, s20, s22
	s_addc_u32 s23, s21, s23
	s_add_i32 s45, s36, 0x14000
	s_mov_b32 m0, s45
	s_add_i32 s57, s36, 0x16000
	global_load_lds_dwordx4 v0, s[22:23]
	s_mov_b32 m0, s57
	s_add_i32 s60, s36, 0x4000
	global_load_lds_dwordx4 v2, s[22:23]
	s_mov_b32 m0, s60
	s_add_i32 s61, s36, 0x6000
	global_load_lds_dwordx4 v0, s[16:17]
	s_mov_b32 m0, s61
	v_ashrrev_i32_e32 v17, 8, v142
	global_load_lds_dwordx4 v2, s[16:17]
	v_lshl_add_u64 v[12:13], s[22:23], 0, v[0:1]
	v_lshl_add_u64 v[14:15], s[22:23], 0, v[2:3]
	v_cmp_eq_u32_e32 vcc, 1, v17
	s_and_saveexec_b64 s[22:23], vcc
	v_readlane_b32 s62, v253, 50
	s_cbranch_execz .LBB0_1080
	s_barrier

.LBB0_1084:
	s_or_b64 exec, exec, s[14:15]
	s_movk_i32 s11, 0x410
	v_lshrrev_b32_e32 v130, 2, v142
	v_lshlrev_b32_e32 v131, 1, v142
	v_and_b32_e32 v0, 15, v142
	v_and_b32_e32 v130, 0xfffffcc, v130
	v_and_b32_e32 v131, 0x180, v131
	v_add_u32_e32 v131, 0, v131
	v_lshlrev_b32_e32 v0, 2, v0
	v_mul_lo_u32 v130, v130, s11
	v_add3_u32 v130, v131, v0, v130
	s_waitcnt vmcnt(0)
	s_barrier
	ds_write2_b32 v130, v114, v126 offset1:16
	v_add_u32_e32 v114, 0x400, v130
	ds_write2_b32 v114, v115, v127 offset0:4 offset1:20
	v_add_u32_e32 v115, 0x800, v130
	ds_write2_b32 v115, v116, v128 offset0:8 offset1:24
	v_add_u32_e32 v116, 0xc00, v130
	ds_write2_b32 v116, v117, v129 offset0:12 offset1:28
	v_add_u32_e32 v117, 0x4000, v130
	ds_write2_b32 v117, v82, v94 offset0:64 offset1:80
	v_add_u32_e32 v94, 0x4400, v130
	ds_write2_b32 v94, v83, v95 offset0:68 offset1:84
	v_add_u32_e32 v95, 0x4800, v130
	ds_write2_b32 v95, v84, v96 offset0:72 offset1:88
	v_add_u32_e32 v96, 0x4c00, v130
	ds_write2_b32 v96, v85, v97 offset0:76 offset1:92
	v_add_u32_e32 v132, 0x8000, v130
	v_add_u32_e32 v97, 0x8400, v130
	v_add_u32_e32 v126, 0x8800, v130
	v_add_u32_e32 v127, 0x8c00, v130
	v_add_u32_e32 v133, 0xc000, v130
	v_add_u32_e32 v128, 0xc400, v130
	v_add_u32_e32 v129, 0xc800, v130
	v_add_u32_e32 v131, 0xcc00, v130
	ds_write2_b32 v132, v74, v78 offset0:128 offset1:144
	ds_write2_b32 v97, v75, v79 offset0:132 offset1:148
	ds_write2_b32 v126, v76, v80 offset0:136 offset1:152
	ds_write2_b32 v127, v77, v81 offset0:140 offset1:156
	ds_write2_b32 v133, v66, v70 offset0:192 offset1:208
	ds_write2_b32 v128, v67, v71 offset0:196 offset1:212
	ds_write2_b32 v129, v68, v72 offset0:200 offset1:216
	ds_write2_b32 v131, v69, v73 offset0:204 offset1:220
	ds_write2_b32 v130, v98, v118 offset0:128 offset1:144
	ds_write2_b32 v114, v99, v119 offset0:132 offset1:148
	ds_write2_b32 v115, v100, v120 offset0:136 offset1:152
	ds_write2_b32 v116, v101, v121 offset0:140 offset1:156
	ds_write2_b32 v117, v102, v122 offset0:192 offset1:208
	ds_write2_b32 v94, v103, v123 offset0:196 offset1:212
	ds_write2_b32 v95, v104, v124 offset0:200 offset1:216
	ds_write2_b32 v96, v105, v125 offset0:204 offset1:220
	ds_write2_b32 v97, v90, v110 offset1:16
	ds_write2_b32 v126, v91, v111 offset0:4 offset1:20
	ds_write2_b32 v127, v92, v112 offset0:8 offset1:24
	v_add_u32_e32 v90, 0x9000, v130
	ds_write2_b32 v90, v93, v113 offset0:12 offset1:28
	ds_write2_b32 v128, v86, v106 offset0:64 offset1:80
	ds_write2_b32 v129, v87, v107 offset0:68 offset1:84
	ds_write2_b32 v131, v88, v108 offset0:72 offset1:88
	v_ashrrev_i32_e32 v88, 5, v142
	v_add_u32_e32 v70, s12, v88
	v_ashrrev_i32_e32 v71, 31, v70
	v_add_u32_e32 v91, 0xd000, v130
	v_lshl_add_u64 v[72:73], v[70:71], 4, s[40:41]
	ds_write2_b32 v91, v89, v109 offset0:76 offset1:92
	s_waitcnt lgkmcnt(0)
	s_barrier
	global_load_dwordx4 v[134:137], v[72:73], off
	global_load_dwordx4 v[138:141], v[72:73], off offset:256
	global_load_dwordx4 v[144:147], v[72:73], off offset:512
	global_load_dwordx4 v[148:151], v[72:73], off offset:768
	global_load_dwordx4 v[152:155], v[72:73], off offset:1024
	global_load_dwordx4 v[156:159], v[72:73], off offset:1280
	global_load_dwordx4 v[160:163], v[72:73], off offset:1536
	global_load_dwordx4 v[164:167], v[72:73], off offset:1792
	v_lshlrev_b32_e32 v0, 3, v142
	v_lshlrev_b32_e32 v66, 2, v142
	v_and_b32_e32 v0, 0xe0, v0
	v_and_b32_e32 v69, 12, v66
	v_lshlrev_b32_e32 v66, 2, v0
	v_lshlrev_b32_e32 v67, 2, v69
	v_or_b32_e32 v0, s42, v0
	v_add3_u32 v68, 0, v66, v67
	v_ashrrev_i32_e32 v66, 1, v0
	v_readlane_b32 s14, v255, 27
	v_ashrrev_i32_e32 v67, 31, v66
	v_readlane_b32 s15, v255, 28
	v_lshlrev_b32_e32 v0, 1, v69
	s_mov_b32 s7, 0x800000
	v_lshl_add_u64 v[66:67], v[66:67], 1, s[14:15]
	v_lshl_add_u64 v[66:67], v[66:67], 0, v[0:1]
	v_mad_u64_u32 v[82:83], s[14:15], v88, s11, v[68:69]
	s_movk_i32 s16, 0x1600
	s_mov_b64 s[22:23], -1
	s_waitcnt vmcnt(0)
	v_mad_i64_i32 v[70:71], s[14:15], v70, s16, v[66:67]
	ds_read_b128 v[72:75], v82
	ds_read_b128 v[76:79], v82 offset:64
	v_add_u32_e32 v0, 0x10400, v82
	s_lshl_b32 s98, s16, 4
	s_mov_b32 s99, 0
	v_add_f32_e32 v134, v134, v135
	v_add_f32_e32 v134, v134, v136
	v_add_f32_e32 v134, v134, v137
	v_fmamk_f32 v134, v134, 0x3a800000, v200
	v_rsq_f32_e32 v134, v134
	v_add_f32_e32 v138, v138, v139
	v_add_f32_e32 v138, v138, v140
	v_add_f32_e32 v138, v138, v141
	v_fmamk_f32 v138, v138, 0x3a800000, v200
	v_rsq_f32_e32 v138, v138
	v_add_f32_e32 v144, v144, v145
	v_add_f32_e32 v144, v144, v146
	v_add_f32_e32 v144, v144, v147
	v_fmamk_f32 v144, v144, 0x3a800000, v200
	v_rsq_f32_e32 v144, v144
	v_add_f32_e32 v148, v148, v149
	v_add_f32_e32 v148, v148, v150
	v_add_f32_e32 v148, v148, v151
	v_fmamk_f32 v148, v148, 0x3a800000, v200
	v_rsq_f32_e32 v148, v148
	v_add_f32_e32 v152, v152, v153
	v_add_f32_e32 v152, v152, v154
	v_add_f32_e32 v152, v152, v155
	v_fmamk_f32 v152, v152, 0x3a800000, v200
	v_rsq_f32_e32 v152, v152
	v_add_f32_e32 v156, v156, v157
	v_add_f32_e32 v156, v156, v158
	v_add_f32_e32 v156, v156, v159
	v_fmamk_f32 v156, v156, 0x3a800000, v200
	v_rsq_f32_e32 v156, v156
	v_add_f32_e32 v160, v160, v161
	v_add_f32_e32 v160, v160, v162
	v_add_f32_e32 v160, v160, v163
	v_fmamk_f32 v160, v160, 0x3a800000, v200
	v_rsq_f32_e32 v160, v160
	v_add_f32_e32 v164, v164, v165
	v_add_f32_e32 v164, v164, v166
	v_add_f32_e32 v164, v164, v167
	v_fmamk_f32 v164, v164, 0x3a800000, v200
	v_rsq_f32_e32 v164, v164
	ds_read_b128 v[84:87], v82 offset:16640
	ds_read_b128 v[98:101], v82 offset:16704
	s_waitcnt lgkmcnt(2)
	v_pk_mul_f32 v[72:73], v[72:73], v[134:135] op_sel_hi:[1,0]
	v_pk_mul_f32 v[74:75], v[74:75], v[134:135] op_sel_hi:[1,0]
	v_mul_f32_e32 v102, 0xbfb8aa3b, v72
	v_mul_f32_e32 v103, 0xbfb8aa3b, v73
	v_mul_f32_e32 v104, 0xbfb8aa3b, v74
	v_mul_f32_e32 v105, 0xbfb8aa3b, v75
	v_exp_f32_e32 v102, v102
	v_exp_f32_e32 v103, v103
	v_exp_f32_e32 v104, v104
	v_exp_f32_e32 v105, v105
	v_pk_mul_f32 v[76:77], v[76:77], v[134:135] op_sel_hi:[1,0]
	v_pk_mul_f32 v[78:79], v[78:79], v[134:135] op_sel_hi:[1,0]
	v_pk_add_f32 v[102:103], v[102:103], 1.0 op_sel_hi:[1,0]
	v_pk_add_f32 v[104:105], v[104:105], 1.0 op_sel_hi:[1,0]
	v_rcp_f32_e32 v102, v102
	v_rcp_f32_e32 v103, v103
	v_rcp_f32_e32 v104, v104
	v_rcp_f32_e32 v105, v105
	s_nop 0
	v_pk_mul_f32 v[72:73], v[72:73], v[102:103]
	v_pk_mul_f32 v[74:75], v[74:75], v[104:105]
	v_pk_mul_f32 v[72:73], v[76:77], v[72:73]
	v_pk_mul_f32 v[74:75], v[78:79], v[74:75]
	v_cvt_pk_bf16_f32 v102, v72, v73
	v_cvt_pk_bf16_f32 v103, v74, v75
	global_store_dwordx2 v[70:71], v[102:103], off
	v_lshl_add_u64 v[70:71], v[70:71], 0, s[98:99]
	ds_read_b128 v[72:75], v82 offset:33280
	ds_read_b128 v[76:79], v82 offset:33344
	s_waitcnt lgkmcnt(2)
	v_pk_mul_f32 v[84:85], v[84:85], v[138:139] op_sel_hi:[1,0]
	v_pk_mul_f32 v[86:87], v[86:87], v[138:139] op_sel_hi:[1,0]
	v_mul_f32_e32 v102, 0xbfb8aa3b, v84
	v_mul_f32_e32 v103, 0xbfb8aa3b, v85
	v_mul_f32_e32 v104, 0xbfb8aa3b, v86
	v_mul_f32_e32 v105, 0xbfb8aa3b, v87
	v_exp_f32_e32 v102, v102
	v_exp_f32_e32 v103, v103
	v_exp_f32_e32 v104, v104
	v_exp_f32_e32 v105, v105
	v_pk_mul_f32 v[98:99], v[98:99], v[138:139] op_sel_hi:[1,0]
	v_pk_mul_f32 v[100:101], v[100:101], v[138:139] op_sel_hi:[1,0]
	v_pk_add_f32 v[102:103], v[102:103], 1.0 op_sel_hi:[1,0]
	v_pk_add_f32 v[104:105], v[104:105], 1.0 op_sel_hi:[1,0]
	v_rcp_f32_e32 v102, v102
	v_rcp_f32_e32 v103, v103
	v_rcp_f32_e32 v104, v104
	v_rcp_f32_e32 v105, v105
	s_nop 0
	v_pk_mul_f32 v[84:85], v[84:85], v[102:103]
	v_pk_mul_f32 v[86:87], v[86:87], v[104:105]
	v_pk_mul_f32 v[84:85], v[98:99], v[84:85]
	v_pk_mul_f32 v[86:87], v[100:101], v[86:87]
	v_cvt_pk_bf16_f32 v102, v84, v85
	v_cvt_pk_bf16_f32 v103, v86, v87
	global_store_dwordx2 v[70:71], v[102:103], off
	v_lshl_add_u64 v[70:71], v[70:71], 0, s[98:99]
	ds_read_b128 v[84:87], v82 offset:49920
	ds_read_b128 v[98:101], v82 offset:49984
	s_waitcnt lgkmcnt(2)
	v_pk_mul_f32 v[72:73], v[72:73], v[144:145] op_sel_hi:[1,0]
	v_pk_mul_f32 v[74:75], v[74:75], v[144:145] op_sel_hi:[1,0]
	v_mul_f32_e32 v102, 0xbfb8aa3b, v72
	v_mul_f32_e32 v103, 0xbfb8aa3b, v73
	v_mul_f32_e32 v104, 0xbfb8aa3b, v74
	v_mul_f32_e32 v105, 0xbfb8aa3b, v75
	v_exp_f32_e32 v102, v102
	v_exp_f32_e32 v103, v103
	v_exp_f32_e32 v104, v104
	v_exp_f32_e32 v105, v105
	v_pk_mul_f32 v[76:77], v[76:77], v[144:145] op_sel_hi:[1,0]
	v_pk_mul_f32 v[78:79], v[78:79], v[144:145] op_sel_hi:[1,0]
	v_pk_add_f32 v[102:103], v[102:103], 1.0 op_sel_hi:[1,0]
	v_pk_add_f32 v[104:105], v[104:105], 1.0 op_sel_hi:[1,0]
	v_rcp_f32_e32 v102, v102
	v_rcp_f32_e32 v103, v103
	v_rcp_f32_e32 v104, v104
	v_rcp_f32_e32 v105, v105
	s_nop 0
	v_pk_mul_f32 v[72:73], v[72:73], v[102:103]
	v_pk_mul_f32 v[74:75], v[74:75], v[104:105]
	v_pk_mul_f32 v[72:73], v[76:77], v[72:73]
	v_pk_mul_f32 v[74:75], v[78:79], v[74:75]
	v_cvt_pk_bf16_f32 v102, v72, v73
	v_cvt_pk_bf16_f32 v103, v74, v75
	global_store_dwordx2 v[70:71], v[102:103], off
	v_lshl_add_u64 v[70:71], v[70:71], 0, s[98:99]
	ds_read_b128 v[72:75], v0
	ds_read_b128 v[76:79], v0 offset:64
	s_waitcnt lgkmcnt(2)
	v_pk_mul_f32 v[84:85], v[84:85], v[148:149] op_sel_hi:[1,0]
	v_pk_mul_f32 v[86:87], v[86:87], v[148:149] op_sel_hi:[1,0]
	v_mul_f32_e32 v102, 0xbfb8aa3b, v84
	v_mul_f32_e32 v103, 0xbfb8aa3b, v85
	v_mul_f32_e32 v104, 0xbfb8aa3b, v86
	v_mul_f32_e32 v105, 0xbfb8aa3b, v87
	v_exp_f32_e32 v102, v102
	v_exp_f32_e32 v103, v103
	v_exp_f32_e32 v104, v104
	v_exp_f32_e32 v105, v105
	v_pk_mul_f32 v[98:99], v[98:99], v[148:149] op_sel_hi:[1,0]
	v_pk_mul_f32 v[100:101], v[100:101], v[148:149] op_sel_hi:[1,0]
	v_pk_add_f32 v[102:103], v[102:103], 1.0 op_sel_hi:[1,0]
	v_pk_add_f32 v[104:105], v[104:105], 1.0 op_sel_hi:[1,0]
	v_rcp_f32_e32 v102, v102
	v_rcp_f32_e32 v103, v103
	v_rcp_f32_e32 v104, v104
	v_rcp_f32_e32 v105, v105
	s_nop 0
	v_pk_mul_f32 v[84:85], v[84:85], v[102:103]
	v_pk_mul_f32 v[86:87], v[86:87], v[104:105]
	v_pk_mul_f32 v[84:85], v[98:99], v[84:85]
	v_pk_mul_f32 v[86:87], v[100:101], v[86:87]
	v_cvt_pk_bf16_f32 v102, v84, v85
	v_cvt_pk_bf16_f32 v103, v86, v87
	global_store_dwordx2 v[70:71], v[102:103], off
	v_lshl_add_u64 v[70:71], v[70:71], 0, s[98:99]
	ds_read_b128 v[84:87], v0 offset:16640
	ds_read_b128 v[98:101], v0 offset:16704
	s_waitcnt lgkmcnt(2)
	v_pk_mul_f32 v[72:73], v[72:73], v[152:153] op_sel_hi:[1,0]
	v_pk_mul_f32 v[74:75], v[74:75], v[152:153] op_sel_hi:[1,0]
	v_mul_f32_e32 v102, 0xbfb8aa3b, v72
	v_mul_f32_e32 v103, 0xbfb8aa3b, v73
	v_mul_f32_e32 v104, 0xbfb8aa3b, v74
	v_mul_f32_e32 v105, 0xbfb8aa3b, v75
	v_exp_f32_e32 v102, v102
	v_exp_f32_e32 v103, v103
	v_exp_f32_e32 v104, v104
	v_exp_f32_e32 v105, v105
	v_pk_mul_f32 v[76:77], v[76:77], v[152:153] op_sel_hi:[1,0]
	v_pk_mul_f32 v[78:79], v[78:79], v[152:153] op_sel_hi:[1,0]
	v_pk_add_f32 v[102:103], v[102:103], 1.0 op_sel_hi:[1,0]
	v_pk_add_f32 v[104:105], v[104:105], 1.0 op_sel_hi:[1,0]
	v_rcp_f32_e32 v102, v102
	v_rcp_f32_e32 v103, v103
	v_rcp_f32_e32 v104, v104
	v_rcp_f32_e32 v105, v105
	s_nop 0
	v_pk_mul_f32 v[72:73], v[72:73], v[102:103]
	v_pk_mul_f32 v[74:75], v[74:75], v[104:105]
	v_pk_mul_f32 v[72:73], v[76:77], v[72:73]
	v_pk_mul_f32 v[74:75], v[78:79], v[74:75]
	v_cvt_pk_bf16_f32 v102, v72, v73
	v_cvt_pk_bf16_f32 v103, v74, v75
	global_store_dwordx2 v[70:71], v[102:103], off
	v_lshl_add_u64 v[70:71], v[70:71], 0, s[98:99]
	ds_read_b128 v[72:75], v0 offset:33280
	ds_read_b128 v[76:79], v0 offset:33344
	s_waitcnt lgkmcnt(2)
	v_pk_mul_f32 v[84:85], v[84:85], v[156:157] op_sel_hi:[1,0]
	v_pk_mul_f32 v[86:87], v[86:87], v[156:157] op_sel_hi:[1,0]
	v_mul_f32_e32 v102, 0xbfb8aa3b, v84
	v_mul_f32_e32 v103, 0xbfb8aa3b, v85
	v_mul_f32_e32 v104, 0xbfb8aa3b, v86
	v_mul_f32_e32 v105, 0xbfb8aa3b, v87
	v_exp_f32_e32 v102, v102
	v_exp_f32_e32 v103, v103
	v_exp_f32_e32 v104, v104
	v_exp_f32_e32 v105, v105
	v_pk_mul_f32 v[98:99], v[98:99], v[156:157] op_sel_hi:[1,0]
	v_pk_mul_f32 v[100:101], v[100:101], v[156:157] op_sel_hi:[1,0]
	v_pk_add_f32 v[102:103], v[102:103], 1.0 op_sel_hi:[1,0]
	v_pk_add_f32 v[104:105], v[104:105], 1.0 op_sel_hi:[1,0]
	v_rcp_f32_e32 v102, v102
	v_rcp_f32_e32 v103, v103
	v_rcp_f32_e32 v104, v104
	v_rcp_f32_e32 v105, v105
	s_nop 0
	v_pk_mul_f32 v[84:85], v[84:85], v[102:103]
	v_pk_mul_f32 v[86:87], v[86:87], v[104:105]
	v_pk_mul_f32 v[84:85], v[98:99], v[84:85]
	v_pk_mul_f32 v[86:87], v[100:101], v[86:87]
	v_cvt_pk_bf16_f32 v102, v84, v85
	v_cvt_pk_bf16_f32 v103, v86, v87
	global_store_dwordx2 v[70:71], v[102:103], off
	v_lshl_add_u64 v[70:71], v[70:71], 0, s[98:99]
	ds_read_b128 v[84:87], v0 offset:49920
	ds_read_b128 v[98:101], v0 offset:49984
	s_waitcnt lgkmcnt(2)
	v_pk_mul_f32 v[72:73], v[72:73], v[160:161] op_sel_hi:[1,0]
	v_pk_mul_f32 v[74:75], v[74:75], v[160:161] op_sel_hi:[1,0]
	v_mul_f32_e32 v102, 0xbfb8aa3b, v72
	v_mul_f32_e32 v103, 0xbfb8aa3b, v73
	v_mul_f32_e32 v104, 0xbfb8aa3b, v74
	v_mul_f32_e32 v105, 0xbfb8aa3b, v75
	v_exp_f32_e32 v102, v102
	v_exp_f32_e32 v103, v103
	v_exp_f32_e32 v104, v104
	v_exp_f32_e32 v105, v105
	v_pk_mul_f32 v[76:77], v[76:77], v[160:161] op_sel_hi:[1,0]
	v_pk_mul_f32 v[78:79], v[78:79], v[160:161] op_sel_hi:[1,0]
	v_pk_add_f32 v[102:103], v[102:103], 1.0 op_sel_hi:[1,0]
	v_pk_add_f32 v[104:105], v[104:105], 1.0 op_sel_hi:[1,0]
	v_rcp_f32_e32 v102, v102
	v_rcp_f32_e32 v103, v103
	v_rcp_f32_e32 v104, v104
	v_rcp_f32_e32 v105, v105
	s_nop 0
	v_pk_mul_f32 v[72:73], v[72:73], v[102:103]
	v_pk_mul_f32 v[74:75], v[74:75], v[104:105]
	v_pk_mul_f32 v[72:73], v[76:77], v[72:73]
	v_pk_mul_f32 v[74:75], v[78:79], v[74:75]
	v_cvt_pk_bf16_f32 v102, v72, v73
	v_cvt_pk_bf16_f32 v103, v74, v75
	global_store_dwordx2 v[70:71], v[102:103], off
	v_lshl_add_u64 v[70:71], v[70:71], 0, s[98:99]
	s_waitcnt lgkmcnt(0)
	v_pk_mul_f32 v[84:85], v[84:85], v[164:165] op_sel_hi:[1,0]
	v_pk_mul_f32 v[86:87], v[86:87], v[164:165] op_sel_hi:[1,0]
	v_mul_f32_e32 v102, 0xbfb8aa3b, v84
	v_mul_f32_e32 v103, 0xbfb8aa3b, v85
	v_mul_f32_e32 v104, 0xbfb8aa3b, v86
	v_mul_f32_e32 v105, 0xbfb8aa3b, v87
	v_exp_f32_e32 v102, v102
	v_exp_f32_e32 v103, v103
	v_exp_f32_e32 v104, v104
	v_exp_f32_e32 v105, v105
	v_pk_mul_f32 v[98:99], v[98:99], v[164:165] op_sel_hi:[1,0]
	v_pk_mul_f32 v[100:101], v[100:101], v[164:165] op_sel_hi:[1,0]
	v_pk_add_f32 v[102:103], v[102:103], 1.0 op_sel_hi:[1,0]
	v_pk_add_f32 v[104:105], v[104:105], 1.0 op_sel_hi:[1,0]
	v_rcp_f32_e32 v102, v102
	v_rcp_f32_e32 v103, v103
	v_rcp_f32_e32 v104, v104
	v_rcp_f32_e32 v105, v105
	s_nop 0
	v_pk_mul_f32 v[84:85], v[84:85], v[102:103]
	v_pk_mul_f32 v[86:87], v[86:87], v[104:105]
	v_pk_mul_f32 v[84:85], v[98:99], v[84:85]
	v_pk_mul_f32 v[86:87], v[100:101], v[86:87]
	v_cvt_pk_bf16_f32 v102, v84, v85
	v_cvt_pk_bf16_f32 v103, v86, v87
	global_store_dwordx2 v[70:71], v[102:103], off
	s_barrier
	ds_write2_b32 v130, v2, v18 offset1:16
	ds_write2_b32 v114, v3, v19 offset0:4 offset1:20
	ds_write2_b32 v115, v4, v20 offset0:8 offset1:24
	ds_write2_b32 v116, v5, v21 offset0:12 offset1:28
	ds_write2_b32 v117, v6, v22 offset0:64 offset1:80
	ds_write2_b32 v94, v7, v23 offset0:68 offset1:84
	ds_write2_b32 v95, v8, v24 offset0:72 offset1:88
	ds_write2_b32 v96, v9, v25 offset0:76 offset1:92
	ds_write2_b32 v132, v10, v26 offset0:128 offset1:144
	ds_write2_b32 v97, v11, v27 offset0:132 offset1:148
	ds_write2_b32 v126, v12, v28 offset0:136 offset1:152
	ds_write2_b32 v127, v13, v29 offset0:140 offset1:156
	ds_write2_b32 v133, v14, v30 offset0:192 offset1:208
	ds_write2_b32 v128, v15, v31 offset0:196 offset1:212
	ds_write2_b32 v129, v16, v32 offset0:200 offset1:216
	ds_write2_b32 v131, v17, v33 offset0:204 offset1:220
	ds_write2_b32 v130, v34, v50 offset0:128 offset1:144
	ds_write2_b32 v114, v35, v51 offset0:132 offset1:148
	ds_write2_b32 v115, v36, v52 offset0:136 offset1:152
	ds_write2_b32 v116, v37, v53 offset0:140 offset1:156
	ds_write2_b32 v117, v38, v54 offset0:192 offset1:208
	ds_write2_b32 v94, v39, v55 offset0:196 offset1:212
	ds_write2_b32 v95, v40, v56 offset0:200 offset1:216
	ds_write2_b32 v96, v41, v57 offset0:204 offset1:220
	ds_write2_b32 v97, v42, v58 offset1:16
	ds_write2_b32 v126, v43, v59 offset0:4 offset1:20
	ds_write2_b32 v127, v44, v60 offset0:8 offset1:24
	ds_write2_b32 v90, v45, v61 offset0:12 offset1:28
	ds_write2_b32 v128, v46, v62 offset0:64 offset1:80
	ds_write2_b32 v129, v47, v63 offset0:68 offset1:84
	ds_write2_b32 v131, v48, v64 offset0:72 offset1:88
	ds_write2_b32 v91, v49, v65 offset0:76 offset1:92
	v_add_u32_e32 v2, s10, v88
	v_ashrrev_i32_e32 v3, 31, v2
	v_lshl_add_u64 v[4:5], v[2:3], 4, s[40:41]
	s_waitcnt lgkmcnt(0)
	s_barrier
	global_load_dwordx4 v[134:137], v[4:5], off
	global_load_dwordx4 v[138:141], v[4:5], off offset:256
	global_load_dwordx4 v[144:147], v[4:5], off offset:512
	global_load_dwordx4 v[148:151], v[4:5], off offset:768
	global_load_dwordx4 v[152:155], v[4:5], off offset:1024
	global_load_dwordx4 v[156:159], v[4:5], off offset:1280
	global_load_dwordx4 v[160:163], v[4:5], off offset:1536
	global_load_dwordx4 v[164:167], v[4:5], off offset:1792
	s_waitcnt vmcnt(0)
	v_mad_i64_i32 v[2:3], s[12:13], v2, s16, v[66:67]
	ds_read_b128 v[4:7], v82
	ds_read_b128 v[8:11], v82 offset:64
	v_add_u32_e32 v0, 0x10400, v82
	s_lshl_b32 s98, s16, 4
	s_mov_b32 s99, 0
	v_add_f32_e32 v134, v134, v135
	v_add_f32_e32 v134, v134, v136
	v_add_f32_e32 v134, v134, v137
	v_fmamk_f32 v134, v134, 0x3a800000, v200
	v_rsq_f32_e32 v134, v134
	v_add_f32_e32 v138, v138, v139
	v_add_f32_e32 v138, v138, v140
	v_add_f32_e32 v138, v138, v141
	v_fmamk_f32 v138, v138, 0x3a800000, v200
	v_rsq_f32_e32 v138, v138
	v_add_f32_e32 v144, v144, v145
	v_add_f32_e32 v144, v144, v146
	v_add_f32_e32 v144, v144, v147
	v_fmamk_f32 v144, v144, 0x3a800000, v200
	v_rsq_f32_e32 v144, v144
	v_add_f32_e32 v148, v148, v149
	v_add_f32_e32 v148, v148, v150
	v_add_f32_e32 v148, v148, v151
	v_fmamk_f32 v148, v148, 0x3a800000, v200
	v_rsq_f32_e32 v148, v148
	v_add_f32_e32 v152, v152, v153
	v_add_f32_e32 v152, v152, v154
	v_add_f32_e32 v152, v152, v155
	v_fmamk_f32 v152, v152, 0x3a800000, v200
	v_rsq_f32_e32 v152, v152
	v_add_f32_e32 v156, v156, v157
	v_add_f32_e32 v156, v156, v158
	v_add_f32_e32 v156, v156, v159
	v_fmamk_f32 v156, v156, 0x3a800000, v200
	v_rsq_f32_e32 v156, v156
	v_add_f32_e32 v160, v160, v161
	v_add_f32_e32 v160, v160, v162
	v_add_f32_e32 v160, v160, v163
	v_fmamk_f32 v160, v160, 0x3a800000, v200
	v_rsq_f32_e32 v160, v160
	v_add_f32_e32 v164, v164, v165
	v_add_f32_e32 v164, v164, v166
	v_add_f32_e32 v164, v164, v167
	v_fmamk_f32 v164, v164, 0x3a800000, v200
	v_rsq_f32_e32 v164, v164
	ds_read_b128 v[12:15], v82 offset:16640
	ds_read_b128 v[16:19], v82 offset:16704
	s_waitcnt lgkmcnt(2)
	v_pk_mul_f32 v[4:5], v[4:5], v[134:135] op_sel_hi:[1,0]
	v_pk_mul_f32 v[6:7], v[6:7], v[134:135] op_sel_hi:[1,0]
	v_mul_f32_e32 v20, 0xbfb8aa3b, v4
	v_mul_f32_e32 v21, 0xbfb8aa3b, v5
	v_mul_f32_e32 v22, 0xbfb8aa3b, v6
	v_mul_f32_e32 v23, 0xbfb8aa3b, v7
	v_exp_f32_e32 v20, v20
	v_exp_f32_e32 v21, v21
	v_exp_f32_e32 v22, v22
	v_exp_f32_e32 v23, v23
	v_pk_mul_f32 v[8:9], v[8:9], v[134:135] op_sel_hi:[1,0]
	v_pk_mul_f32 v[10:11], v[10:11], v[134:135] op_sel_hi:[1,0]
	v_pk_add_f32 v[20:21], v[20:21], 1.0 op_sel_hi:[1,0]
	v_pk_add_f32 v[22:23], v[22:23], 1.0 op_sel_hi:[1,0]
	v_rcp_f32_e32 v20, v20
	v_rcp_f32_e32 v21, v21
	v_rcp_f32_e32 v22, v22
	v_rcp_f32_e32 v23, v23
	s_nop 0
	v_pk_mul_f32 v[4:5], v[4:5], v[20:21]
	v_pk_mul_f32 v[6:7], v[6:7], v[22:23]
	v_pk_mul_f32 v[4:5], v[8:9], v[4:5]
	v_pk_mul_f32 v[6:7], v[10:11], v[6:7]
	v_cvt_pk_bf16_f32 v20, v4, v5
	v_cvt_pk_bf16_f32 v21, v6, v7
	global_store_dwordx2 v[2:3], v[20:21], off
	v_lshl_add_u64 v[2:3], v[2:3], 0, s[98:99]
	ds_read_b128 v[4:7], v82 offset:33280
	ds_read_b128 v[8:11], v82 offset:33344
	s_waitcnt lgkmcnt(2)
	v_pk_mul_f32 v[12:13], v[12:13], v[138:139] op_sel_hi:[1,0]
	v_pk_mul_f32 v[14:15], v[14:15], v[138:139] op_sel_hi:[1,0]
	v_mul_f32_e32 v20, 0xbfb8aa3b, v12
	v_mul_f32_e32 v21, 0xbfb8aa3b, v13
	v_mul_f32_e32 v22, 0xbfb8aa3b, v14
	v_mul_f32_e32 v23, 0xbfb8aa3b, v15
	v_exp_f32_e32 v20, v20
	v_exp_f32_e32 v21, v21
	v_exp_f32_e32 v22, v22
	v_exp_f32_e32 v23, v23
	v_pk_mul_f32 v[16:17], v[16:17], v[138:139] op_sel_hi:[1,0]
	v_pk_mul_f32 v[18:19], v[18:19], v[138:139] op_sel_hi:[1,0]
	v_pk_add_f32 v[20:21], v[20:21], 1.0 op_sel_hi:[1,0]
	v_pk_add_f32 v[22:23], v[22:23], 1.0 op_sel_hi:[1,0]
	v_rcp_f32_e32 v20, v20
	v_rcp_f32_e32 v21, v21
	v_rcp_f32_e32 v22, v22
	v_rcp_f32_e32 v23, v23
	s_nop 0
	v_pk_mul_f32 v[12:13], v[12:13], v[20:21]
	v_pk_mul_f32 v[14:15], v[14:15], v[22:23]
	v_pk_mul_f32 v[12:13], v[16:17], v[12:13]
	v_pk_mul_f32 v[14:15], v[18:19], v[14:15]
	v_cvt_pk_bf16_f32 v20, v12, v13
	v_cvt_pk_bf16_f32 v21, v14, v15
	global_store_dwordx2 v[2:3], v[20:21], off
	v_lshl_add_u64 v[2:3], v[2:3], 0, s[98:99]
	ds_read_b128 v[12:15], v82 offset:49920
	ds_read_b128 v[16:19], v82 offset:49984
	s_waitcnt lgkmcnt(2)
	v_pk_mul_f32 v[4:5], v[4:5], v[144:145] op_sel_hi:[1,0]
	v_pk_mul_f32 v[6:7], v[6:7], v[144:145] op_sel_hi:[1,0]
	v_mul_f32_e32 v20, 0xbfb8aa3b, v4
	v_mul_f32_e32 v21, 0xbfb8aa3b, v5
	v_mul_f32_e32 v22, 0xbfb8aa3b, v6
	v_mul_f32_e32 v23, 0xbfb8aa3b, v7
	v_exp_f32_e32 v20, v20
	v_exp_f32_e32 v21, v21
	v_exp_f32_e32 v22, v22
	v_exp_f32_e32 v23, v23
	v_pk_mul_f32 v[8:9], v[8:9], v[144:145] op_sel_hi:[1,0]
	v_pk_mul_f32 v[10:11], v[10:11], v[144:145] op_sel_hi:[1,0]
	v_pk_add_f32 v[20:21], v[20:21], 1.0 op_sel_hi:[1,0]
	v_pk_add_f32 v[22:23], v[22:23], 1.0 op_sel_hi:[1,0]
	v_rcp_f32_e32 v20, v20
	v_rcp_f32_e32 v21, v21
	v_rcp_f32_e32 v22, v22
	v_rcp_f32_e32 v23, v23
	s_nop 0
	v_pk_mul_f32 v[4:5], v[4:5], v[20:21]
	v_pk_mul_f32 v[6:7], v[6:7], v[22:23]
	v_pk_mul_f32 v[4:5], v[8:9], v[4:5]
	v_pk_mul_f32 v[6:7], v[10:11], v[6:7]
	v_cvt_pk_bf16_f32 v20, v4, v5
	v_cvt_pk_bf16_f32 v21, v6, v7
	global_store_dwordx2 v[2:3], v[20:21], off
	v_lshl_add_u64 v[2:3], v[2:3], 0, s[98:99]
	ds_read_b128 v[4:7], v0
	ds_read_b128 v[8:11], v0 offset:64
	s_waitcnt lgkmcnt(2)
	v_pk_mul_f32 v[12:13], v[12:13], v[148:149] op_sel_hi:[1,0]
	v_pk_mul_f32 v[14:15], v[14:15], v[148:149] op_sel_hi:[1,0]
	v_mul_f32_e32 v20, 0xbfb8aa3b, v12
	v_mul_f32_e32 v21, 0xbfb8aa3b, v13
	v_mul_f32_e32 v22, 0xbfb8aa3b, v14
	v_mul_f32_e32 v23, 0xbfb8aa3b, v15
	v_exp_f32_e32 v20, v20
	v_exp_f32_e32 v21, v21
	v_exp_f32_e32 v22, v22
	v_exp_f32_e32 v23, v23
	v_pk_mul_f32 v[16:17], v[16:17], v[148:149] op_sel_hi:[1,0]
	v_pk_mul_f32 v[18:19], v[18:19], v[148:149] op_sel_hi:[1,0]
	v_pk_add_f32 v[20:21], v[20:21], 1.0 op_sel_hi:[1,0]
	v_pk_add_f32 v[22:23], v[22:23], 1.0 op_sel_hi:[1,0]
	v_rcp_f32_e32 v20, v20
	v_rcp_f32_e32 v21, v21
	v_rcp_f32_e32 v22, v22
	v_rcp_f32_e32 v23, v23
	s_nop 0
	v_pk_mul_f32 v[12:13], v[12:13], v[20:21]
	v_pk_mul_f32 v[14:15], v[14:15], v[22:23]
	v_pk_mul_f32 v[12:13], v[16:17], v[12:13]
	v_pk_mul_f32 v[14:15], v[18:19], v[14:15]
	v_cvt_pk_bf16_f32 v20, v12, v13
	v_cvt_pk_bf16_f32 v21, v14, v15
	global_store_dwordx2 v[2:3], v[20:21], off
	v_lshl_add_u64 v[2:3], v[2:3], 0, s[98:99]
	ds_read_b128 v[12:15], v0 offset:16640
	ds_read_b128 v[16:19], v0 offset:16704
	s_waitcnt lgkmcnt(2)
	v_pk_mul_f32 v[4:5], v[4:5], v[152:153] op_sel_hi:[1,0]
	v_pk_mul_f32 v[6:7], v[6:7], v[152:153] op_sel_hi:[1,0]
	v_mul_f32_e32 v20, 0xbfb8aa3b, v4
	v_mul_f32_e32 v21, 0xbfb8aa3b, v5
	v_mul_f32_e32 v22, 0xbfb8aa3b, v6
	v_mul_f32_e32 v23, 0xbfb8aa3b, v7
	v_exp_f32_e32 v20, v20
	v_exp_f32_e32 v21, v21
	v_exp_f32_e32 v22, v22
	v_exp_f32_e32 v23, v23
	v_pk_mul_f32 v[8:9], v[8:9], v[152:153] op_sel_hi:[1,0]
	v_pk_mul_f32 v[10:11], v[10:11], v[152:153] op_sel_hi:[1,0]
	v_pk_add_f32 v[20:21], v[20:21], 1.0 op_sel_hi:[1,0]
	v_pk_add_f32 v[22:23], v[22:23], 1.0 op_sel_hi:[1,0]
	v_rcp_f32_e32 v20, v20
	v_rcp_f32_e32 v21, v21
	v_rcp_f32_e32 v22, v22
	v_rcp_f32_e32 v23, v23
	s_nop 0
	v_pk_mul_f32 v[4:5], v[4:5], v[20:21]
	v_pk_mul_f32 v[6:7], v[6:7], v[22:23]
	v_pk_mul_f32 v[4:5], v[8:9], v[4:5]
	v_pk_mul_f32 v[6:7], v[10:11], v[6:7]
	v_cvt_pk_bf16_f32 v20, v4, v5
	v_cvt_pk_bf16_f32 v21, v6, v7
	global_store_dwordx2 v[2:3], v[20:21], off
	v_lshl_add_u64 v[2:3], v[2:3], 0, s[98:99]
	ds_read_b128 v[4:7], v0 offset:33280
	ds_read_b128 v[8:11], v0 offset:33344
	s_waitcnt lgkmcnt(2)
	v_pk_mul_f32 v[12:13], v[12:13], v[156:157] op_sel_hi:[1,0]
	v_pk_mul_f32 v[14:15], v[14:15], v[156:157] op_sel_hi:[1,0]
	v_mul_f32_e32 v20, 0xbfb8aa3b, v12
	v_mul_f32_e32 v21, 0xbfb8aa3b, v13
	v_mul_f32_e32 v22, 0xbfb8aa3b, v14
	v_mul_f32_e32 v23, 0xbfb8aa3b, v15
	v_exp_f32_e32 v20, v20
	v_exp_f32_e32 v21, v21
	v_exp_f32_e32 v22, v22
	v_exp_f32_e32 v23, v23
	v_pk_mul_f32 v[16:17], v[16:17], v[156:157] op_sel_hi:[1,0]
	v_pk_mul_f32 v[18:19], v[18:19], v[156:157] op_sel_hi:[1,0]
	v_pk_add_f32 v[20:21], v[20:21], 1.0 op_sel_hi:[1,0]
	v_pk_add_f32 v[22:23], v[22:23], 1.0 op_sel_hi:[1,0]
	v_rcp_f32_e32 v20, v20
	v_rcp_f32_e32 v21, v21
	v_rcp_f32_e32 v22, v22
	v_rcp_f32_e32 v23, v23
	s_nop 0
	v_pk_mul_f32 v[12:13], v[12:13], v[20:21]
	v_pk_mul_f32 v[14:15], v[14:15], v[22:23]
	v_pk_mul_f32 v[12:13], v[16:17], v[12:13]
	v_pk_mul_f32 v[14:15], v[18:19], v[14:15]
	v_cvt_pk_bf16_f32 v20, v12, v13
	v_cvt_pk_bf16_f32 v21, v14, v15
	global_store_dwordx2 v[2:3], v[20:21], off
	v_lshl_add_u64 v[2:3], v[2:3], 0, s[98:99]
	ds_read_b128 v[12:15], v0 offset:49920
	ds_read_b128 v[16:19], v0 offset:49984
	s_waitcnt lgkmcnt(2)
	v_pk_mul_f32 v[4:5], v[4:5], v[160:161] op_sel_hi:[1,0]
	v_pk_mul_f32 v[6:7], v[6:7], v[160:161] op_sel_hi:[1,0]
	v_mul_f32_e32 v20, 0xbfb8aa3b, v4
	v_mul_f32_e32 v21, 0xbfb8aa3b, v5
	v_mul_f32_e32 v22, 0xbfb8aa3b, v6
	v_mul_f32_e32 v23, 0xbfb8aa3b, v7
	v_exp_f32_e32 v20, v20
	v_exp_f32_e32 v21, v21
	v_exp_f32_e32 v22, v22
	v_exp_f32_e32 v23, v23
	v_pk_mul_f32 v[8:9], v[8:9], v[160:161] op_sel_hi:[1,0]
	v_pk_mul_f32 v[10:11], v[10:11], v[160:161] op_sel_hi:[1,0]
	v_pk_add_f32 v[20:21], v[20:21], 1.0 op_sel_hi:[1,0]
	v_pk_add_f32 v[22:23], v[22:23], 1.0 op_sel_hi:[1,0]
	v_rcp_f32_e32 v20, v20
	v_rcp_f32_e32 v21, v21
	v_rcp_f32_e32 v22, v22
	v_rcp_f32_e32 v23, v23
	s_nop 0
	v_pk_mul_f32 v[4:5], v[4:5], v[20:21]
	v_pk_mul_f32 v[6:7], v[6:7], v[22:23]
	v_pk_mul_f32 v[4:5], v[8:9], v[4:5]
	v_pk_mul_f32 v[6:7], v[10:11], v[6:7]
	v_cvt_pk_bf16_f32 v20, v4, v5
	v_cvt_pk_bf16_f32 v21, v6, v7
	global_store_dwordx2 v[2:3], v[20:21], off
	v_lshl_add_u64 v[2:3], v[2:3], 0, s[98:99]
	s_waitcnt lgkmcnt(0)
	v_pk_mul_f32 v[12:13], v[12:13], v[164:165] op_sel_hi:[1,0]
	v_pk_mul_f32 v[14:15], v[14:15], v[164:165] op_sel_hi:[1,0]
	v_mul_f32_e32 v20, 0xbfb8aa3b, v12
	v_mul_f32_e32 v21, 0xbfb8aa3b, v13
	v_mul_f32_e32 v22, 0xbfb8aa3b, v14
	v_mul_f32_e32 v23, 0xbfb8aa3b, v15
	v_exp_f32_e32 v20, v20
	v_exp_f32_e32 v21, v21
	v_exp_f32_e32 v22, v22
	v_exp_f32_e32 v23, v23
	v_pk_mul_f32 v[16:17], v[16:17], v[164:165] op_sel_hi:[1,0]
	v_pk_mul_f32 v[18:19], v[18:19], v[164:165] op_sel_hi:[1,0]
	v_pk_add_f32 v[20:21], v[20:21], 1.0 op_sel_hi:[1,0]
	v_pk_add_f32 v[22:23], v[22:23], 1.0 op_sel_hi:[1,0]
	v_rcp_f32_e32 v20, v20
	v_rcp_f32_e32 v21, v21
	v_rcp_f32_e32 v22, v22
	v_rcp_f32_e32 v23, v23
	s_nop 0
	v_pk_mul_f32 v[12:13], v[12:13], v[20:21]
	v_pk_mul_f32 v[14:15], v[14:15], v[22:23]
	v_pk_mul_f32 v[12:13], v[16:17], v[12:13]
	v_pk_mul_f32 v[14:15], v[18:19], v[14:15]
	v_cvt_pk_bf16_f32 v20, v12, v13
	v_cvt_pk_bf16_f32 v21, v14, v15
	global_store_dwordx2 v[2:3], v[20:21], off
	s_barrier

.LBB0_1134:
	s_or_b64 exec, exec, s[42:43]
	s_movk_i32 s33, 0x410
	v_lshrrev_b32_e32 v130, 2, v142
	v_lshlrev_b32_e32 v131, 1, v142
	v_and_b32_e32 v0, 15, v142
	v_and_b32_e32 v130, 0xfffffcc, v130
	v_and_b32_e32 v131, 0x180, v131
	v_add_u32_e32 v131, 0, v131
	v_lshlrev_b32_e32 v0, 2, v0
	v_mul_lo_u32 v130, v130, s33
	v_add3_u32 v130, v131, v0, v130
	s_waitcnt vmcnt(0)
	s_barrier
	ds_write2_b32 v130, v114, v126 offset1:16
	v_add_u32_e32 v114, 0x400, v130
	ds_write2_b32 v114, v115, v127 offset0:4 offset1:20
	v_add_u32_e32 v115, 0x800, v130
	ds_write2_b32 v115, v116, v128 offset0:8 offset1:24
	v_add_u32_e32 v116, 0xc00, v130
	ds_write2_b32 v116, v117, v129 offset0:12 offset1:28
	v_add_u32_e32 v117, 0x4000, v130
	ds_write2_b32 v117, v82, v94 offset0:64 offset1:80
	v_add_u32_e32 v94, 0x4400, v130
	ds_write2_b32 v94, v83, v95 offset0:68 offset1:84
	v_add_u32_e32 v95, 0x4800, v130
	ds_write2_b32 v95, v84, v96 offset0:72 offset1:88
	v_add_u32_e32 v96, 0x4c00, v130
	v_add_u32_e32 v133, 0xc000, v130
	ds_write2_b32 v96, v85, v97 offset0:76 offset1:92
	v_add_u32_e32 v132, 0x8000, v130
	v_add_u32_e32 v97, 0x8400, v130
	v_add_u32_e32 v126, 0x8800, v130
	v_add_u32_e32 v127, 0x8c00, v130
	ds_write2_b32 v133, v66, v70 offset0:192 offset1:208
	v_add_u32_e32 v128, 0xc400, v130
	v_add_u32_e32 v129, 0xc800, v130
	v_add_u32_e32 v131, 0xcc00, v130
	v_lshlrev_b32_e32 v0, 3, v142
	v_lshlrev_b32_e32 v66, 2, v142
	ds_write2_b32 v132, v74, v78 offset0:128 offset1:144
	ds_write2_b32 v97, v75, v79 offset0:132 offset1:148
	ds_write2_b32 v126, v76, v80 offset0:136 offset1:152
	ds_write2_b32 v127, v77, v81 offset0:140 offset1:156
	ds_write2_b32 v128, v67, v71 offset0:196 offset1:212
	ds_write2_b32 v129, v68, v72 offset0:200 offset1:216
	ds_write2_b32 v131, v69, v73 offset0:204 offset1:220
	ds_write2_b32 v130, v98, v118 offset0:128 offset1:144
	ds_write2_b32 v114, v99, v119 offset0:132 offset1:148
	ds_write2_b32 v115, v100, v120 offset0:136 offset1:152
	ds_write2_b32 v116, v101, v121 offset0:140 offset1:156
	ds_write2_b32 v117, v102, v122 offset0:192 offset1:208
	ds_write2_b32 v94, v103, v123 offset0:196 offset1:212
	ds_write2_b32 v95, v104, v124 offset0:200 offset1:216
	ds_write2_b32 v96, v105, v125 offset0:204 offset1:220
	ds_write2_b32 v97, v90, v110 offset1:16
	ds_write2_b32 v126, v91, v111 offset0:4 offset1:20
	ds_write2_b32 v127, v92, v112 offset0:8 offset1:24
	v_add_u32_e32 v90, 0x9000, v130
	v_and_b32_e32 v0, 0xe0, v0
	v_and_b32_e32 v68, 12, v66
	ds_write2_b32 v90, v93, v113 offset0:12 offset1:28
	ds_write2_b32 v128, v86, v106 offset0:64 offset1:80
	ds_write2_b32 v129, v87, v107 offset0:68 offset1:84
	ds_write2_b32 v131, v88, v108 offset0:72 offset1:88
	v_lshlrev_b32_e32 v66, 2, v0
	v_lshlrev_b32_e32 v67, 2, v68
	v_or_b32_e32 v0, s60, v0
	v_ashrrev_i32_e32 v88, 5, v142
	v_add3_u32 v74, 0, v66, v67
	v_ashrrev_i32_e32 v66, 1, v0
	v_lshlrev_b32_e32 v0, 1, v68
	v_add_u32_e32 v68, s12, v88
	v_ashrrev_i32_e32 v69, 31, v68
	v_add_u32_e32 v91, 0xd000, v130
	v_lshl_add_u64 v[70:71], v[68:69], 4, s[40:41]
	ds_write2_b32 v91, v89, v109 offset0:76 offset1:92
	s_waitcnt lgkmcnt(0)
	s_barrier
	global_load_dwordx4 v[134:137], v[70:71], off
	global_load_dwordx4 v[138:141], v[70:71], off offset:256
	global_load_dwordx4 v[144:147], v[70:71], off offset:512
	global_load_dwordx4 v[148:151], v[70:71], off offset:768
	global_load_dwordx4 v[152:155], v[70:71], off offset:1024
	global_load_dwordx4 v[156:159], v[70:71], off offset:1280
	global_load_dwordx4 v[160:163], v[70:71], off offset:1536
	global_load_dwordx4 v[164:167], v[70:71], off offset:1792
	v_readlane_b32 s20, v255, 27
	v_ashrrev_i32_e32 v67, 31, v66
	v_readlane_b32 s21, v255, 28
	v_mad_u64_u32 v[82:83], s[36:37], v88, s33, v[74:75]
	s_nop 0
	v_lshl_add_u64 v[66:67], v[66:67], 1, s[20:21]
	v_lshl_add_u64 v[66:67], v[66:67], 0, v[0:1]
	s_mov_b32 s20, 0x800000
	s_movk_i32 s21, 0x1600
	s_or_b32 s42, s60, 0x100
	s_ashr_i32 s43, s42, 31
	s_lshl_b64 s[44:45], s[42:43], 11
	s_waitcnt vmcnt(0)
	v_mad_i64_i32 v[68:69], s[36:37], v68, s21, v[66:67]
	ds_read_b128 v[70:73], v82
	ds_read_b128 v[74:77], v82 offset:64
	v_add_u32_e32 v0, 0x10400, v82
	s_lshl_b32 s98, s21, 4
	s_mov_b32 s99, 0
	v_add_f32_e32 v134, v134, v135
	v_add_f32_e32 v134, v134, v136
	v_add_f32_e32 v134, v134, v137
	v_fmamk_f32 v134, v134, 0x3a800000, v200
	v_rsq_f32_e32 v134, v134
	v_add_f32_e32 v138, v138, v139
	v_add_f32_e32 v138, v138, v140
	v_add_f32_e32 v138, v138, v141
	v_fmamk_f32 v138, v138, 0x3a800000, v200
	v_rsq_f32_e32 v138, v138
	v_add_f32_e32 v144, v144, v145
	v_add_f32_e32 v144, v144, v146
	v_add_f32_e32 v144, v144, v147
	v_fmamk_f32 v144, v144, 0x3a800000, v200
	v_rsq_f32_e32 v144, v144
	v_add_f32_e32 v148, v148, v149
	v_add_f32_e32 v148, v148, v150
	v_add_f32_e32 v148, v148, v151
	v_fmamk_f32 v148, v148, 0x3a800000, v200
	v_rsq_f32_e32 v148, v148
	v_add_f32_e32 v152, v152, v153
	v_add_f32_e32 v152, v152, v154
	v_add_f32_e32 v152, v152, v155
	v_fmamk_f32 v152, v152, 0x3a800000, v200
	v_rsq_f32_e32 v152, v152
	v_add_f32_e32 v156, v156, v157
	v_add_f32_e32 v156, v156, v158
	v_add_f32_e32 v156, v156, v159
	v_fmamk_f32 v156, v156, 0x3a800000, v200
	v_rsq_f32_e32 v156, v156
	v_add_f32_e32 v160, v160, v161
	v_add_f32_e32 v160, v160, v162
	v_add_f32_e32 v160, v160, v163
	v_fmamk_f32 v160, v160, 0x3a800000, v200
	v_rsq_f32_e32 v160, v160
	v_add_f32_e32 v164, v164, v165
	v_add_f32_e32 v164, v164, v166
	v_add_f32_e32 v164, v164, v167
	v_fmamk_f32 v164, v164, 0x3a800000, v200
	v_rsq_f32_e32 v164, v164
	ds_read_b128 v[78:81], v82 offset:16640
	ds_read_b128 v[84:87], v82 offset:16704
	s_waitcnt lgkmcnt(2)
	v_pk_mul_f32 v[70:71], v[70:71], v[134:135] op_sel_hi:[1,0]
	v_pk_mul_f32 v[72:73], v[72:73], v[134:135] op_sel_hi:[1,0]
	v_mul_f32_e32 v98, 0xbfb8aa3b, v70
	v_mul_f32_e32 v99, 0xbfb8aa3b, v71
	v_mul_f32_e32 v100, 0xbfb8aa3b, v72
	v_mul_f32_e32 v101, 0xbfb8aa3b, v73
	v_exp_f32_e32 v98, v98
	v_exp_f32_e32 v99, v99
	v_exp_f32_e32 v100, v100
	v_exp_f32_e32 v101, v101
	v_pk_mul_f32 v[74:75], v[74:75], v[134:135] op_sel_hi:[1,0]
	v_pk_mul_f32 v[76:77], v[76:77], v[134:135] op_sel_hi:[1,0]
	v_pk_add_f32 v[98:99], v[98:99], 1.0 op_sel_hi:[1,0]
	v_pk_add_f32 v[100:101], v[100:101], 1.0 op_sel_hi:[1,0]
	v_rcp_f32_e32 v98, v98
	v_rcp_f32_e32 v99, v99
	v_rcp_f32_e32 v100, v100
	v_rcp_f32_e32 v101, v101
	s_nop 0
	v_pk_mul_f32 v[70:71], v[70:71], v[98:99]
	v_pk_mul_f32 v[72:73], v[72:73], v[100:101]
	v_pk_mul_f32 v[70:71], v[74:75], v[70:71]
	v_pk_mul_f32 v[72:73], v[76:77], v[72:73]
	v_cvt_pk_bf16_f32 v98, v70, v71
	v_cvt_pk_bf16_f32 v99, v72, v73
	global_store_dwordx2 v[68:69], v[98:99], off
	v_lshl_add_u64 v[68:69], v[68:69], 0, s[98:99]
	ds_read_b128 v[70:73], v82 offset:33280
	ds_read_b128 v[74:77], v82 offset:33344
	s_waitcnt lgkmcnt(2)
	v_pk_mul_f32 v[78:79], v[78:79], v[138:139] op_sel_hi:[1,0]
	v_pk_mul_f32 v[80:81], v[80:81], v[138:139] op_sel_hi:[1,0]
	v_mul_f32_e32 v98, 0xbfb8aa3b, v78
	v_mul_f32_e32 v99, 0xbfb8aa3b, v79
	v_mul_f32_e32 v100, 0xbfb8aa3b, v80
	v_mul_f32_e32 v101, 0xbfb8aa3b, v81
	v_exp_f32_e32 v98, v98
	v_exp_f32_e32 v99, v99
	v_exp_f32_e32 v100, v100
	v_exp_f32_e32 v101, v101
	v_pk_mul_f32 v[84:85], v[84:85], v[138:139] op_sel_hi:[1,0]
	v_pk_mul_f32 v[86:87], v[86:87], v[138:139] op_sel_hi:[1,0]
	v_pk_add_f32 v[98:99], v[98:99], 1.0 op_sel_hi:[1,0]
	v_pk_add_f32 v[100:101], v[100:101], 1.0 op_sel_hi:[1,0]
	v_rcp_f32_e32 v98, v98
	v_rcp_f32_e32 v99, v99
	v_rcp_f32_e32 v100, v100
	v_rcp_f32_e32 v101, v101
	s_nop 0
	v_pk_mul_f32 v[78:79], v[78:79], v[98:99]
	v_pk_mul_f32 v[80:81], v[80:81], v[100:101]
	v_pk_mul_f32 v[78:79], v[84:85], v[78:79]
	v_pk_mul_f32 v[80:81], v[86:87], v[80:81]
	v_cvt_pk_bf16_f32 v98, v78, v79
	v_cvt_pk_bf16_f32 v99, v80, v81
	global_store_dwordx2 v[68:69], v[98:99], off
	v_lshl_add_u64 v[68:69], v[68:69], 0, s[98:99]
	ds_read_b128 v[78:81], v82 offset:49920
	ds_read_b128 v[84:87], v82 offset:49984
	s_waitcnt lgkmcnt(2)
	v_pk_mul_f32 v[70:71], v[70:71], v[144:145] op_sel_hi:[1,0]
	v_pk_mul_f32 v[72:73], v[72:73], v[144:145] op_sel_hi:[1,0]
	v_mul_f32_e32 v98, 0xbfb8aa3b, v70
	v_mul_f32_e32 v99, 0xbfb8aa3b, v71
	v_mul_f32_e32 v100, 0xbfb8aa3b, v72
	v_mul_f32_e32 v101, 0xbfb8aa3b, v73
	v_exp_f32_e32 v98, v98
	v_exp_f32_e32 v99, v99
	v_exp_f32_e32 v100, v100
	v_exp_f32_e32 v101, v101
	v_pk_mul_f32 v[74:75], v[74:75], v[144:145] op_sel_hi:[1,0]
	v_pk_mul_f32 v[76:77], v[76:77], v[144:145] op_sel_hi:[1,0]
	v_pk_add_f32 v[98:99], v[98:99], 1.0 op_sel_hi:[1,0]
	v_pk_add_f32 v[100:101], v[100:101], 1.0 op_sel_hi:[1,0]
	v_rcp_f32_e32 v98, v98
	v_rcp_f32_e32 v99, v99
	v_rcp_f32_e32 v100, v100
	v_rcp_f32_e32 v101, v101
	s_nop 0
	v_pk_mul_f32 v[70:71], v[70:71], v[98:99]
	v_pk_mul_f32 v[72:73], v[72:73], v[100:101]
	v_pk_mul_f32 v[70:71], v[74:75], v[70:71]
	v_pk_mul_f32 v[72:73], v[76:77], v[72:73]
	v_cvt_pk_bf16_f32 v98, v70, v71
	v_cvt_pk_bf16_f32 v99, v72, v73
	global_store_dwordx2 v[68:69], v[98:99], off
	v_lshl_add_u64 v[68:69], v[68:69], 0, s[98:99]
	ds_read_b128 v[70:73], v0
	ds_read_b128 v[74:77], v0 offset:64
	s_waitcnt lgkmcnt(2)
	v_pk_mul_f32 v[78:79], v[78:79], v[148:149] op_sel_hi:[1,0]
	v_pk_mul_f32 v[80:81], v[80:81], v[148:149] op_sel_hi:[1,0]
	v_mul_f32_e32 v98, 0xbfb8aa3b, v78
	v_mul_f32_e32 v99, 0xbfb8aa3b, v79
	v_mul_f32_e32 v100, 0xbfb8aa3b, v80
	v_mul_f32_e32 v101, 0xbfb8aa3b, v81
	v_exp_f32_e32 v98, v98
	v_exp_f32_e32 v99, v99
	v_exp_f32_e32 v100, v100
	v_exp_f32_e32 v101, v101
	v_pk_mul_f32 v[84:85], v[84:85], v[148:149] op_sel_hi:[1,0]
	v_pk_mul_f32 v[86:87], v[86:87], v[148:149] op_sel_hi:[1,0]
	v_pk_add_f32 v[98:99], v[98:99], 1.0 op_sel_hi:[1,0]
	v_pk_add_f32 v[100:101], v[100:101], 1.0 op_sel_hi:[1,0]
	v_rcp_f32_e32 v98, v98
	v_rcp_f32_e32 v99, v99
	v_rcp_f32_e32 v100, v100
	v_rcp_f32_e32 v101, v101
	s_nop 0
	v_pk_mul_f32 v[78:79], v[78:79], v[98:99]
	v_pk_mul_f32 v[80:81], v[80:81], v[100:101]
	v_pk_mul_f32 v[78:79], v[84:85], v[78:79]
	v_pk_mul_f32 v[80:81], v[86:87], v[80:81]
	v_cvt_pk_bf16_f32 v98, v78, v79
	v_cvt_pk_bf16_f32 v99, v80, v81
	global_store_dwordx2 v[68:69], v[98:99], off
	v_lshl_add_u64 v[68:69], v[68:69], 0, s[98:99]
	ds_read_b128 v[78:81], v0 offset:16640
	ds_read_b128 v[84:87], v0 offset:16704
	s_waitcnt lgkmcnt(2)
	v_pk_mul_f32 v[70:71], v[70:71], v[152:153] op_sel_hi:[1,0]
	v_pk_mul_f32 v[72:73], v[72:73], v[152:153] op_sel_hi:[1,0]
	v_mul_f32_e32 v98, 0xbfb8aa3b, v70
	v_mul_f32_e32 v99, 0xbfb8aa3b, v71
	v_mul_f32_e32 v100, 0xbfb8aa3b, v72
	v_mul_f32_e32 v101, 0xbfb8aa3b, v73
	v_exp_f32_e32 v98, v98
	v_exp_f32_e32 v99, v99
	v_exp_f32_e32 v100, v100
	v_exp_f32_e32 v101, v101
	v_pk_mul_f32 v[74:75], v[74:75], v[152:153] op_sel_hi:[1,0]
	v_pk_mul_f32 v[76:77], v[76:77], v[152:153] op_sel_hi:[1,0]
	v_pk_add_f32 v[98:99], v[98:99], 1.0 op_sel_hi:[1,0]
	v_pk_add_f32 v[100:101], v[100:101], 1.0 op_sel_hi:[1,0]
	v_rcp_f32_e32 v98, v98
	v_rcp_f32_e32 v99, v99
	v_rcp_f32_e32 v100, v100
	v_rcp_f32_e32 v101, v101
	s_nop 0
	v_pk_mul_f32 v[70:71], v[70:71], v[98:99]
	v_pk_mul_f32 v[72:73], v[72:73], v[100:101]
	v_pk_mul_f32 v[70:71], v[74:75], v[70:71]
	v_pk_mul_f32 v[72:73], v[76:77], v[72:73]
	v_cvt_pk_bf16_f32 v98, v70, v71
	v_cvt_pk_bf16_f32 v99, v72, v73
	global_store_dwordx2 v[68:69], v[98:99], off
	v_lshl_add_u64 v[68:69], v[68:69], 0, s[98:99]
	ds_read_b128 v[70:73], v0 offset:33280
	ds_read_b128 v[74:77], v0 offset:33344
	s_waitcnt lgkmcnt(2)
	v_pk_mul_f32 v[78:79], v[78:79], v[156:157] op_sel_hi:[1,0]
	v_pk_mul_f32 v[80:81], v[80:81], v[156:157] op_sel_hi:[1,0]
	v_mul_f32_e32 v98, 0xbfb8aa3b, v78
	v_mul_f32_e32 v99, 0xbfb8aa3b, v79
	v_mul_f32_e32 v100, 0xbfb8aa3b, v80
	v_mul_f32_e32 v101, 0xbfb8aa3b, v81
	v_exp_f32_e32 v98, v98
	v_exp_f32_e32 v99, v99
	v_exp_f32_e32 v100, v100
	v_exp_f32_e32 v101, v101
	v_pk_mul_f32 v[84:85], v[84:85], v[156:157] op_sel_hi:[1,0]
	v_pk_mul_f32 v[86:87], v[86:87], v[156:157] op_sel_hi:[1,0]
	v_pk_add_f32 v[98:99], v[98:99], 1.0 op_sel_hi:[1,0]
	v_pk_add_f32 v[100:101], v[100:101], 1.0 op_sel_hi:[1,0]
	v_rcp_f32_e32 v98, v98
	v_rcp_f32_e32 v99, v99
	v_rcp_f32_e32 v100, v100
	v_rcp_f32_e32 v101, v101
	s_nop 0
	v_pk_mul_f32 v[78:79], v[78:79], v[98:99]
	v_pk_mul_f32 v[80:81], v[80:81], v[100:101]
	v_pk_mul_f32 v[78:79], v[84:85], v[78:79]
	v_pk_mul_f32 v[80:81], v[86:87], v[80:81]
	v_cvt_pk_bf16_f32 v98, v78, v79
	v_cvt_pk_bf16_f32 v99, v80, v81
	global_store_dwordx2 v[68:69], v[98:99], off
	v_lshl_add_u64 v[68:69], v[68:69], 0, s[98:99]
	ds_read_b128 v[78:81], v0 offset:49920
	ds_read_b128 v[84:87], v0 offset:49984
	s_waitcnt lgkmcnt(2)
	v_pk_mul_f32 v[70:71], v[70:71], v[160:161] op_sel_hi:[1,0]
	v_pk_mul_f32 v[72:73], v[72:73], v[160:161] op_sel_hi:[1,0]
	v_mul_f32_e32 v98, 0xbfb8aa3b, v70
	v_mul_f32_e32 v99, 0xbfb8aa3b, v71
	v_mul_f32_e32 v100, 0xbfb8aa3b, v72
	v_mul_f32_e32 v101, 0xbfb8aa3b, v73
	v_exp_f32_e32 v98, v98
	v_exp_f32_e32 v99, v99
	v_exp_f32_e32 v100, v100
	v_exp_f32_e32 v101, v101
	v_pk_mul_f32 v[74:75], v[74:75], v[160:161] op_sel_hi:[1,0]
	v_pk_mul_f32 v[76:77], v[76:77], v[160:161] op_sel_hi:[1,0]
	v_pk_add_f32 v[98:99], v[98:99], 1.0 op_sel_hi:[1,0]
	v_pk_add_f32 v[100:101], v[100:101], 1.0 op_sel_hi:[1,0]
	v_rcp_f32_e32 v98, v98
	v_rcp_f32_e32 v99, v99
	v_rcp_f32_e32 v100, v100
	v_rcp_f32_e32 v101, v101
	s_nop 0
	v_pk_mul_f32 v[70:71], v[70:71], v[98:99]
	v_pk_mul_f32 v[72:73], v[72:73], v[100:101]
	v_pk_mul_f32 v[70:71], v[74:75], v[70:71]
	v_pk_mul_f32 v[72:73], v[76:77], v[72:73]
	v_cvt_pk_bf16_f32 v98, v70, v71
	v_cvt_pk_bf16_f32 v99, v72, v73
	global_store_dwordx2 v[68:69], v[98:99], off
	v_lshl_add_u64 v[68:69], v[68:69], 0, s[98:99]
	s_waitcnt lgkmcnt(0)
	v_pk_mul_f32 v[78:79], v[78:79], v[164:165] op_sel_hi:[1,0]
	v_pk_mul_f32 v[80:81], v[80:81], v[164:165] op_sel_hi:[1,0]
	v_mul_f32_e32 v98, 0xbfb8aa3b, v78
	v_mul_f32_e32 v99, 0xbfb8aa3b, v79
	v_mul_f32_e32 v100, 0xbfb8aa3b, v80
	v_mul_f32_e32 v101, 0xbfb8aa3b, v81
	v_exp_f32_e32 v98, v98
	v_exp_f32_e32 v99, v99
	v_exp_f32_e32 v100, v100
	v_exp_f32_e32 v101, v101
	v_pk_mul_f32 v[84:85], v[84:85], v[164:165] op_sel_hi:[1,0]
	v_pk_mul_f32 v[86:87], v[86:87], v[164:165] op_sel_hi:[1,0]
	v_pk_add_f32 v[98:99], v[98:99], 1.0 op_sel_hi:[1,0]
	v_pk_add_f32 v[100:101], v[100:101], 1.0 op_sel_hi:[1,0]
	v_rcp_f32_e32 v98, v98
	v_rcp_f32_e32 v99, v99
	v_rcp_f32_e32 v100, v100
	v_rcp_f32_e32 v101, v101
	s_nop 0
	v_pk_mul_f32 v[78:79], v[78:79], v[98:99]
	v_pk_mul_f32 v[80:81], v[80:81], v[100:101]
	v_pk_mul_f32 v[78:79], v[84:85], v[78:79]
	v_pk_mul_f32 v[80:81], v[86:87], v[80:81]
	v_cvt_pk_bf16_f32 v98, v78, v79
	v_cvt_pk_bf16_f32 v99, v80, v81
	global_store_dwordx2 v[68:69], v[98:99], off
	v_mov_b32_e32 v142, v201
	s_barrier
	ds_write2_b32 v130, v2, v18 offset1:16
	ds_write2_b32 v114, v3, v19 offset0:4 offset1:20
	ds_write2_b32 v115, v4, v20 offset0:8 offset1:24
	ds_write2_b32 v116, v5, v21 offset0:12 offset1:28
	ds_write2_b32 v117, v6, v22 offset0:64 offset1:80
	ds_write2_b32 v94, v7, v23 offset0:68 offset1:84
	ds_write2_b32 v95, v8, v24 offset0:72 offset1:88
	ds_write2_b32 v96, v9, v25 offset0:76 offset1:92
	ds_write2_b32 v132, v10, v26 offset0:128 offset1:144
	ds_write2_b32 v97, v11, v27 offset0:132 offset1:148
	ds_write2_b32 v126, v12, v28 offset0:136 offset1:152
	ds_write2_b32 v127, v13, v29 offset0:140 offset1:156
	ds_write2_b32 v133, v14, v30 offset0:192 offset1:208
	ds_write2_b32 v128, v15, v31 offset0:196 offset1:212
	ds_write2_b32 v129, v16, v32 offset0:200 offset1:216
	ds_write2_b32 v131, v17, v33 offset0:204 offset1:220
	ds_write2_b32 v130, v34, v50 offset0:128 offset1:144
	ds_write2_b32 v114, v35, v51 offset0:132 offset1:148
	ds_write2_b32 v115, v36, v52 offset0:136 offset1:152
	ds_write2_b32 v116, v37, v53 offset0:140 offset1:156
	ds_write2_b32 v117, v38, v54 offset0:192 offset1:208
	ds_write2_b32 v94, v39, v55 offset0:196 offset1:212
	ds_write2_b32 v95, v40, v56 offset0:200 offset1:216
	ds_write2_b32 v96, v41, v57 offset0:204 offset1:220
	ds_write2_b32 v97, v42, v58 offset1:16
	ds_write2_b32 v126, v43, v59 offset0:4 offset1:20
	ds_write2_b32 v127, v44, v60 offset0:8 offset1:24
	ds_write2_b32 v90, v45, v61 offset0:12 offset1:28
	ds_write2_b32 v128, v46, v62 offset0:64 offset1:80
	ds_write2_b32 v129, v47, v63 offset0:68 offset1:84
	ds_write2_b32 v131, v48, v64 offset0:72 offset1:88
	ds_write2_b32 v91, v49, v65 offset0:76 offset1:92
	v_add_u32_e32 v2, s10, v88
	v_ashrrev_i32_e32 v3, 31, v2
	v_lshl_add_u64 v[4:5], v[2:3], 4, s[40:41]
	s_waitcnt lgkmcnt(0)
	s_barrier
	global_load_dwordx4 v[134:137], v[4:5], off
	global_load_dwordx4 v[138:141], v[4:5], off offset:256
	global_load_dwordx4 v[144:147], v[4:5], off offset:512
	global_load_dwordx4 v[148:151], v[4:5], off offset:768
	global_load_dwordx4 v[152:155], v[4:5], off offset:1024
	global_load_dwordx4 v[156:159], v[4:5], off offset:1280
	global_load_dwordx4 v[160:163], v[4:5], off offset:1536
	global_load_dwordx4 v[164:167], v[4:5], off offset:1792
	s_waitcnt vmcnt(0)
	v_mad_i64_i32 v[2:3], s[36:37], v2, s21, v[66:67]
	ds_read_b128 v[4:7], v82
	ds_read_b128 v[8:11], v82 offset:64
	v_add_u32_e32 v0, 0x10400, v82
	s_lshl_b32 s98, s21, 4
	s_mov_b32 s99, 0
	v_add_f32_e32 v134, v134, v135
	v_add_f32_e32 v134, v134, v136
	v_add_f32_e32 v134, v134, v137
	v_fmamk_f32 v134, v134, 0x3a800000, v200
	v_rsq_f32_e32 v134, v134
	v_add_f32_e32 v138, v138, v139
	v_add_f32_e32 v138, v138, v140
	v_add_f32_e32 v138, v138, v141
	v_fmamk_f32 v138, v138, 0x3a800000, v200
	v_rsq_f32_e32 v138, v138
	v_add_f32_e32 v144, v144, v145
	v_add_f32_e32 v144, v144, v146
	v_add_f32_e32 v144, v144, v147
	v_fmamk_f32 v144, v144, 0x3a800000, v200
	v_rsq_f32_e32 v144, v144
	v_add_f32_e32 v148, v148, v149
	v_add_f32_e32 v148, v148, v150
	v_add_f32_e32 v148, v148, v151
	v_fmamk_f32 v148, v148, 0x3a800000, v200
	v_rsq_f32_e32 v148, v148
	v_add_f32_e32 v152, v152, v153
	v_add_f32_e32 v152, v152, v154
	v_add_f32_e32 v152, v152, v155
	v_fmamk_f32 v152, v152, 0x3a800000, v200
	v_rsq_f32_e32 v152, v152
	v_add_f32_e32 v156, v156, v157
	v_add_f32_e32 v156, v156, v158
	v_add_f32_e32 v156, v156, v159
	v_fmamk_f32 v156, v156, 0x3a800000, v200
	v_rsq_f32_e32 v156, v156
	v_add_f32_e32 v160, v160, v161
	v_add_f32_e32 v160, v160, v162
	v_add_f32_e32 v160, v160, v163
	v_fmamk_f32 v160, v160, 0x3a800000, v200
	v_rsq_f32_e32 v160, v160
	v_add_f32_e32 v164, v164, v165
	v_add_f32_e32 v164, v164, v166
	v_add_f32_e32 v164, v164, v167
	v_fmamk_f32 v164, v164, 0x3a800000, v200
	v_rsq_f32_e32 v164, v164
	ds_read_b128 v[12:15], v82 offset:16640
	ds_read_b128 v[16:19], v82 offset:16704
	s_waitcnt lgkmcnt(2)
	v_pk_mul_f32 v[4:5], v[4:5], v[134:135] op_sel_hi:[1,0]
	v_pk_mul_f32 v[6:7], v[6:7], v[134:135] op_sel_hi:[1,0]
	v_mul_f32_e32 v20, 0xbfb8aa3b, v4
	v_mul_f32_e32 v21, 0xbfb8aa3b, v5
	v_mul_f32_e32 v22, 0xbfb8aa3b, v6
	v_mul_f32_e32 v23, 0xbfb8aa3b, v7
	v_exp_f32_e32 v20, v20
	v_exp_f32_e32 v21, v21
	v_exp_f32_e32 v22, v22
	v_exp_f32_e32 v23, v23
	v_pk_mul_f32 v[8:9], v[8:9], v[134:135] op_sel_hi:[1,0]
	v_pk_mul_f32 v[10:11], v[10:11], v[134:135] op_sel_hi:[1,0]
	v_pk_add_f32 v[20:21], v[20:21], 1.0 op_sel_hi:[1,0]
	v_pk_add_f32 v[22:23], v[22:23], 1.0 op_sel_hi:[1,0]
	v_rcp_f32_e32 v20, v20
	v_rcp_f32_e32 v21, v21
	v_rcp_f32_e32 v22, v22
	v_rcp_f32_e32 v23, v23
	s_nop 0
	v_pk_mul_f32 v[4:5], v[4:5], v[20:21]
	v_pk_mul_f32 v[6:7], v[6:7], v[22:23]
	v_pk_mul_f32 v[4:5], v[8:9], v[4:5]
	v_pk_mul_f32 v[6:7], v[10:11], v[6:7]
	v_cvt_pk_bf16_f32 v20, v4, v5
	v_cvt_pk_bf16_f32 v21, v6, v7
	global_store_dwordx2 v[2:3], v[20:21], off
	v_lshl_add_u64 v[2:3], v[2:3], 0, s[98:99]
	ds_read_b128 v[4:7], v82 offset:33280
	ds_read_b128 v[8:11], v82 offset:33344
	s_waitcnt lgkmcnt(2)
	v_pk_mul_f32 v[12:13], v[12:13], v[138:139] op_sel_hi:[1,0]
	v_pk_mul_f32 v[14:15], v[14:15], v[138:139] op_sel_hi:[1,0]
	v_mul_f32_e32 v20, 0xbfb8aa3b, v12
	v_mul_f32_e32 v21, 0xbfb8aa3b, v13
	v_mul_f32_e32 v22, 0xbfb8aa3b, v14
	v_mul_f32_e32 v23, 0xbfb8aa3b, v15
	v_exp_f32_e32 v20, v20
	v_exp_f32_e32 v21, v21
	v_exp_f32_e32 v22, v22
	v_exp_f32_e32 v23, v23
	v_pk_mul_f32 v[16:17], v[16:17], v[138:139] op_sel_hi:[1,0]
	v_pk_mul_f32 v[18:19], v[18:19], v[138:139] op_sel_hi:[1,0]
	v_pk_add_f32 v[20:21], v[20:21], 1.0 op_sel_hi:[1,0]
	v_pk_add_f32 v[22:23], v[22:23], 1.0 op_sel_hi:[1,0]
	v_rcp_f32_e32 v20, v20
	v_rcp_f32_e32 v21, v21
	v_rcp_f32_e32 v22, v22
	v_rcp_f32_e32 v23, v23
	s_nop 0
	v_pk_mul_f32 v[12:13], v[12:13], v[20:21]
	v_pk_mul_f32 v[14:15], v[14:15], v[22:23]
	v_pk_mul_f32 v[12:13], v[16:17], v[12:13]
	v_pk_mul_f32 v[14:15], v[18:19], v[14:15]
	v_cvt_pk_bf16_f32 v20, v12, v13
	v_cvt_pk_bf16_f32 v21, v14, v15
	global_store_dwordx2 v[2:3], v[20:21], off
	v_lshl_add_u64 v[2:3], v[2:3], 0, s[98:99]
	ds_read_b128 v[12:15], v82 offset:49920
	ds_read_b128 v[16:19], v82 offset:49984
	s_waitcnt lgkmcnt(2)
	v_pk_mul_f32 v[4:5], v[4:5], v[144:145] op_sel_hi:[1,0]
	v_pk_mul_f32 v[6:7], v[6:7], v[144:145] op_sel_hi:[1,0]
	v_mul_f32_e32 v20, 0xbfb8aa3b, v4
	v_mul_f32_e32 v21, 0xbfb8aa3b, v5
	v_mul_f32_e32 v22, 0xbfb8aa3b, v6
	v_mul_f32_e32 v23, 0xbfb8aa3b, v7
	v_exp_f32_e32 v20, v20
	v_exp_f32_e32 v21, v21
	v_exp_f32_e32 v22, v22
	v_exp_f32_e32 v23, v23
	v_pk_mul_f32 v[8:9], v[8:9], v[144:145] op_sel_hi:[1,0]
	v_pk_mul_f32 v[10:11], v[10:11], v[144:145] op_sel_hi:[1,0]
	v_pk_add_f32 v[20:21], v[20:21], 1.0 op_sel_hi:[1,0]
	v_pk_add_f32 v[22:23], v[22:23], 1.0 op_sel_hi:[1,0]
	v_rcp_f32_e32 v20, v20
	v_rcp_f32_e32 v21, v21
	v_rcp_f32_e32 v22, v22
	v_rcp_f32_e32 v23, v23
	s_nop 0
	v_pk_mul_f32 v[4:5], v[4:5], v[20:21]
	v_pk_mul_f32 v[6:7], v[6:7], v[22:23]
	v_pk_mul_f32 v[4:5], v[8:9], v[4:5]
	v_pk_mul_f32 v[6:7], v[10:11], v[6:7]
	v_cvt_pk_bf16_f32 v20, v4, v5
	v_cvt_pk_bf16_f32 v21, v6, v7
	global_store_dwordx2 v[2:3], v[20:21], off
	v_lshl_add_u64 v[2:3], v[2:3], 0, s[98:99]
	ds_read_b128 v[4:7], v0
	ds_read_b128 v[8:11], v0 offset:64
	s_waitcnt lgkmcnt(2)
	v_pk_mul_f32 v[12:13], v[12:13], v[148:149] op_sel_hi:[1,0]
	v_pk_mul_f32 v[14:15], v[14:15], v[148:149] op_sel_hi:[1,0]
	v_mul_f32_e32 v20, 0xbfb8aa3b, v12
	v_mul_f32_e32 v21, 0xbfb8aa3b, v13
	v_mul_f32_e32 v22, 0xbfb8aa3b, v14
	v_mul_f32_e32 v23, 0xbfb8aa3b, v15
	v_exp_f32_e32 v20, v20
	v_exp_f32_e32 v21, v21
	v_exp_f32_e32 v22, v22
	v_exp_f32_e32 v23, v23
	v_pk_mul_f32 v[16:17], v[16:17], v[148:149] op_sel_hi:[1,0]
	v_pk_mul_f32 v[18:19], v[18:19], v[148:149] op_sel_hi:[1,0]
	v_pk_add_f32 v[20:21], v[20:21], 1.0 op_sel_hi:[1,0]
	v_pk_add_f32 v[22:23], v[22:23], 1.0 op_sel_hi:[1,0]
	v_rcp_f32_e32 v20, v20
	v_rcp_f32_e32 v21, v21
	v_rcp_f32_e32 v22, v22
	v_rcp_f32_e32 v23, v23
	s_nop 0
	v_pk_mul_f32 v[12:13], v[12:13], v[20:21]
	v_pk_mul_f32 v[14:15], v[14:15], v[22:23]
	v_pk_mul_f32 v[12:13], v[16:17], v[12:13]
	v_pk_mul_f32 v[14:15], v[18:19], v[14:15]
	v_cvt_pk_bf16_f32 v20, v12, v13
	v_cvt_pk_bf16_f32 v21, v14, v15
	global_store_dwordx2 v[2:3], v[20:21], off
	v_lshl_add_u64 v[2:3], v[2:3], 0, s[98:99]
	ds_read_b128 v[12:15], v0 offset:16640
	ds_read_b128 v[16:19], v0 offset:16704
	s_waitcnt lgkmcnt(2)
	v_pk_mul_f32 v[4:5], v[4:5], v[152:153] op_sel_hi:[1,0]
	v_pk_mul_f32 v[6:7], v[6:7], v[152:153] op_sel_hi:[1,0]
	v_mul_f32_e32 v20, 0xbfb8aa3b, v4
	v_mul_f32_e32 v21, 0xbfb8aa3b, v5
	v_mul_f32_e32 v22, 0xbfb8aa3b, v6
	v_mul_f32_e32 v23, 0xbfb8aa3b, v7
	v_exp_f32_e32 v20, v20
	v_exp_f32_e32 v21, v21
	v_exp_f32_e32 v22, v22
	v_exp_f32_e32 v23, v23
	v_pk_mul_f32 v[8:9], v[8:9], v[152:153] op_sel_hi:[1,0]
	v_pk_mul_f32 v[10:11], v[10:11], v[152:153] op_sel_hi:[1,0]
	v_pk_add_f32 v[20:21], v[20:21], 1.0 op_sel_hi:[1,0]
	v_pk_add_f32 v[22:23], v[22:23], 1.0 op_sel_hi:[1,0]
	v_rcp_f32_e32 v20, v20
	v_rcp_f32_e32 v21, v21
	v_rcp_f32_e32 v22, v22
	v_rcp_f32_e32 v23, v23
	s_nop 0
	v_pk_mul_f32 v[4:5], v[4:5], v[20:21]
	v_pk_mul_f32 v[6:7], v[6:7], v[22:23]
	v_pk_mul_f32 v[4:5], v[8:9], v[4:5]
	v_pk_mul_f32 v[6:7], v[10:11], v[6:7]
	v_cvt_pk_bf16_f32 v20, v4, v5
	v_cvt_pk_bf16_f32 v21, v6, v7
	global_store_dwordx2 v[2:3], v[20:21], off
	v_lshl_add_u64 v[2:3], v[2:3], 0, s[98:99]
	ds_read_b128 v[4:7], v0 offset:33280
	ds_read_b128 v[8:11], v0 offset:33344
	s_waitcnt lgkmcnt(2)
	v_pk_mul_f32 v[12:13], v[12:13], v[156:157] op_sel_hi:[1,0]
	v_pk_mul_f32 v[14:15], v[14:15], v[156:157] op_sel_hi:[1,0]
	v_mul_f32_e32 v20, 0xbfb8aa3b, v12
	v_mul_f32_e32 v21, 0xbfb8aa3b, v13
	v_mul_f32_e32 v22, 0xbfb8aa3b, v14
	v_mul_f32_e32 v23, 0xbfb8aa3b, v15
	v_exp_f32_e32 v20, v20
	v_exp_f32_e32 v21, v21
	v_exp_f32_e32 v22, v22
	v_exp_f32_e32 v23, v23
	v_pk_mul_f32 v[16:17], v[16:17], v[156:157] op_sel_hi:[1,0]
	v_pk_mul_f32 v[18:19], v[18:19], v[156:157] op_sel_hi:[1,0]
	v_pk_add_f32 v[20:21], v[20:21], 1.0 op_sel_hi:[1,0]
	v_pk_add_f32 v[22:23], v[22:23], 1.0 op_sel_hi:[1,0]
	v_rcp_f32_e32 v20, v20
	v_rcp_f32_e32 v21, v21
	v_rcp_f32_e32 v22, v22
	v_rcp_f32_e32 v23, v23
	s_nop 0
	v_pk_mul_f32 v[12:13], v[12:13], v[20:21]
	v_pk_mul_f32 v[14:15], v[14:15], v[22:23]
	v_pk_mul_f32 v[12:13], v[16:17], v[12:13]
	v_pk_mul_f32 v[14:15], v[18:19], v[14:15]
	v_cvt_pk_bf16_f32 v20, v12, v13
	v_cvt_pk_bf16_f32 v21, v14, v15
	global_store_dwordx2 v[2:3], v[20:21], off
	v_lshl_add_u64 v[2:3], v[2:3], 0, s[98:99]
	ds_read_b128 v[12:15], v0 offset:49920
	ds_read_b128 v[16:19], v0 offset:49984
	s_waitcnt lgkmcnt(2)
	v_pk_mul_f32 v[4:5], v[4:5], v[160:161] op_sel_hi:[1,0]
	v_pk_mul_f32 v[6:7], v[6:7], v[160:161] op_sel_hi:[1,0]
	v_mul_f32_e32 v20, 0xbfb8aa3b, v4
	v_mul_f32_e32 v21, 0xbfb8aa3b, v5
	v_mul_f32_e32 v22, 0xbfb8aa3b, v6
	v_mul_f32_e32 v23, 0xbfb8aa3b, v7
	v_exp_f32_e32 v20, v20
	v_exp_f32_e32 v21, v21
	v_exp_f32_e32 v22, v22
	v_exp_f32_e32 v23, v23
	v_pk_mul_f32 v[8:9], v[8:9], v[160:161] op_sel_hi:[1,0]
	v_pk_mul_f32 v[10:11], v[10:11], v[160:161] op_sel_hi:[1,0]
	v_pk_add_f32 v[20:21], v[20:21], 1.0 op_sel_hi:[1,0]
	v_pk_add_f32 v[22:23], v[22:23], 1.0 op_sel_hi:[1,0]
	v_rcp_f32_e32 v20, v20
	v_rcp_f32_e32 v21, v21
	v_rcp_f32_e32 v22, v22
	v_rcp_f32_e32 v23, v23
	s_nop 0
	v_pk_mul_f32 v[4:5], v[4:5], v[20:21]
	v_pk_mul_f32 v[6:7], v[6:7], v[22:23]
	v_pk_mul_f32 v[4:5], v[8:9], v[4:5]
	v_pk_mul_f32 v[6:7], v[10:11], v[6:7]
	v_cvt_pk_bf16_f32 v20, v4, v5
	v_cvt_pk_bf16_f32 v21, v6, v7
	global_store_dwordx2 v[2:3], v[20:21], off
	v_lshl_add_u64 v[2:3], v[2:3], 0, s[98:99]
	s_waitcnt lgkmcnt(0)
	v_pk_mul_f32 v[12:13], v[12:13], v[164:165] op_sel_hi:[1,0]
	v_pk_mul_f32 v[14:15], v[14:15], v[164:165] op_sel_hi:[1,0]
	v_mul_f32_e32 v20, 0xbfb8aa3b, v12
	v_mul_f32_e32 v21, 0xbfb8aa3b, v13
	v_mul_f32_e32 v22, 0xbfb8aa3b, v14
	v_mul_f32_e32 v23, 0xbfb8aa3b, v15
	v_exp_f32_e32 v20, v20
	v_exp_f32_e32 v21, v21
	v_exp_f32_e32 v22, v22
	v_exp_f32_e32 v23, v23
	v_pk_mul_f32 v[16:17], v[16:17], v[164:165] op_sel_hi:[1,0]
	v_pk_mul_f32 v[18:19], v[18:19], v[164:165] op_sel_hi:[1,0]
	v_pk_add_f32 v[20:21], v[20:21], 1.0 op_sel_hi:[1,0]
	v_pk_add_f32 v[22:23], v[22:23], 1.0 op_sel_hi:[1,0]
	v_rcp_f32_e32 v20, v20
	v_rcp_f32_e32 v21, v21
	v_rcp_f32_e32 v22, v22
	v_rcp_f32_e32 v23, v23
	s_nop 0
	v_pk_mul_f32 v[12:13], v[12:13], v[20:21]
	v_pk_mul_f32 v[14:15], v[14:15], v[22:23]
	v_pk_mul_f32 v[12:13], v[16:17], v[12:13]
	v_pk_mul_f32 v[14:15], v[18:19], v[14:15]
	v_cvt_pk_bf16_f32 v20, v12, v13
	v_cvt_pk_bf16_f32 v21, v14, v15
	global_store_dwordx2 v[2:3], v[20:21], off
	v_readlane_b32 s20, v255, 16
	s_barrier
	v_readlane_b32 s21, v255, 25
	v_ashrrev_i32_e32 v0, 31, v142
	v_lshrrev_b32_e32 v0, 26, v0
	v_add_u32_e32 v0, v142, v0
	v_ashrrev_i32_e32 v16, 6, v0
	v_bfe_i32 v0, v142, 27, 1
	v_lshlrev_b32_e32 v2, 4, v142
	v_lshrrev_b32_e32 v0, 22, v0
	v_add_u32_e32 v0, v2, v0
	v_and_b32_e32 v0, 0xfffffc00, v0
	v_sub_u32_e32 v0, v2, v0
	v_lshrrev_b32_e32 v3, 4, v0
	v_bitop3_b32 v3, v3, v0, 32 bitop3:0x6c
	v_ashrrev_i32_e32 v0, 31, v0
	v_lshrrev_b32_e32 v0, 26, v0
	v_add_u32_e32 v0, v3, v0
	v_ashrrev_i32_e32 v18, 6, v0
	v_mul_i32_i24_e32 v5, 64, v18
	v_sub_u32_e32 v3, v3, v5
	v_lshlrev_b32_e32 v4, 3, v16
	v_lshlrev_b32_e32 v0, 5, v16
	v_ashrrev_i16_sdwa v3, v217, sext(v3) dst_sel:DWORD dst_unused:UNUSED_PAD src0_sel:DWORD src1_sel:BYTE_0
	v_and_b32_e32 v4, 0x1ffff0, v4
	v_and_b32_e32 v0, 32, v0
	v_bfe_i32 v19, v3, 0, 16
	v_add_u32_e32 v0, v0, v19
	v_add_lshl_u32 v3, v18, v4, 11
	v_add_u32_e32 v2, 0x2000, v2
	v_lshl_add_u32 v0, v0, 1, v3
	v_ashrrev_i32_e32 v3, 31, v2
	v_lshrrev_b32_e32 v3, 22, v3
	v_add_u32_e32 v3, v2, v3
	v_ashrrev_i32_e32 v21, 10, v3
	v_mul_i32_i24_e32 v3, 0x400, v21
	v_sub_u32_e32 v2, v2, v3
	v_lshrrev_b32_e32 v3, 4, v2
	v_bitop3_b32 v2, v3, v2, 32 bitop3:0x6c
	v_ashrrev_i32_e32 v4, 31, v2
	v_ashrrev_i32_e32 v20, 6, v142
	v_lshrrev_b32_e32 v4, 26, v4
	v_readfirstlane_b32 s33, v20
	v_add_u32_e32 v4, v2, v4
	s_lshl_b32 s70, s33, 10
	v_ashrrev_i32_e32 v22, 6, v4
	v_and_b32_e32 v4, 0xc0, v4
	v_sub_u32_e32 v2, v2, v4
	s_add_u32 s44, s20, s44
	v_lshlrev_b32_e32 v3, 3, v21
	v_lshlrev_b32_e32 v5, 5, v21
	v_ashrrev_i16_sdwa v2, v217, sext(v2) dst_sel:DWORD dst_unused:UNUSED_PAD src0_sel:DWORD src1_sel:BYTE_0
	s_addc_u32 s45, s21, s45
	s_add_i32 s36, s70, 0
	v_and_b32_e32 v3, 0x1ffff0, v3
	v_and_b32_e32 v5, 32, v5
	v_bfe_i32 v23, v2, 0, 16
	s_add_i32 s37, s36, 0x10000
	v_add_u32_e32 v2, v5, v23
	v_add_lshl_u32 v3, v22, v3, 11
	s_mov_b32 m0, s37
	s_add_i32 s43, s36, 0x12000
	v_lshl_add_u32 v2, v2, 1, v3
	global_load_lds_dwordx4 v0, s[44:45]
	v_mov_b32_e32 v3, v1
	s_mov_b32 m0, s43
	v_lshl_add_u64 v[4:5], s[44:45], 0, v[0:1]
	v_lshl_add_u64 v[8:9], s[44:45], 0, v[2:3]
	global_load_lds_dwordx4 v2, s[44:45]
	s_mov_b32 m0, s36
	s_add_i32 s44, s36, 0x2000
	global_load_lds_dwordx4 v0, s[22:23]
	s_mov_b32 m0, s44
	v_lshl_add_u64 v[10:11], s[22:23], 0, v[0:1]
	v_lshl_add_u64 v[6:7], s[22:23], 0, v[2:3]
	global_load_lds_dwordx4 v2, s[22:23]
	s_or_b32 s22, s60, 0x180
	s_ashr_i32 s23, s22, 31
	s_lshl_b64 s[22:23], s[22:23], 11
	s_add_u32 s22, s20, s22
	s_addc_u32 s23, s21, s23
	s_add_i32 s45, s36, 0x14000
	s_mov_b32 m0, s45
	s_add_i32 s57, s36, 0x16000
	global_load_lds_dwordx4 v0, s[22:23]
	s_mov_b32 m0, s57
	s_add_i32 s60, s36, 0x4000
	global_load_lds_dwordx4 v2, s[22:23]
	s_mov_b32 m0, s60
	s_add_i32 s61, s36, 0x6000
	global_load_lds_dwordx4 v0, s[16:17]
	s_mov_b32 m0, s61
	v_ashrrev_i32_e32 v17, 8, v142
	global_load_lds_dwordx4 v2, s[16:17]
	v_lshl_add_u64 v[12:13], s[22:23], 0, v[0:1]
	v_lshl_add_u64 v[14:15], s[22:23], 0, v[2:3]
	v_cmp_eq_u32_e32 vcc, 1, v17
	s_and_saveexec_b64 s[22:23], vcc
	v_readlane_b32 s62, v253, 50
	s_cbranch_execz .LBB0_1136
	s_barrier

.LBB0_1140:
	s_or_b64 exec, exec, s[14:15]
	s_movk_i32 s11, 0x410
	v_lshrrev_b32_e32 v130, 2, v142
	v_lshlrev_b32_e32 v131, 1, v142
	v_and_b32_e32 v0, 15, v142
	v_and_b32_e32 v130, 0xfffffcc, v130
	v_and_b32_e32 v131, 0x180, v131
	v_add_u32_e32 v131, 0, v131
	v_lshlrev_b32_e32 v0, 2, v0
	v_mul_lo_u32 v130, v130, s11
	v_add3_u32 v130, v131, v0, v130
	s_waitcnt vmcnt(0)
	s_barrier
	ds_write2_b32 v130, v114, v126 offset1:16
	v_add_u32_e32 v114, 0x400, v130
	ds_write2_b32 v114, v115, v127 offset0:4 offset1:20
	v_add_u32_e32 v115, 0x800, v130
	ds_write2_b32 v115, v116, v128 offset0:8 offset1:24
	v_add_u32_e32 v116, 0xc00, v130
	ds_write2_b32 v116, v117, v129 offset0:12 offset1:28
	v_add_u32_e32 v117, 0x4000, v130
	ds_write2_b32 v117, v82, v94 offset0:64 offset1:80
	v_add_u32_e32 v94, 0x4400, v130
	ds_write2_b32 v94, v83, v95 offset0:68 offset1:84
	v_add_u32_e32 v95, 0x4800, v130
	ds_write2_b32 v95, v84, v96 offset0:72 offset1:88
	v_add_u32_e32 v96, 0x4c00, v130
	ds_write2_b32 v96, v85, v97 offset0:76 offset1:92
	v_add_u32_e32 v132, 0x8000, v130
	v_add_u32_e32 v97, 0x8400, v130
	v_add_u32_e32 v126, 0x8800, v130
	v_add_u32_e32 v127, 0x8c00, v130
	v_add_u32_e32 v133, 0xc000, v130
	v_add_u32_e32 v128, 0xc400, v130
	v_add_u32_e32 v129, 0xc800, v130
	v_add_u32_e32 v131, 0xcc00, v130
	ds_write2_b32 v132, v74, v78 offset0:128 offset1:144
	ds_write2_b32 v97, v75, v79 offset0:132 offset1:148
	ds_write2_b32 v126, v76, v80 offset0:136 offset1:152
	ds_write2_b32 v127, v77, v81 offset0:140 offset1:156
	ds_write2_b32 v133, v66, v70 offset0:192 offset1:208
	ds_write2_b32 v128, v67, v71 offset0:196 offset1:212
	ds_write2_b32 v129, v68, v72 offset0:200 offset1:216
	ds_write2_b32 v131, v69, v73 offset0:204 offset1:220
	ds_write2_b32 v130, v98, v118 offset0:128 offset1:144
	ds_write2_b32 v114, v99, v119 offset0:132 offset1:148
	ds_write2_b32 v115, v100, v120 offset0:136 offset1:152
	ds_write2_b32 v116, v101, v121 offset0:140 offset1:156
	ds_write2_b32 v117, v102, v122 offset0:192 offset1:208
	ds_write2_b32 v94, v103, v123 offset0:196 offset1:212
	ds_write2_b32 v95, v104, v124 offset0:200 offset1:216
	ds_write2_b32 v96, v105, v125 offset0:204 offset1:220
	ds_write2_b32 v97, v90, v110 offset1:16
	ds_write2_b32 v126, v91, v111 offset0:4 offset1:20
	ds_write2_b32 v127, v92, v112 offset0:8 offset1:24
	v_add_u32_e32 v90, 0x9000, v130
	ds_write2_b32 v90, v93, v113 offset0:12 offset1:28
	ds_write2_b32 v128, v86, v106 offset0:64 offset1:80
	ds_write2_b32 v129, v87, v107 offset0:68 offset1:84
	ds_write2_b32 v131, v88, v108 offset0:72 offset1:88
	v_ashrrev_i32_e32 v88, 5, v142
	v_add_u32_e32 v70, s12, v88
	v_ashrrev_i32_e32 v71, 31, v70
	v_add_u32_e32 v91, 0xd000, v130
	v_lshl_add_u64 v[72:73], v[70:71], 4, s[40:41]
	ds_write2_b32 v91, v89, v109 offset0:76 offset1:92
	s_waitcnt lgkmcnt(0)
	s_barrier
	global_load_dwordx4 v[134:137], v[72:73], off
	global_load_dwordx4 v[138:141], v[72:73], off offset:256
	global_load_dwordx4 v[144:147], v[72:73], off offset:512
	global_load_dwordx4 v[148:151], v[72:73], off offset:768
	global_load_dwordx4 v[152:155], v[72:73], off offset:1024
	global_load_dwordx4 v[156:159], v[72:73], off offset:1280
	global_load_dwordx4 v[160:163], v[72:73], off offset:1536
	global_load_dwordx4 v[164:167], v[72:73], off offset:1792
	v_lshlrev_b32_e32 v0, 3, v142
	v_lshlrev_b32_e32 v66, 2, v142
	v_and_b32_e32 v0, 0xe0, v0
	v_and_b32_e32 v69, 12, v66
	v_lshlrev_b32_e32 v66, 2, v0
	v_lshlrev_b32_e32 v67, 2, v69
	v_or_b32_e32 v0, s42, v0
	v_add3_u32 v68, 0, v66, v67
	v_ashrrev_i32_e32 v66, 1, v0
	v_readlane_b32 s14, v255, 27
	v_ashrrev_i32_e32 v67, 31, v66
	v_readlane_b32 s15, v255, 28
	v_lshlrev_b32_e32 v0, 1, v69
	s_mov_b32 s7, 0x800000
	v_lshl_add_u64 v[66:67], v[66:67], 1, s[14:15]
	v_lshl_add_u64 v[66:67], v[66:67], 0, v[0:1]
	v_mad_u64_u32 v[82:83], s[14:15], v88, s11, v[68:69]
	s_movk_i32 s16, 0x1600
	s_waitcnt vmcnt(0)
	v_mad_i64_i32 v[70:71], s[14:15], v70, s16, v[66:67]
	ds_read_b128 v[72:75], v82
	ds_read_b128 v[76:79], v82 offset:64
	v_add_u32_e32 v0, 0x10400, v82
	s_lshl_b32 s98, s16, 4
	s_mov_b32 s99, 0
	v_add_f32_e32 v134, v134, v135
	v_add_f32_e32 v134, v134, v136
	v_add_f32_e32 v134, v134, v137
	v_fmamk_f32 v134, v134, 0x3a800000, v200
	v_rsq_f32_e32 v134, v134
	v_add_f32_e32 v138, v138, v139
	v_add_f32_e32 v138, v138, v140
	v_add_f32_e32 v138, v138, v141
	v_fmamk_f32 v138, v138, 0x3a800000, v200
	v_rsq_f32_e32 v138, v138
	v_add_f32_e32 v144, v144, v145
	v_add_f32_e32 v144, v144, v146
	v_add_f32_e32 v144, v144, v147
	v_fmamk_f32 v144, v144, 0x3a800000, v200
	v_rsq_f32_e32 v144, v144
	v_add_f32_e32 v148, v148, v149
	v_add_f32_e32 v148, v148, v150
	v_add_f32_e32 v148, v148, v151
	v_fmamk_f32 v148, v148, 0x3a800000, v200
	v_rsq_f32_e32 v148, v148
	v_add_f32_e32 v152, v152, v153
	v_add_f32_e32 v152, v152, v154
	v_add_f32_e32 v152, v152, v155
	v_fmamk_f32 v152, v152, 0x3a800000, v200
	v_rsq_f32_e32 v152, v152
	v_add_f32_e32 v156, v156, v157
	v_add_f32_e32 v156, v156, v158
	v_add_f32_e32 v156, v156, v159
	v_fmamk_f32 v156, v156, 0x3a800000, v200
	v_rsq_f32_e32 v156, v156
	v_add_f32_e32 v160, v160, v161
	v_add_f32_e32 v160, v160, v162
	v_add_f32_e32 v160, v160, v163
	v_fmamk_f32 v160, v160, 0x3a800000, v200
	v_rsq_f32_e32 v160, v160
	v_add_f32_e32 v164, v164, v165
	v_add_f32_e32 v164, v164, v166
	v_add_f32_e32 v164, v164, v167
	v_fmamk_f32 v164, v164, 0x3a800000, v200
	v_rsq_f32_e32 v164, v164
	ds_read_b128 v[84:87], v82 offset:16640
	ds_read_b128 v[98:101], v82 offset:16704
	s_waitcnt lgkmcnt(2)
	v_pk_mul_f32 v[72:73], v[72:73], v[134:135] op_sel_hi:[1,0]
	v_pk_mul_f32 v[74:75], v[74:75], v[134:135] op_sel_hi:[1,0]
	v_mul_f32_e32 v102, 0xbfb8aa3b, v72
	v_mul_f32_e32 v103, 0xbfb8aa3b, v73
	v_mul_f32_e32 v104, 0xbfb8aa3b, v74
	v_mul_f32_e32 v105, 0xbfb8aa3b, v75
	v_exp_f32_e32 v102, v102
	v_exp_f32_e32 v103, v103
	v_exp_f32_e32 v104, v104
	v_exp_f32_e32 v105, v105
	v_pk_mul_f32 v[76:77], v[76:77], v[134:135] op_sel_hi:[1,0]
	v_pk_mul_f32 v[78:79], v[78:79], v[134:135] op_sel_hi:[1,0]
	v_pk_add_f32 v[102:103], v[102:103], 1.0 op_sel_hi:[1,0]
	v_pk_add_f32 v[104:105], v[104:105], 1.0 op_sel_hi:[1,0]
	v_rcp_f32_e32 v102, v102
	v_rcp_f32_e32 v103, v103
	v_rcp_f32_e32 v104, v104
	v_rcp_f32_e32 v105, v105
	s_nop 0
	v_pk_mul_f32 v[72:73], v[72:73], v[102:103]
	v_pk_mul_f32 v[74:75], v[74:75], v[104:105]
	v_pk_mul_f32 v[72:73], v[76:77], v[72:73]
	v_pk_mul_f32 v[74:75], v[78:79], v[74:75]
	v_cvt_pk_bf16_f32 v102, v72, v73
	v_cvt_pk_bf16_f32 v103, v74, v75
	global_store_dwordx2 v[70:71], v[102:103], off
	v_lshl_add_u64 v[70:71], v[70:71], 0, s[98:99]
	ds_read_b128 v[72:75], v82 offset:33280
	ds_read_b128 v[76:79], v82 offset:33344
	s_waitcnt lgkmcnt(2)
	v_pk_mul_f32 v[84:85], v[84:85], v[138:139] op_sel_hi:[1,0]
	v_pk_mul_f32 v[86:87], v[86:87], v[138:139] op_sel_hi:[1,0]
	v_mul_f32_e32 v102, 0xbfb8aa3b, v84
	v_mul_f32_e32 v103, 0xbfb8aa3b, v85
	v_mul_f32_e32 v104, 0xbfb8aa3b, v86
	v_mul_f32_e32 v105, 0xbfb8aa3b, v87
	v_exp_f32_e32 v102, v102
	v_exp_f32_e32 v103, v103
	v_exp_f32_e32 v104, v104
	v_exp_f32_e32 v105, v105
	v_pk_mul_f32 v[98:99], v[98:99], v[138:139] op_sel_hi:[1,0]
	v_pk_mul_f32 v[100:101], v[100:101], v[138:139] op_sel_hi:[1,0]
	v_pk_add_f32 v[102:103], v[102:103], 1.0 op_sel_hi:[1,0]
	v_pk_add_f32 v[104:105], v[104:105], 1.0 op_sel_hi:[1,0]
	v_rcp_f32_e32 v102, v102
	v_rcp_f32_e32 v103, v103
	v_rcp_f32_e32 v104, v104
	v_rcp_f32_e32 v105, v105
	s_nop 0
	v_pk_mul_f32 v[84:85], v[84:85], v[102:103]
	v_pk_mul_f32 v[86:87], v[86:87], v[104:105]
	v_pk_mul_f32 v[84:85], v[98:99], v[84:85]
	v_pk_mul_f32 v[86:87], v[100:101], v[86:87]
	v_cvt_pk_bf16_f32 v102, v84, v85
	v_cvt_pk_bf16_f32 v103, v86, v87
	global_store_dwordx2 v[70:71], v[102:103], off
	v_lshl_add_u64 v[70:71], v[70:71], 0, s[98:99]
	ds_read_b128 v[84:87], v82 offset:49920
	ds_read_b128 v[98:101], v82 offset:49984
	s_waitcnt lgkmcnt(2)
	v_pk_mul_f32 v[72:73], v[72:73], v[144:145] op_sel_hi:[1,0]
	v_pk_mul_f32 v[74:75], v[74:75], v[144:145] op_sel_hi:[1,0]
	v_mul_f32_e32 v102, 0xbfb8aa3b, v72
	v_mul_f32_e32 v103, 0xbfb8aa3b, v73
	v_mul_f32_e32 v104, 0xbfb8aa3b, v74
	v_mul_f32_e32 v105, 0xbfb8aa3b, v75
	v_exp_f32_e32 v102, v102
	v_exp_f32_e32 v103, v103
	v_exp_f32_e32 v104, v104
	v_exp_f32_e32 v105, v105
	v_pk_mul_f32 v[76:77], v[76:77], v[144:145] op_sel_hi:[1,0]
	v_pk_mul_f32 v[78:79], v[78:79], v[144:145] op_sel_hi:[1,0]
	v_pk_add_f32 v[102:103], v[102:103], 1.0 op_sel_hi:[1,0]
	v_pk_add_f32 v[104:105], v[104:105], 1.0 op_sel_hi:[1,0]
	v_rcp_f32_e32 v102, v102
	v_rcp_f32_e32 v103, v103
	v_rcp_f32_e32 v104, v104
	v_rcp_f32_e32 v105, v105
	s_nop 0
	v_pk_mul_f32 v[72:73], v[72:73], v[102:103]
	v_pk_mul_f32 v[74:75], v[74:75], v[104:105]
	v_pk_mul_f32 v[72:73], v[76:77], v[72:73]
	v_pk_mul_f32 v[74:75], v[78:79], v[74:75]
	v_cvt_pk_bf16_f32 v102, v72, v73
	v_cvt_pk_bf16_f32 v103, v74, v75
	global_store_dwordx2 v[70:71], v[102:103], off
	v_lshl_add_u64 v[70:71], v[70:71], 0, s[98:99]
	ds_read_b128 v[72:75], v0
	ds_read_b128 v[76:79], v0 offset:64
	s_waitcnt lgkmcnt(2)
	v_pk_mul_f32 v[84:85], v[84:85], v[148:149] op_sel_hi:[1,0]
	v_pk_mul_f32 v[86:87], v[86:87], v[148:149] op_sel_hi:[1,0]
	v_mul_f32_e32 v102, 0xbfb8aa3b, v84
	v_mul_f32_e32 v103, 0xbfb8aa3b, v85
	v_mul_f32_e32 v104, 0xbfb8aa3b, v86
	v_mul_f32_e32 v105, 0xbfb8aa3b, v87
	v_exp_f32_e32 v102, v102
	v_exp_f32_e32 v103, v103
	v_exp_f32_e32 v104, v104
	v_exp_f32_e32 v105, v105
	v_pk_mul_f32 v[98:99], v[98:99], v[148:149] op_sel_hi:[1,0]
	v_pk_mul_f32 v[100:101], v[100:101], v[148:149] op_sel_hi:[1,0]
	v_pk_add_f32 v[102:103], v[102:103], 1.0 op_sel_hi:[1,0]
	v_pk_add_f32 v[104:105], v[104:105], 1.0 op_sel_hi:[1,0]
	v_rcp_f32_e32 v102, v102
	v_rcp_f32_e32 v103, v103
	v_rcp_f32_e32 v104, v104
	v_rcp_f32_e32 v105, v105
	s_nop 0
	v_pk_mul_f32 v[84:85], v[84:85], v[102:103]
	v_pk_mul_f32 v[86:87], v[86:87], v[104:105]
	v_pk_mul_f32 v[84:85], v[98:99], v[84:85]
	v_pk_mul_f32 v[86:87], v[100:101], v[86:87]
	v_cvt_pk_bf16_f32 v102, v84, v85
	v_cvt_pk_bf16_f32 v103, v86, v87
	global_store_dwordx2 v[70:71], v[102:103], off
	v_lshl_add_u64 v[70:71], v[70:71], 0, s[98:99]
	ds_read_b128 v[84:87], v0 offset:16640
	ds_read_b128 v[98:101], v0 offset:16704
	s_waitcnt lgkmcnt(2)
	v_pk_mul_f32 v[72:73], v[72:73], v[152:153] op_sel_hi:[1,0]
	v_pk_mul_f32 v[74:75], v[74:75], v[152:153] op_sel_hi:[1,0]
	v_mul_f32_e32 v102, 0xbfb8aa3b, v72
	v_mul_f32_e32 v103, 0xbfb8aa3b, v73
	v_mul_f32_e32 v104, 0xbfb8aa3b, v74
	v_mul_f32_e32 v105, 0xbfb8aa3b, v75
	v_exp_f32_e32 v102, v102
	v_exp_f32_e32 v103, v103
	v_exp_f32_e32 v104, v104
	v_exp_f32_e32 v105, v105
	v_pk_mul_f32 v[76:77], v[76:77], v[152:153] op_sel_hi:[1,0]
	v_pk_mul_f32 v[78:79], v[78:79], v[152:153] op_sel_hi:[1,0]
	v_pk_add_f32 v[102:103], v[102:103], 1.0 op_sel_hi:[1,0]
	v_pk_add_f32 v[104:105], v[104:105], 1.0 op_sel_hi:[1,0]
	v_rcp_f32_e32 v102, v102
	v_rcp_f32_e32 v103, v103
	v_rcp_f32_e32 v104, v104
	v_rcp_f32_e32 v105, v105
	s_nop 0
	v_pk_mul_f32 v[72:73], v[72:73], v[102:103]
	v_pk_mul_f32 v[74:75], v[74:75], v[104:105]
	v_pk_mul_f32 v[72:73], v[76:77], v[72:73]
	v_pk_mul_f32 v[74:75], v[78:79], v[74:75]
	v_cvt_pk_bf16_f32 v102, v72, v73
	v_cvt_pk_bf16_f32 v103, v74, v75
	global_store_dwordx2 v[70:71], v[102:103], off
	v_lshl_add_u64 v[70:71], v[70:71], 0, s[98:99]
	ds_read_b128 v[72:75], v0 offset:33280
	ds_read_b128 v[76:79], v0 offset:33344
	s_waitcnt lgkmcnt(2)
	v_pk_mul_f32 v[84:85], v[84:85], v[156:157] op_sel_hi:[1,0]
	v_pk_mul_f32 v[86:87], v[86:87], v[156:157] op_sel_hi:[1,0]
	v_mul_f32_e32 v102, 0xbfb8aa3b, v84
	v_mul_f32_e32 v103, 0xbfb8aa3b, v85
	v_mul_f32_e32 v104, 0xbfb8aa3b, v86
	v_mul_f32_e32 v105, 0xbfb8aa3b, v87
	v_exp_f32_e32 v102, v102
	v_exp_f32_e32 v103, v103
	v_exp_f32_e32 v104, v104
	v_exp_f32_e32 v105, v105
	v_pk_mul_f32 v[98:99], v[98:99], v[156:157] op_sel_hi:[1,0]
	v_pk_mul_f32 v[100:101], v[100:101], v[156:157] op_sel_hi:[1,0]
	v_pk_add_f32 v[102:103], v[102:103], 1.0 op_sel_hi:[1,0]
	v_pk_add_f32 v[104:105], v[104:105], 1.0 op_sel_hi:[1,0]
	v_rcp_f32_e32 v102, v102
	v_rcp_f32_e32 v103, v103
	v_rcp_f32_e32 v104, v104
	v_rcp_f32_e32 v105, v105
	s_nop 0
	v_pk_mul_f32 v[84:85], v[84:85], v[102:103]
	v_pk_mul_f32 v[86:87], v[86:87], v[104:105]
	v_pk_mul_f32 v[84:85], v[98:99], v[84:85]
	v_pk_mul_f32 v[86:87], v[100:101], v[86:87]
	v_cvt_pk_bf16_f32 v102, v84, v85
	v_cvt_pk_bf16_f32 v103, v86, v87
	global_store_dwordx2 v[70:71], v[102:103], off
	v_lshl_add_u64 v[70:71], v[70:71], 0, s[98:99]
	ds_read_b128 v[84:87], v0 offset:49920
	ds_read_b128 v[98:101], v0 offset:49984
	s_waitcnt lgkmcnt(2)
	v_pk_mul_f32 v[72:73], v[72:73], v[160:161] op_sel_hi:[1,0]
	v_pk_mul_f32 v[74:75], v[74:75], v[160:161] op_sel_hi:[1,0]
	v_mul_f32_e32 v102, 0xbfb8aa3b, v72
	v_mul_f32_e32 v103, 0xbfb8aa3b, v73
	v_mul_f32_e32 v104, 0xbfb8aa3b, v74
	v_mul_f32_e32 v105, 0xbfb8aa3b, v75
	v_exp_f32_e32 v102, v102
	v_exp_f32_e32 v103, v103
	v_exp_f32_e32 v104, v104
	v_exp_f32_e32 v105, v105
	v_pk_mul_f32 v[76:77], v[76:77], v[160:161] op_sel_hi:[1,0]
	v_pk_mul_f32 v[78:79], v[78:79], v[160:161] op_sel_hi:[1,0]
	v_pk_add_f32 v[102:103], v[102:103], 1.0 op_sel_hi:[1,0]
	v_pk_add_f32 v[104:105], v[104:105], 1.0 op_sel_hi:[1,0]
	v_rcp_f32_e32 v102, v102
	v_rcp_f32_e32 v103, v103
	v_rcp_f32_e32 v104, v104
	v_rcp_f32_e32 v105, v105
	s_nop 0
	v_pk_mul_f32 v[72:73], v[72:73], v[102:103]
	v_pk_mul_f32 v[74:75], v[74:75], v[104:105]
	v_pk_mul_f32 v[72:73], v[76:77], v[72:73]
	v_pk_mul_f32 v[74:75], v[78:79], v[74:75]
	v_cvt_pk_bf16_f32 v102, v72, v73
	v_cvt_pk_bf16_f32 v103, v74, v75
	global_store_dwordx2 v[70:71], v[102:103], off
	v_lshl_add_u64 v[70:71], v[70:71], 0, s[98:99]
	s_waitcnt lgkmcnt(0)
	v_pk_mul_f32 v[84:85], v[84:85], v[164:165] op_sel_hi:[1,0]
	v_pk_mul_f32 v[86:87], v[86:87], v[164:165] op_sel_hi:[1,0]
	v_mul_f32_e32 v102, 0xbfb8aa3b, v84
	v_mul_f32_e32 v103, 0xbfb8aa3b, v85
	v_mul_f32_e32 v104, 0xbfb8aa3b, v86
	v_mul_f32_e32 v105, 0xbfb8aa3b, v87
	v_exp_f32_e32 v102, v102
	v_exp_f32_e32 v103, v103
	v_exp_f32_e32 v104, v104
	v_exp_f32_e32 v105, v105
	v_pk_mul_f32 v[98:99], v[98:99], v[164:165] op_sel_hi:[1,0]
	v_pk_mul_f32 v[100:101], v[100:101], v[164:165] op_sel_hi:[1,0]
	v_pk_add_f32 v[102:103], v[102:103], 1.0 op_sel_hi:[1,0]
	v_pk_add_f32 v[104:105], v[104:105], 1.0 op_sel_hi:[1,0]
	v_rcp_f32_e32 v102, v102
	v_rcp_f32_e32 v103, v103
	v_rcp_f32_e32 v104, v104
	v_rcp_f32_e32 v105, v105
	s_nop 0
	v_pk_mul_f32 v[84:85], v[84:85], v[102:103]
	v_pk_mul_f32 v[86:87], v[86:87], v[104:105]
	v_pk_mul_f32 v[84:85], v[98:99], v[84:85]
	v_pk_mul_f32 v[86:87], v[100:101], v[86:87]
	v_cvt_pk_bf16_f32 v102, v84, v85
	v_cvt_pk_bf16_f32 v103, v86, v87
	global_store_dwordx2 v[70:71], v[102:103], off
	s_barrier
	ds_write2_b32 v130, v2, v18 offset1:16
	ds_write2_b32 v114, v3, v19 offset0:4 offset1:20
	ds_write2_b32 v115, v4, v20 offset0:8 offset1:24
	ds_write2_b32 v116, v5, v21 offset0:12 offset1:28
	ds_write2_b32 v117, v6, v22 offset0:64 offset1:80
	ds_write2_b32 v94, v7, v23 offset0:68 offset1:84
	ds_write2_b32 v95, v8, v24 offset0:72 offset1:88
	ds_write2_b32 v96, v9, v25 offset0:76 offset1:92
	ds_write2_b32 v132, v10, v26 offset0:128 offset1:144
	ds_write2_b32 v97, v11, v27 offset0:132 offset1:148
	ds_write2_b32 v126, v12, v28 offset0:136 offset1:152
	ds_write2_b32 v127, v13, v29 offset0:140 offset1:156
	ds_write2_b32 v133, v14, v30 offset0:192 offset1:208
	ds_write2_b32 v128, v15, v31 offset0:196 offset1:212
	ds_write2_b32 v129, v16, v32 offset0:200 offset1:216
	ds_write2_b32 v131, v17, v33 offset0:204 offset1:220
	ds_write2_b32 v130, v34, v50 offset0:128 offset1:144
	ds_write2_b32 v114, v35, v51 offset0:132 offset1:148
	ds_write2_b32 v115, v36, v52 offset0:136 offset1:152
	ds_write2_b32 v116, v37, v53 offset0:140 offset1:156
	ds_write2_b32 v117, v38, v54 offset0:192 offset1:208
	ds_write2_b32 v94, v39, v55 offset0:196 offset1:212
	ds_write2_b32 v95, v40, v56 offset0:200 offset1:216
	ds_write2_b32 v96, v41, v57 offset0:204 offset1:220
	ds_write2_b32 v97, v42, v58 offset1:16
	ds_write2_b32 v126, v43, v59 offset0:4 offset1:20
	ds_write2_b32 v127, v44, v60 offset0:8 offset1:24
	ds_write2_b32 v90, v45, v61 offset0:12 offset1:28
	ds_write2_b32 v128, v46, v62 offset0:64 offset1:80
	ds_write2_b32 v129, v47, v63 offset0:68 offset1:84
	ds_write2_b32 v131, v48, v64 offset0:72 offset1:88
	ds_write2_b32 v91, v49, v65 offset0:76 offset1:92
	v_add_u32_e32 v2, s10, v88
	v_ashrrev_i32_e32 v3, 31, v2
	v_lshl_add_u64 v[4:5], v[2:3], 4, s[40:41]
	s_waitcnt lgkmcnt(0)
	s_barrier
	global_load_dwordx4 v[134:137], v[4:5], off
	global_load_dwordx4 v[138:141], v[4:5], off offset:256
	global_load_dwordx4 v[144:147], v[4:5], off offset:512
	global_load_dwordx4 v[148:151], v[4:5], off offset:768
	global_load_dwordx4 v[152:155], v[4:5], off offset:1024
	global_load_dwordx4 v[156:159], v[4:5], off offset:1280
	global_load_dwordx4 v[160:163], v[4:5], off offset:1536
	global_load_dwordx4 v[164:167], v[4:5], off offset:1792
	s_waitcnt vmcnt(0)
	v_mad_i64_i32 v[2:3], s[12:13], v2, s16, v[66:67]
	ds_read_b128 v[4:7], v82
	ds_read_b128 v[8:11], v82 offset:64
	v_add_u32_e32 v0, 0x10400, v82
	s_lshl_b32 s98, s16, 4
	s_mov_b32 s99, 0
	v_add_f32_e32 v134, v134, v135
	v_add_f32_e32 v134, v134, v136
	v_add_f32_e32 v134, v134, v137
	v_fmamk_f32 v134, v134, 0x3a800000, v200
	v_rsq_f32_e32 v134, v134
	v_add_f32_e32 v138, v138, v139
	v_add_f32_e32 v138, v138, v140
	v_add_f32_e32 v138, v138, v141
	v_fmamk_f32 v138, v138, 0x3a800000, v200
	v_rsq_f32_e32 v138, v138
	v_add_f32_e32 v144, v144, v145
	v_add_f32_e32 v144, v144, v146
	v_add_f32_e32 v144, v144, v147
	v_fmamk_f32 v144, v144, 0x3a800000, v200
	v_rsq_f32_e32 v144, v144
	v_add_f32_e32 v148, v148, v149
	v_add_f32_e32 v148, v148, v150
	v_add_f32_e32 v148, v148, v151
	v_fmamk_f32 v148, v148, 0x3a800000, v200
	v_rsq_f32_e32 v148, v148
	v_add_f32_e32 v152, v152, v153
	v_add_f32_e32 v152, v152, v154
	v_add_f32_e32 v152, v152, v155
	v_fmamk_f32 v152, v152, 0x3a800000, v200
	v_rsq_f32_e32 v152, v152
	v_add_f32_e32 v156, v156, v157
	v_add_f32_e32 v156, v156, v158
	v_add_f32_e32 v156, v156, v159
	v_fmamk_f32 v156, v156, 0x3a800000, v200
	v_rsq_f32_e32 v156, v156
	v_add_f32_e32 v160, v160, v161
	v_add_f32_e32 v160, v160, v162
	v_add_f32_e32 v160, v160, v163
	v_fmamk_f32 v160, v160, 0x3a800000, v200
	v_rsq_f32_e32 v160, v160
	v_add_f32_e32 v164, v164, v165
	v_add_f32_e32 v164, v164, v166
	v_add_f32_e32 v164, v164, v167
	v_fmamk_f32 v164, v164, 0x3a800000, v200
	v_rsq_f32_e32 v164, v164
	ds_read_b128 v[12:15], v82 offset:16640
	ds_read_b128 v[16:19], v82 offset:16704
	s_waitcnt lgkmcnt(2)
	v_pk_mul_f32 v[4:5], v[4:5], v[134:135] op_sel_hi:[1,0]
	v_pk_mul_f32 v[6:7], v[6:7], v[134:135] op_sel_hi:[1,0]
	v_mul_f32_e32 v20, 0xbfb8aa3b, v4
	v_mul_f32_e32 v21, 0xbfb8aa3b, v5
	v_mul_f32_e32 v22, 0xbfb8aa3b, v6
	v_mul_f32_e32 v23, 0xbfb8aa3b, v7
	v_exp_f32_e32 v20, v20
	v_exp_f32_e32 v21, v21
	v_exp_f32_e32 v22, v22
	v_exp_f32_e32 v23, v23
	v_pk_mul_f32 v[8:9], v[8:9], v[134:135] op_sel_hi:[1,0]
	v_pk_mul_f32 v[10:11], v[10:11], v[134:135] op_sel_hi:[1,0]
	v_pk_add_f32 v[20:21], v[20:21], 1.0 op_sel_hi:[1,0]
	v_pk_add_f32 v[22:23], v[22:23], 1.0 op_sel_hi:[1,0]
	v_rcp_f32_e32 v20, v20
	v_rcp_f32_e32 v21, v21
	v_rcp_f32_e32 v22, v22
	v_rcp_f32_e32 v23, v23
	s_nop 0
	v_pk_mul_f32 v[4:5], v[4:5], v[20:21]
	v_pk_mul_f32 v[6:7], v[6:7], v[22:23]
	v_pk_mul_f32 v[4:5], v[8:9], v[4:5]
	v_pk_mul_f32 v[6:7], v[10:11], v[6:7]
	v_cvt_pk_bf16_f32 v20, v4, v5
	v_cvt_pk_bf16_f32 v21, v6, v7
	global_store_dwordx2 v[2:3], v[20:21], off
	v_lshl_add_u64 v[2:3], v[2:3], 0, s[98:99]
	ds_read_b128 v[4:7], v82 offset:33280
	ds_read_b128 v[8:11], v82 offset:33344
	s_waitcnt lgkmcnt(2)
	v_pk_mul_f32 v[12:13], v[12:13], v[138:139] op_sel_hi:[1,0]
	v_pk_mul_f32 v[14:15], v[14:15], v[138:139] op_sel_hi:[1,0]
	v_mul_f32_e32 v20, 0xbfb8aa3b, v12
	v_mul_f32_e32 v21, 0xbfb8aa3b, v13
	v_mul_f32_e32 v22, 0xbfb8aa3b, v14
	v_mul_f32_e32 v23, 0xbfb8aa3b, v15
	v_exp_f32_e32 v20, v20
	v_exp_f32_e32 v21, v21
	v_exp_f32_e32 v22, v22
	v_exp_f32_e32 v23, v23
	v_pk_mul_f32 v[16:17], v[16:17], v[138:139] op_sel_hi:[1,0]
	v_pk_mul_f32 v[18:19], v[18:19], v[138:139] op_sel_hi:[1,0]
	v_pk_add_f32 v[20:21], v[20:21], 1.0 op_sel_hi:[1,0]
	v_pk_add_f32 v[22:23], v[22:23], 1.0 op_sel_hi:[1,0]
	v_rcp_f32_e32 v20, v20
	v_rcp_f32_e32 v21, v21
	v_rcp_f32_e32 v22, v22
	v_rcp_f32_e32 v23, v23
	s_nop 0
	v_pk_mul_f32 v[12:13], v[12:13], v[20:21]
	v_pk_mul_f32 v[14:15], v[14:15], v[22:23]
	v_pk_mul_f32 v[12:13], v[16:17], v[12:13]
	v_pk_mul_f32 v[14:15], v[18:19], v[14:15]
	v_cvt_pk_bf16_f32 v20, v12, v13
	v_cvt_pk_bf16_f32 v21, v14, v15
	global_store_dwordx2 v[2:3], v[20:21], off
	v_lshl_add_u64 v[2:3], v[2:3], 0, s[98:99]
	ds_read_b128 v[12:15], v82 offset:49920
	ds_read_b128 v[16:19], v82 offset:49984
	s_waitcnt lgkmcnt(2)
	v_pk_mul_f32 v[4:5], v[4:5], v[144:145] op_sel_hi:[1,0]
	v_pk_mul_f32 v[6:7], v[6:7], v[144:145] op_sel_hi:[1,0]
	v_mul_f32_e32 v20, 0xbfb8aa3b, v4
	v_mul_f32_e32 v21, 0xbfb8aa3b, v5
	v_mul_f32_e32 v22, 0xbfb8aa3b, v6
	v_mul_f32_e32 v23, 0xbfb8aa3b, v7
	v_exp_f32_e32 v20, v20
	v_exp_f32_e32 v21, v21
	v_exp_f32_e32 v22, v22
	v_exp_f32_e32 v23, v23
	v_pk_mul_f32 v[8:9], v[8:9], v[144:145] op_sel_hi:[1,0]
	v_pk_mul_f32 v[10:11], v[10:11], v[144:145] op_sel_hi:[1,0]
	v_pk_add_f32 v[20:21], v[20:21], 1.0 op_sel_hi:[1,0]
	v_pk_add_f32 v[22:23], v[22:23], 1.0 op_sel_hi:[1,0]
	v_rcp_f32_e32 v20, v20
	v_rcp_f32_e32 v21, v21
	v_rcp_f32_e32 v22, v22
	v_rcp_f32_e32 v23, v23
	s_nop 0
	v_pk_mul_f32 v[4:5], v[4:5], v[20:21]
	v_pk_mul_f32 v[6:7], v[6:7], v[22:23]
	v_pk_mul_f32 v[4:5], v[8:9], v[4:5]
	v_pk_mul_f32 v[6:7], v[10:11], v[6:7]
	v_cvt_pk_bf16_f32 v20, v4, v5
	v_cvt_pk_bf16_f32 v21, v6, v7
	global_store_dwordx2 v[2:3], v[20:21], off
	v_lshl_add_u64 v[2:3], v[2:3], 0, s[98:99]
	ds_read_b128 v[4:7], v0
	ds_read_b128 v[8:11], v0 offset:64
	s_waitcnt lgkmcnt(2)
	v_pk_mul_f32 v[12:13], v[12:13], v[148:149] op_sel_hi:[1,0]
	v_pk_mul_f32 v[14:15], v[14:15], v[148:149] op_sel_hi:[1,0]
	v_mul_f32_e32 v20, 0xbfb8aa3b, v12
	v_mul_f32_e32 v21, 0xbfb8aa3b, v13
	v_mul_f32_e32 v22, 0xbfb8aa3b, v14
	v_mul_f32_e32 v23, 0xbfb8aa3b, v15
	v_exp_f32_e32 v20, v20
	v_exp_f32_e32 v21, v21
	v_exp_f32_e32 v22, v22
	v_exp_f32_e32 v23, v23
	v_pk_mul_f32 v[16:17], v[16:17], v[148:149] op_sel_hi:[1,0]
	v_pk_mul_f32 v[18:19], v[18:19], v[148:149] op_sel_hi:[1,0]
	v_pk_add_f32 v[20:21], v[20:21], 1.0 op_sel_hi:[1,0]
	v_pk_add_f32 v[22:23], v[22:23], 1.0 op_sel_hi:[1,0]
	v_rcp_f32_e32 v20, v20
	v_rcp_f32_e32 v21, v21
	v_rcp_f32_e32 v22, v22
	v_rcp_f32_e32 v23, v23
	s_nop 0
	v_pk_mul_f32 v[12:13], v[12:13], v[20:21]
	v_pk_mul_f32 v[14:15], v[14:15], v[22:23]
	v_pk_mul_f32 v[12:13], v[16:17], v[12:13]
	v_pk_mul_f32 v[14:15], v[18:19], v[14:15]
	v_cvt_pk_bf16_f32 v20, v12, v13
	v_cvt_pk_bf16_f32 v21, v14, v15
	global_store_dwordx2 v[2:3], v[20:21], off
	v_lshl_add_u64 v[2:3], v[2:3], 0, s[98:99]
	ds_read_b128 v[12:15], v0 offset:16640
	ds_read_b128 v[16:19], v0 offset:16704
	s_waitcnt lgkmcnt(2)
	v_pk_mul_f32 v[4:5], v[4:5], v[152:153] op_sel_hi:[1,0]
	v_pk_mul_f32 v[6:7], v[6:7], v[152:153] op_sel_hi:[1,0]
	v_mul_f32_e32 v20, 0xbfb8aa3b, v4
	v_mul_f32_e32 v21, 0xbfb8aa3b, v5
	v_mul_f32_e32 v22, 0xbfb8aa3b, v6
	v_mul_f32_e32 v23, 0xbfb8aa3b, v7
	v_exp_f32_e32 v20, v20
	v_exp_f32_e32 v21, v21
	v_exp_f32_e32 v22, v22
	v_exp_f32_e32 v23, v23
	v_pk_mul_f32 v[8:9], v[8:9], v[152:153] op_sel_hi:[1,0]
	v_pk_mul_f32 v[10:11], v[10:11], v[152:153] op_sel_hi:[1,0]
	v_pk_add_f32 v[20:21], v[20:21], 1.0 op_sel_hi:[1,0]
	v_pk_add_f32 v[22:23], v[22:23], 1.0 op_sel_hi:[1,0]
	v_rcp_f32_e32 v20, v20
	v_rcp_f32_e32 v21, v21
	v_rcp_f32_e32 v22, v22
	v_rcp_f32_e32 v23, v23
	s_nop 0
	v_pk_mul_f32 v[4:5], v[4:5], v[20:21]
	v_pk_mul_f32 v[6:7], v[6:7], v[22:23]
	v_pk_mul_f32 v[4:5], v[8:9], v[4:5]
	v_pk_mul_f32 v[6:7], v[10:11], v[6:7]
	v_cvt_pk_bf16_f32 v20, v4, v5
	v_cvt_pk_bf16_f32 v21, v6, v7
	global_store_dwordx2 v[2:3], v[20:21], off
	v_lshl_add_u64 v[2:3], v[2:3], 0, s[98:99]
	ds_read_b128 v[4:7], v0 offset:33280
	ds_read_b128 v[8:11], v0 offset:33344
	s_waitcnt lgkmcnt(2)
	v_pk_mul_f32 v[12:13], v[12:13], v[156:157] op_sel_hi:[1,0]
	v_pk_mul_f32 v[14:15], v[14:15], v[156:157] op_sel_hi:[1,0]
	v_mul_f32_e32 v20, 0xbfb8aa3b, v12
	v_mul_f32_e32 v21, 0xbfb8aa3b, v13
	v_mul_f32_e32 v22, 0xbfb8aa3b, v14
	v_mul_f32_e32 v23, 0xbfb8aa3b, v15
	v_exp_f32_e32 v20, v20
	v_exp_f32_e32 v21, v21
	v_exp_f32_e32 v22, v22
	v_exp_f32_e32 v23, v23
	v_pk_mul_f32 v[16:17], v[16:17], v[156:157] op_sel_hi:[1,0]
	v_pk_mul_f32 v[18:19], v[18:19], v[156:157] op_sel_hi:[1,0]
	v_pk_add_f32 v[20:21], v[20:21], 1.0 op_sel_hi:[1,0]
	v_pk_add_f32 v[22:23], v[22:23], 1.0 op_sel_hi:[1,0]
	v_rcp_f32_e32 v20, v20
	v_rcp_f32_e32 v21, v21
	v_rcp_f32_e32 v22, v22
	v_rcp_f32_e32 v23, v23
	s_nop 0
	v_pk_mul_f32 v[12:13], v[12:13], v[20:21]
	v_pk_mul_f32 v[14:15], v[14:15], v[22:23]
	v_pk_mul_f32 v[12:13], v[16:17], v[12:13]
	v_pk_mul_f32 v[14:15], v[18:19], v[14:15]
	v_cvt_pk_bf16_f32 v20, v12, v13
	v_cvt_pk_bf16_f32 v21, v14, v15
	global_store_dwordx2 v[2:3], v[20:21], off
	v_lshl_add_u64 v[2:3], v[2:3], 0, s[98:99]
	ds_read_b128 v[12:15], v0 offset:49920
	ds_read_b128 v[16:19], v0 offset:49984
	s_waitcnt lgkmcnt(2)
	v_pk_mul_f32 v[4:5], v[4:5], v[160:161] op_sel_hi:[1,0]
	v_pk_mul_f32 v[6:7], v[6:7], v[160:161] op_sel_hi:[1,0]
	v_mul_f32_e32 v20, 0xbfb8aa3b, v4
	v_mul_f32_e32 v21, 0xbfb8aa3b, v5
	v_mul_f32_e32 v22, 0xbfb8aa3b, v6
	v_mul_f32_e32 v23, 0xbfb8aa3b, v7
	v_exp_f32_e32 v20, v20
	v_exp_f32_e32 v21, v21
	v_exp_f32_e32 v22, v22
	v_exp_f32_e32 v23, v23
	v_pk_mul_f32 v[8:9], v[8:9], v[160:161] op_sel_hi:[1,0]
	v_pk_mul_f32 v[10:11], v[10:11], v[160:161] op_sel_hi:[1,0]
	v_pk_add_f32 v[20:21], v[20:21], 1.0 op_sel_hi:[1,0]
	v_pk_add_f32 v[22:23], v[22:23], 1.0 op_sel_hi:[1,0]
	v_rcp_f32_e32 v20, v20
	v_rcp_f32_e32 v21, v21
	v_rcp_f32_e32 v22, v22
	v_rcp_f32_e32 v23, v23
	s_nop 0
	v_pk_mul_f32 v[4:5], v[4:5], v[20:21]
	v_pk_mul_f32 v[6:7], v[6:7], v[22:23]
	v_pk_mul_f32 v[4:5], v[8:9], v[4:5]
	v_pk_mul_f32 v[6:7], v[10:11], v[6:7]
	v_cvt_pk_bf16_f32 v20, v4, v5
	v_cvt_pk_bf16_f32 v21, v6, v7
	global_store_dwordx2 v[2:3], v[20:21], off
	v_lshl_add_u64 v[2:3], v[2:3], 0, s[98:99]
	s_waitcnt lgkmcnt(0)
	v_pk_mul_f32 v[12:13], v[12:13], v[164:165] op_sel_hi:[1,0]
	v_pk_mul_f32 v[14:15], v[14:15], v[164:165] op_sel_hi:[1,0]
	v_mul_f32_e32 v20, 0xbfb8aa3b, v12
	v_mul_f32_e32 v21, 0xbfb8aa3b, v13
	v_mul_f32_e32 v22, 0xbfb8aa3b, v14
	v_mul_f32_e32 v23, 0xbfb8aa3b, v15
	v_exp_f32_e32 v20, v20
	v_exp_f32_e32 v21, v21
	v_exp_f32_e32 v22, v22
	v_exp_f32_e32 v23, v23
	v_pk_mul_f32 v[16:17], v[16:17], v[164:165] op_sel_hi:[1,0]
	v_pk_mul_f32 v[18:19], v[18:19], v[164:165] op_sel_hi:[1,0]
	v_pk_add_f32 v[20:21], v[20:21], 1.0 op_sel_hi:[1,0]
	v_pk_add_f32 v[22:23], v[22:23], 1.0 op_sel_hi:[1,0]
	v_rcp_f32_e32 v20, v20
	v_rcp_f32_e32 v21, v21
	v_rcp_f32_e32 v22, v22
	v_rcp_f32_e32 v23, v23
	s_nop 0
	v_pk_mul_f32 v[12:13], v[12:13], v[20:21]
	v_pk_mul_f32 v[14:15], v[14:15], v[22:23]
	v_pk_mul_f32 v[12:13], v[16:17], v[12:13]
	v_pk_mul_f32 v[14:15], v[18:19], v[14:15]
	v_cvt_pk_bf16_f32 v20, v12, v13
	v_cvt_pk_bf16_f32 v21, v14, v15
	global_store_dwordx2 v[2:3], v[20:21], off
	s_barrier
